# pool window sums: second dword of each pair unpacked in place (two independent chains per row)
# speedup vs baseline: 1.0022x; 1.0022x over previous
.LBB0_332:
	s_or_b64 exec, exec, s[6:7]
	s_waitcnt lgkmcnt(0)
	global_load_dwordx4 v[82:85], v[144:145], off offset:512
	global_load_dwordx4 v[86:89], v[146:147], off offset:512
	global_load_dwordx4 v[90:93], v[148:149], off offset:512
	global_load_dwordx4 v[94:97], v[150:151], off offset:512
	global_load_dwordx4 v[112:115], v[144:145], off offset:1024
	global_load_dwordx4 v[116:119], v[146:147], off offset:1024
	global_load_dwordx4 v[122:125], v[148:149], off offset:1024
	global_load_dwordx4 v[126:129], v[150:151], off offset:1024
	v_or_b32_e32 v2, s28, v1
	v_min_u32_e32 v3, 15, v2
	v_add_u32_e32 v3, 1, v3
	v_cvt_f32_ubyte0_e32 v3, v3
	v_div_scale_f32 v4, s[6:7], v3, v3, 1.0
	v_rcp_f32_e32 v5, v4
	s_ashr_i32 s8, s30, 6
	s_mul_i32 s10, s8, 15
	v_cmp_lt_u32_e64 s[6:7], s41, v2
	v_fma_f32 v6, -v4, v5, 1.0
	v_fmac_f32_e32 v5, v6, v5
	v_div_scale_f32 v6, vcc, 1.0, v3, 1.0
	v_mul_f32_e32 v7, v6, v5
	v_fma_f32 v8, -v4, v7, v6
	v_fmac_f32_e32 v7, v8, v5
	v_fma_f32 v4, -v4, v7, v6
	v_div_fmas_f32 v4, v4, v5, v7
	v_div_fixup_f32 v159, v4, v3, 1.0
	s_ashr_i32 s11, s10, 31
	v_add_u32_e32 v2, 0xfffff80f, v2
	v_mov_b32_e32 v3, v155
	v_lshl_add_u64 v[2:3], v[2:3], 0, s[10:11]
	v_lshlrev_b64 v[2:3], 11, v[2:3]
	v_lshl_add_u64 v[2:3], s[70:71], 0, v[2:3]
	v_mov_b32_e32 v163, v155
	v_lshl_add_u64 v[2:3], v[2:3], 0, v[162:163]
	v_lshl_add_u64 v[192:193], v[2:3], 0, s[16:17]
	v_mov_b32_e32 v2, 0
	s_mov_b32 s49, 0
	s_mov_b64 s[10:11], 0
	v_mov_b32_e32 v3, v2
	v_mov_b32_e32 v4, v2
	v_mov_b32_e32 v5, v2
	v_mov_b32_e32 v6, v2
	v_mov_b32_e32 v7, v2
	v_mov_b32_e32 v8, v2
	v_mov_b32_e32 v9, v2
	v_mov_b32_e32 v10, v2
	v_mov_b32_e32 v11, v2
	v_mov_b32_e32 v12, v2
	v_mov_b32_e32 v13, v2
	v_mov_b32_e32 v14, v2
	v_mov_b32_e32 v15, v2
	v_mov_b32_e32 v16, v2
	v_mov_b32_e32 v17, v2
	v_mov_b32_e32 v18, v2
	v_mov_b32_e32 v19, v2
	v_mov_b32_e32 v20, v2
	v_mov_b32_e32 v21, v2
	v_mov_b32_e32 v22, v2
	v_mov_b32_e32 v23, v2
	v_mov_b32_e32 v24, v2
	v_mov_b32_e32 v25, v2
	v_mov_b32_e32 v26, v2
	v_mov_b32_e32 v27, v2
	v_mov_b32_e32 v28, v2
	v_mov_b32_e32 v29, v2
	v_mov_b32_e32 v30, v2
	v_mov_b32_e32 v31, v2
	v_mov_b32_e32 v32, v2
	v_mov_b32_e32 v33, v2
	v_mov_b32_e32 v34, v2
	v_mov_b32_e32 v35, v2
	v_mov_b32_e32 v36, v2
	v_mov_b32_e32 v37, v2
	v_mov_b32_e32 v38, v2
	v_mov_b32_e32 v39, v2
	v_mov_b32_e32 v40, v2
	v_mov_b32_e32 v41, v2
	v_mov_b32_e32 v42, v2
	v_mov_b32_e32 v43, v2
	v_mov_b32_e32 v44, v2
	v_mov_b32_e32 v45, v2
	v_mov_b32_e32 v46, v2
	v_mov_b32_e32 v47, v2
	v_mov_b32_e32 v48, v2
	v_mov_b32_e32 v49, v2
	v_mov_b32_e32 v50, v2
	v_mov_b32_e32 v51, v2
	v_mov_b32_e32 v52, v2
	v_mov_b32_e32 v53, v2
	v_mov_b32_e32 v54, v2
	v_mov_b32_e32 v55, v2
	v_mov_b32_e32 v56, v2
	v_mov_b32_e32 v57, v2
	v_mov_b32_e32 v58, v2
	v_mov_b32_e32 v59, v2
	v_mov_b32_e32 v60, v2
	v_mov_b32_e32 v61, v2
	v_mov_b32_e32 v62, v2
	v_mov_b32_e32 v63, v2
	v_mov_b32_e32 v64, v2
	v_mov_b32_e32 v65, v2
	v_lshl_add_u32 v163, v197, 1, v214
	ds_read_b128 v[222:225], v163 offset:4080
	ds_read_b128 v[226:229], v163 offset:3808
	ds_read_b128 v[230:233], v163 offset:3536
	ds_read_b128 v[234:237], v163 offset:3264
	ds_read_b128 v[238:241], v163 offset:2992
	ds_read_b128 v[242:245], v163 offset:2720
	ds_read_b128 v[248:251], v163 offset:2448
	ds_read_b128 v[252:255], v163 offset:2176
	s_waitcnt lgkmcnt(7)
	v_lshlrev_b32_e32 v98, 16, v222
	v_and_b32_e32 v99, 0xffff0000, v222
	v_lshlrev_b32_e32 v100, 16, v223
	v_and_b32_e32 v101, 0xffff0000, v223
	v_lshlrev_b32_e32 v102, 16, v224
	v_and_b32_e32 v103, 0xffff0000, v224
	v_lshlrev_b32_e32 v104, 16, v225
	v_and_b32_e32 v105, 0xffff0000, v225
	ds_read_b128 v[222:225], v163 offset:1904
	s_waitcnt lgkmcnt(7)
	v_lshlrev_b32_e32 v216, 16, v226
	v_and_b32_e32 v217, 0xffff0000, v226
	v_lshlrev_b32_e32 v226, 16, v227
	v_and_b32_e32 v227, 0xffff0000, v227
	v_pk_add_f32 v[106:107], v[98:99], v[216:217]
	v_pk_add_f32 v[108:109], v[100:101], v[226:227]
	v_lshlrev_b32_e32 v216, 16, v228
	v_and_b32_e32 v217, 0xffff0000, v228
	v_lshlrev_b32_e32 v228, 16, v229
	v_and_b32_e32 v229, 0xffff0000, v229
	v_pk_add_f32 v[218:219], v[102:103], v[216:217]
	v_pk_add_f32 v[220:221], v[104:105], v[228:229]
	ds_read_b128 v[226:229], v163 offset:1632
	s_waitcnt lgkmcnt(7)
	v_lshlrev_b32_e32 v216, 16, v230
	v_and_b32_e32 v217, 0xffff0000, v230
	v_lshlrev_b32_e32 v230, 16, v231
	v_and_b32_e32 v231, 0xffff0000, v231
	v_pk_add_f32 v[106:107], v[106:107], v[216:217]
	v_pk_add_f32 v[108:109], v[108:109], v[230:231]
	v_lshlrev_b32_e32 v216, 16, v232
	v_and_b32_e32 v217, 0xffff0000, v232
	v_lshlrev_b32_e32 v232, 16, v233
	v_and_b32_e32 v233, 0xffff0000, v233
	v_pk_add_f32 v[218:219], v[218:219], v[216:217]
	v_pk_add_f32 v[220:221], v[220:221], v[232:233]
	ds_read_b128 v[230:233], v163 offset:1360
	s_waitcnt lgkmcnt(7)
	v_lshlrev_b32_e32 v216, 16, v234
	v_and_b32_e32 v217, 0xffff0000, v234
	v_lshlrev_b32_e32 v234, 16, v235
	v_and_b32_e32 v235, 0xffff0000, v235
	v_pk_add_f32 v[106:107], v[106:107], v[216:217]
	v_pk_add_f32 v[108:109], v[108:109], v[234:235]
	v_lshlrev_b32_e32 v216, 16, v236
	v_and_b32_e32 v217, 0xffff0000, v236
	v_lshlrev_b32_e32 v236, 16, v237
	v_and_b32_e32 v237, 0xffff0000, v237
	v_pk_add_f32 v[218:219], v[218:219], v[216:217]
	v_pk_add_f32 v[220:221], v[220:221], v[236:237]
	ds_read_b128 v[234:237], v163 offset:1088
	s_waitcnt lgkmcnt(7)
	v_lshlrev_b32_e32 v216, 16, v238
	v_and_b32_e32 v217, 0xffff0000, v238
	v_lshlrev_b32_e32 v238, 16, v239
	v_and_b32_e32 v239, 0xffff0000, v239
	v_pk_add_f32 v[106:107], v[106:107], v[216:217]
	v_pk_add_f32 v[108:109], v[108:109], v[238:239]
	v_lshlrev_b32_e32 v216, 16, v240
	v_and_b32_e32 v217, 0xffff0000, v240
	v_lshlrev_b32_e32 v240, 16, v241
	v_and_b32_e32 v241, 0xffff0000, v241
	v_pk_add_f32 v[218:219], v[218:219], v[216:217]
	v_pk_add_f32 v[220:221], v[220:221], v[240:241]
	ds_read_b128 v[238:241], v163 offset:816
	s_waitcnt lgkmcnt(7)
	v_lshlrev_b32_e32 v216, 16, v242
	v_and_b32_e32 v217, 0xffff0000, v242
	v_lshlrev_b32_e32 v242, 16, v243
	v_and_b32_e32 v243, 0xffff0000, v243
	v_pk_add_f32 v[106:107], v[106:107], v[216:217]
	v_pk_add_f32 v[108:109], v[108:109], v[242:243]
	v_lshlrev_b32_e32 v216, 16, v244
	v_and_b32_e32 v217, 0xffff0000, v244
	v_lshlrev_b32_e32 v244, 16, v245
	v_and_b32_e32 v245, 0xffff0000, v245
	v_pk_add_f32 v[218:219], v[218:219], v[216:217]
	v_pk_add_f32 v[220:221], v[220:221], v[244:245]
	ds_read_b128 v[242:245], v163 offset:544
	s_waitcnt lgkmcnt(7)
	v_lshlrev_b32_e32 v216, 16, v248
	v_and_b32_e32 v217, 0xffff0000, v248
	v_lshlrev_b32_e32 v248, 16, v249
	v_and_b32_e32 v249, 0xffff0000, v249
	v_pk_add_f32 v[106:107], v[106:107], v[216:217]
	v_pk_add_f32 v[108:109], v[108:109], v[248:249]
	v_lshlrev_b32_e32 v216, 16, v250
	v_and_b32_e32 v217, 0xffff0000, v250
	v_lshlrev_b32_e32 v250, 16, v251
	v_and_b32_e32 v251, 0xffff0000, v251
	v_pk_add_f32 v[218:219], v[218:219], v[216:217]
	v_pk_add_f32 v[220:221], v[220:221], v[250:251]
	ds_read_b128 v[248:251], v163 offset:272
	s_waitcnt lgkmcnt(7)
	v_lshlrev_b32_e32 v216, 16, v252
	v_and_b32_e32 v217, 0xffff0000, v252
	v_lshlrev_b32_e32 v252, 16, v253
	v_and_b32_e32 v253, 0xffff0000, v253
	v_pk_add_f32 v[106:107], v[106:107], v[216:217]
	v_pk_add_f32 v[108:109], v[108:109], v[252:253]
	v_lshlrev_b32_e32 v216, 16, v254
	v_and_b32_e32 v217, 0xffff0000, v254
	v_lshlrev_b32_e32 v254, 16, v255
	v_and_b32_e32 v255, 0xffff0000, v255
	v_pk_add_f32 v[218:219], v[218:219], v[216:217]
	v_pk_add_f32 v[220:221], v[220:221], v[254:255]
	ds_read_b128 v[252:255], v163 offset:0
	s_waitcnt lgkmcnt(7)
	v_lshlrev_b32_e32 v216, 16, v222
	v_and_b32_e32 v217, 0xffff0000, v222
	v_lshlrev_b32_e32 v222, 16, v223
	v_and_b32_e32 v223, 0xffff0000, v223
	v_pk_add_f32 v[106:107], v[106:107], v[216:217]
	v_pk_add_f32 v[108:109], v[108:109], v[222:223]
	v_lshlrev_b32_e32 v216, 16, v224
	v_and_b32_e32 v217, 0xffff0000, v224
	v_lshlrev_b32_e32 v224, 16, v225
	v_and_b32_e32 v225, 0xffff0000, v225
	v_pk_add_f32 v[218:219], v[218:219], v[216:217]
	v_pk_add_f32 v[220:221], v[220:221], v[224:225]
	ds_read_b128 v[222:225], v163 offset:4112
	s_waitcnt lgkmcnt(7)
	v_lshlrev_b32_e32 v216, 16, v226
	v_and_b32_e32 v217, 0xffff0000, v226
	v_lshlrev_b32_e32 v226, 16, v227
	v_and_b32_e32 v227, 0xffff0000, v227
	v_pk_add_f32 v[106:107], v[106:107], v[216:217]
	v_pk_add_f32 v[108:109], v[108:109], v[226:227]
	v_lshlrev_b32_e32 v216, 16, v228
	v_and_b32_e32 v217, 0xffff0000, v228
	v_lshlrev_b32_e32 v228, 16, v229
	v_and_b32_e32 v229, 0xffff0000, v229
	v_pk_add_f32 v[218:219], v[218:219], v[216:217]
	v_pk_add_f32 v[220:221], v[220:221], v[228:229]
	ds_read_b128 v[226:229], v163 offset:3840
	s_waitcnt lgkmcnt(7)
	v_lshlrev_b32_e32 v216, 16, v230
	v_and_b32_e32 v217, 0xffff0000, v230
	v_lshlrev_b32_e32 v230, 16, v231
	v_and_b32_e32 v231, 0xffff0000, v231
	v_pk_add_f32 v[106:107], v[106:107], v[216:217]
	v_pk_add_f32 v[108:109], v[108:109], v[230:231]
	v_lshlrev_b32_e32 v216, 16, v232
	v_and_b32_e32 v217, 0xffff0000, v232
	v_lshlrev_b32_e32 v232, 16, v233
	v_and_b32_e32 v233, 0xffff0000, v233
	v_pk_add_f32 v[218:219], v[218:219], v[216:217]
	v_pk_add_f32 v[220:221], v[220:221], v[232:233]
	ds_read_b128 v[230:233], v163 offset:3568
	s_waitcnt lgkmcnt(7)
	v_lshlrev_b32_e32 v216, 16, v234
	v_and_b32_e32 v217, 0xffff0000, v234
	v_lshlrev_b32_e32 v234, 16, v235
	v_and_b32_e32 v235, 0xffff0000, v235
	v_pk_add_f32 v[106:107], v[106:107], v[216:217]
	v_pk_add_f32 v[108:109], v[108:109], v[234:235]
	v_lshlrev_b32_e32 v216, 16, v236
	v_and_b32_e32 v217, 0xffff0000, v236
	v_lshlrev_b32_e32 v236, 16, v237
	v_and_b32_e32 v237, 0xffff0000, v237
	v_pk_add_f32 v[218:219], v[218:219], v[216:217]
	v_pk_add_f32 v[220:221], v[220:221], v[236:237]
	ds_read_b128 v[234:237], v163 offset:3296
	s_waitcnt lgkmcnt(7)
	v_lshlrev_b32_e32 v216, 16, v238
	v_and_b32_e32 v217, 0xffff0000, v238
	v_lshlrev_b32_e32 v238, 16, v239
	v_and_b32_e32 v239, 0xffff0000, v239
	v_pk_add_f32 v[106:107], v[106:107], v[216:217]
	v_pk_add_f32 v[108:109], v[108:109], v[238:239]
	v_lshlrev_b32_e32 v216, 16, v240
	v_and_b32_e32 v217, 0xffff0000, v240
	v_lshlrev_b32_e32 v240, 16, v241
	v_and_b32_e32 v241, 0xffff0000, v241
	v_pk_add_f32 v[218:219], v[218:219], v[216:217]
	v_pk_add_f32 v[220:221], v[220:221], v[240:241]
	ds_read_b128 v[238:241], v163 offset:3024
	s_waitcnt lgkmcnt(7)
	v_lshlrev_b32_e32 v216, 16, v242
	v_and_b32_e32 v217, 0xffff0000, v242
	v_lshlrev_b32_e32 v242, 16, v243
	v_and_b32_e32 v243, 0xffff0000, v243
	v_pk_add_f32 v[106:107], v[106:107], v[216:217]
	v_pk_add_f32 v[108:109], v[108:109], v[242:243]
	v_lshlrev_b32_e32 v216, 16, v244
	v_and_b32_e32 v217, 0xffff0000, v244
	v_lshlrev_b32_e32 v244, 16, v245
	v_and_b32_e32 v245, 0xffff0000, v245
	v_pk_add_f32 v[218:219], v[218:219], v[216:217]
	v_pk_add_f32 v[220:221], v[220:221], v[244:245]
	ds_read_b128 v[242:245], v163 offset:2752
	s_waitcnt lgkmcnt(7)
	v_lshlrev_b32_e32 v216, 16, v248
	v_and_b32_e32 v217, 0xffff0000, v248
	v_lshlrev_b32_e32 v248, 16, v249
	v_and_b32_e32 v249, 0xffff0000, v249
	v_pk_add_f32 v[106:107], v[106:107], v[216:217]
	v_pk_add_f32 v[108:109], v[108:109], v[248:249]
	v_lshlrev_b32_e32 v216, 16, v250
	v_and_b32_e32 v217, 0xffff0000, v250
	v_lshlrev_b32_e32 v250, 16, v251
	v_and_b32_e32 v251, 0xffff0000, v251
	v_pk_add_f32 v[218:219], v[218:219], v[216:217]
	v_pk_add_f32 v[220:221], v[220:221], v[250:251]
	ds_read_b128 v[248:251], v163 offset:2480
	s_waitcnt lgkmcnt(7)
	v_lshlrev_b32_e32 v216, 16, v252
	v_and_b32_e32 v217, 0xffff0000, v252
	v_lshlrev_b32_e32 v252, 16, v253
	v_and_b32_e32 v253, 0xffff0000, v253
	v_pk_add_f32 v[106:107], v[106:107], v[216:217]
	v_pk_add_f32 v[108:109], v[108:109], v[252:253]
	v_lshlrev_b32_e32 v216, 16, v254
	v_and_b32_e32 v217, 0xffff0000, v254
	v_lshlrev_b32_e32 v254, 16, v255
	v_and_b32_e32 v255, 0xffff0000, v255
	v_pk_add_f32 v[218:219], v[218:219], v[216:217]
	v_pk_add_f32 v[220:221], v[220:221], v[254:255]
	ds_read_b128 v[252:255], v163 offset:2208
	v_fma_f32 v106, v159, v106, -v98
	v_fma_f32 v107, v159, v107, -v99
	v_fma_f32 v108, v159, v108, -v100
	v_fma_f32 v109, v159, v109, -v101
	v_fma_f32 v218, v159, v218, -v102
	v_fma_f32 v219, v159, v219, -v103
	v_fma_f32 v220, v159, v220, -v104
	v_fma_f32 v221, v159, v221, -v105
	v_cvt_pk_bf16_f32 v106, v106, v107
	v_cvt_pk_bf16_f32 v107, v108, v109
	v_cvt_pk_bf16_f32 v108, v218, v219
	v_cvt_pk_bf16_f32 v109, v220, v221
	s_and_saveexec_b64 s[28:29], s[6:7]
	s_cbranch_execz .Lpu0_0
	global_store_dwordx4 v[192:193], v[98:101], off offset:0
	global_store_dwordx4 v[192:193], v[102:105], off offset:16
.Lpu0_0:
	s_or_b64 exec, exec, s[28:29]
	s_waitcnt vmcnt(8)
	v_mfma_f32_32x32x16_bf16 v[2:17], v[106:109], v[70:73], v[2:17]
	v_mfma_f32_32x32x16_bf16 v[18:33], v[106:109], v[74:77], v[18:33]
	v_mfma_f32_32x32x16_bf16 v[34:49], v[106:109], v[78:81], v[34:49]
	v_mfma_f32_32x32x16_bf16 v[50:65], v[106:109], v[66:69], v[50:65]
	global_load_dwordx4 v[70:73], v[144:145], off offset:1536
	global_load_dwordx4 v[74:77], v[146:147], off offset:1536
	global_load_dwordx4 v[78:81], v[148:149], off offset:1536
	global_load_dwordx4 v[66:69], v[150:151], off offset:1536
	s_waitcnt lgkmcnt(7)
	v_lshlrev_b32_e32 v98, 16, v222
	v_and_b32_e32 v99, 0xffff0000, v222
	v_lshlrev_b32_e32 v100, 16, v223
	v_and_b32_e32 v101, 0xffff0000, v223
	v_lshlrev_b32_e32 v102, 16, v224
	v_and_b32_e32 v103, 0xffff0000, v224
	v_lshlrev_b32_e32 v104, 16, v225
	v_and_b32_e32 v105, 0xffff0000, v225
	ds_read_b128 v[222:225], v163 offset:1936
	s_waitcnt lgkmcnt(7)
	v_lshlrev_b32_e32 v216, 16, v226
	v_and_b32_e32 v217, 0xffff0000, v226
	v_lshlrev_b32_e32 v226, 16, v227
	v_and_b32_e32 v227, 0xffff0000, v227
	v_pk_add_f32 v[106:107], v[98:99], v[216:217]
	v_pk_add_f32 v[108:109], v[100:101], v[226:227]
	v_lshlrev_b32_e32 v216, 16, v228
	v_and_b32_e32 v217, 0xffff0000, v228
	v_lshlrev_b32_e32 v228, 16, v229
	v_and_b32_e32 v229, 0xffff0000, v229
	v_pk_add_f32 v[218:219], v[102:103], v[216:217]
	v_pk_add_f32 v[220:221], v[104:105], v[228:229]
	ds_read_b128 v[226:229], v163 offset:1664
	s_waitcnt lgkmcnt(7)
	v_lshlrev_b32_e32 v216, 16, v230
	v_and_b32_e32 v217, 0xffff0000, v230
	v_lshlrev_b32_e32 v230, 16, v231
	v_and_b32_e32 v231, 0xffff0000, v231
	v_pk_add_f32 v[106:107], v[106:107], v[216:217]
	v_pk_add_f32 v[108:109], v[108:109], v[230:231]
	v_lshlrev_b32_e32 v216, 16, v232
	v_and_b32_e32 v217, 0xffff0000, v232
	v_lshlrev_b32_e32 v232, 16, v233
	v_and_b32_e32 v233, 0xffff0000, v233
	v_pk_add_f32 v[218:219], v[218:219], v[216:217]
	v_pk_add_f32 v[220:221], v[220:221], v[232:233]
	ds_read_b128 v[230:233], v163 offset:1392
	s_waitcnt lgkmcnt(7)
	v_lshlrev_b32_e32 v216, 16, v234
	v_and_b32_e32 v217, 0xffff0000, v234
	v_lshlrev_b32_e32 v234, 16, v235
	v_and_b32_e32 v235, 0xffff0000, v235
	v_pk_add_f32 v[106:107], v[106:107], v[216:217]
	v_pk_add_f32 v[108:109], v[108:109], v[234:235]
	v_lshlrev_b32_e32 v216, 16, v236
	v_and_b32_e32 v217, 0xffff0000, v236
	v_lshlrev_b32_e32 v236, 16, v237
	v_and_b32_e32 v237, 0xffff0000, v237
	v_pk_add_f32 v[218:219], v[218:219], v[216:217]
	v_pk_add_f32 v[220:221], v[220:221], v[236:237]
	ds_read_b128 v[234:237], v163 offset:1120
	s_waitcnt lgkmcnt(7)
	v_lshlrev_b32_e32 v216, 16, v238
	v_and_b32_e32 v217, 0xffff0000, v238
	v_lshlrev_b32_e32 v238, 16, v239
	v_and_b32_e32 v239, 0xffff0000, v239
	v_pk_add_f32 v[106:107], v[106:107], v[216:217]
	v_pk_add_f32 v[108:109], v[108:109], v[238:239]
	v_lshlrev_b32_e32 v216, 16, v240
	v_and_b32_e32 v217, 0xffff0000, v240
	v_lshlrev_b32_e32 v240, 16, v241
	v_and_b32_e32 v241, 0xffff0000, v241
	v_pk_add_f32 v[218:219], v[218:219], v[216:217]
	v_pk_add_f32 v[220:221], v[220:221], v[240:241]
	ds_read_b128 v[238:241], v163 offset:848
	s_waitcnt lgkmcnt(7)
	v_lshlrev_b32_e32 v216, 16, v242
	v_and_b32_e32 v217, 0xffff0000, v242
	v_lshlrev_b32_e32 v242, 16, v243
	v_and_b32_e32 v243, 0xffff0000, v243
	v_pk_add_f32 v[106:107], v[106:107], v[216:217]
	v_pk_add_f32 v[108:109], v[108:109], v[242:243]
	v_lshlrev_b32_e32 v216, 16, v244
	v_and_b32_e32 v217, 0xffff0000, v244
	v_lshlrev_b32_e32 v244, 16, v245
	v_and_b32_e32 v245, 0xffff0000, v245
	v_pk_add_f32 v[218:219], v[218:219], v[216:217]
	v_pk_add_f32 v[220:221], v[220:221], v[244:245]
	ds_read_b128 v[242:245], v163 offset:576
	s_waitcnt lgkmcnt(7)
	v_lshlrev_b32_e32 v216, 16, v248
	v_and_b32_e32 v217, 0xffff0000, v248
	v_lshlrev_b32_e32 v248, 16, v249
	v_and_b32_e32 v249, 0xffff0000, v249
	v_pk_add_f32 v[106:107], v[106:107], v[216:217]
	v_pk_add_f32 v[108:109], v[108:109], v[248:249]
	v_lshlrev_b32_e32 v216, 16, v250
	v_and_b32_e32 v217, 0xffff0000, v250
	v_lshlrev_b32_e32 v250, 16, v251
	v_and_b32_e32 v251, 0xffff0000, v251
	v_pk_add_f32 v[218:219], v[218:219], v[216:217]
	v_pk_add_f32 v[220:221], v[220:221], v[250:251]
	ds_read_b128 v[248:251], v163 offset:304
	s_waitcnt lgkmcnt(7)
	v_lshlrev_b32_e32 v216, 16, v252
	v_and_b32_e32 v217, 0xffff0000, v252
	v_lshlrev_b32_e32 v252, 16, v253
	v_and_b32_e32 v253, 0xffff0000, v253
	v_pk_add_f32 v[106:107], v[106:107], v[216:217]
	v_pk_add_f32 v[108:109], v[108:109], v[252:253]
	v_lshlrev_b32_e32 v216, 16, v254
	v_and_b32_e32 v217, 0xffff0000, v254
	v_lshlrev_b32_e32 v254, 16, v255
	v_and_b32_e32 v255, 0xffff0000, v255
	v_pk_add_f32 v[218:219], v[218:219], v[216:217]
	v_pk_add_f32 v[220:221], v[220:221], v[254:255]
	ds_read_b128 v[252:255], v163 offset:32
	s_waitcnt lgkmcnt(7)
	v_lshlrev_b32_e32 v216, 16, v222
	v_and_b32_e32 v217, 0xffff0000, v222
	v_lshlrev_b32_e32 v222, 16, v223
	v_and_b32_e32 v223, 0xffff0000, v223
	v_pk_add_f32 v[106:107], v[106:107], v[216:217]
	v_pk_add_f32 v[108:109], v[108:109], v[222:223]
	v_lshlrev_b32_e32 v216, 16, v224
	v_and_b32_e32 v217, 0xffff0000, v224
	v_lshlrev_b32_e32 v224, 16, v225
	v_and_b32_e32 v225, 0xffff0000, v225
	v_pk_add_f32 v[218:219], v[218:219], v[216:217]
	v_pk_add_f32 v[220:221], v[220:221], v[224:225]
	ds_read_b128 v[222:225], v163 offset:4144
	s_waitcnt lgkmcnt(7)
	v_lshlrev_b32_e32 v216, 16, v226
	v_and_b32_e32 v217, 0xffff0000, v226
	v_lshlrev_b32_e32 v226, 16, v227
	v_and_b32_e32 v227, 0xffff0000, v227
	v_pk_add_f32 v[106:107], v[106:107], v[216:217]
	v_pk_add_f32 v[108:109], v[108:109], v[226:227]
	v_lshlrev_b32_e32 v216, 16, v228
	v_and_b32_e32 v217, 0xffff0000, v228
	v_lshlrev_b32_e32 v228, 16, v229
	v_and_b32_e32 v229, 0xffff0000, v229
	v_pk_add_f32 v[218:219], v[218:219], v[216:217]
	v_pk_add_f32 v[220:221], v[220:221], v[228:229]
	ds_read_b128 v[226:229], v163 offset:3872
	s_waitcnt lgkmcnt(7)
	v_lshlrev_b32_e32 v216, 16, v230
	v_and_b32_e32 v217, 0xffff0000, v230
	v_lshlrev_b32_e32 v230, 16, v231
	v_and_b32_e32 v231, 0xffff0000, v231
	v_pk_add_f32 v[106:107], v[106:107], v[216:217]
	v_pk_add_f32 v[108:109], v[108:109], v[230:231]
	v_lshlrev_b32_e32 v216, 16, v232
	v_and_b32_e32 v217, 0xffff0000, v232
	v_lshlrev_b32_e32 v232, 16, v233
	v_and_b32_e32 v233, 0xffff0000, v233
	v_pk_add_f32 v[218:219], v[218:219], v[216:217]
	v_pk_add_f32 v[220:221], v[220:221], v[232:233]
	ds_read_b128 v[230:233], v163 offset:3600
	s_waitcnt lgkmcnt(7)
	v_lshlrev_b32_e32 v216, 16, v234
	v_and_b32_e32 v217, 0xffff0000, v234
	v_lshlrev_b32_e32 v234, 16, v235
	v_and_b32_e32 v235, 0xffff0000, v235
	v_pk_add_f32 v[106:107], v[106:107], v[216:217]
	v_pk_add_f32 v[108:109], v[108:109], v[234:235]
	v_lshlrev_b32_e32 v216, 16, v236
	v_and_b32_e32 v217, 0xffff0000, v236
	v_lshlrev_b32_e32 v236, 16, v237
	v_and_b32_e32 v237, 0xffff0000, v237
	v_pk_add_f32 v[218:219], v[218:219], v[216:217]
	v_pk_add_f32 v[220:221], v[220:221], v[236:237]
	ds_read_b128 v[234:237], v163 offset:3328
	s_waitcnt lgkmcnt(7)
	v_lshlrev_b32_e32 v216, 16, v238
	v_and_b32_e32 v217, 0xffff0000, v238
	v_lshlrev_b32_e32 v238, 16, v239
	v_and_b32_e32 v239, 0xffff0000, v239
	v_pk_add_f32 v[106:107], v[106:107], v[216:217]
	v_pk_add_f32 v[108:109], v[108:109], v[238:239]
	v_lshlrev_b32_e32 v216, 16, v240
	v_and_b32_e32 v217, 0xffff0000, v240
	v_lshlrev_b32_e32 v240, 16, v241
	v_and_b32_e32 v241, 0xffff0000, v241
	v_pk_add_f32 v[218:219], v[218:219], v[216:217]
	v_pk_add_f32 v[220:221], v[220:221], v[240:241]
	ds_read_b128 v[238:241], v163 offset:3056
	s_waitcnt lgkmcnt(7)
	v_lshlrev_b32_e32 v216, 16, v242
	v_and_b32_e32 v217, 0xffff0000, v242
	v_lshlrev_b32_e32 v242, 16, v243
	v_and_b32_e32 v243, 0xffff0000, v243
	v_pk_add_f32 v[106:107], v[106:107], v[216:217]
	v_pk_add_f32 v[108:109], v[108:109], v[242:243]
	v_lshlrev_b32_e32 v216, 16, v244
	v_and_b32_e32 v217, 0xffff0000, v244
	v_lshlrev_b32_e32 v244, 16, v245
	v_and_b32_e32 v245, 0xffff0000, v245
	v_pk_add_f32 v[218:219], v[218:219], v[216:217]
	v_pk_add_f32 v[220:221], v[220:221], v[244:245]
	ds_read_b128 v[242:245], v163 offset:2784
	s_waitcnt lgkmcnt(7)
	v_lshlrev_b32_e32 v216, 16, v248
	v_and_b32_e32 v217, 0xffff0000, v248
	v_lshlrev_b32_e32 v248, 16, v249
	v_and_b32_e32 v249, 0xffff0000, v249
	v_pk_add_f32 v[106:107], v[106:107], v[216:217]
	v_pk_add_f32 v[108:109], v[108:109], v[248:249]
	v_lshlrev_b32_e32 v216, 16, v250
	v_and_b32_e32 v217, 0xffff0000, v250
	v_lshlrev_b32_e32 v250, 16, v251
	v_and_b32_e32 v251, 0xffff0000, v251
	v_pk_add_f32 v[218:219], v[218:219], v[216:217]
	v_pk_add_f32 v[220:221], v[220:221], v[250:251]
	ds_read_b128 v[248:251], v163 offset:2512
	s_waitcnt lgkmcnt(7)
	v_lshlrev_b32_e32 v216, 16, v252
	v_and_b32_e32 v217, 0xffff0000, v252
	v_lshlrev_b32_e32 v252, 16, v253
	v_and_b32_e32 v253, 0xffff0000, v253
	v_pk_add_f32 v[106:107], v[106:107], v[216:217]
	v_pk_add_f32 v[108:109], v[108:109], v[252:253]
	v_lshlrev_b32_e32 v216, 16, v254
	v_and_b32_e32 v217, 0xffff0000, v254
	v_lshlrev_b32_e32 v254, 16, v255
	v_and_b32_e32 v255, 0xffff0000, v255
	v_pk_add_f32 v[218:219], v[218:219], v[216:217]
	v_pk_add_f32 v[220:221], v[220:221], v[254:255]
	ds_read_b128 v[252:255], v163 offset:2240
	v_fma_f32 v106, v159, v106, -v98
	v_fma_f32 v107, v159, v107, -v99
	v_fma_f32 v108, v159, v108, -v100
	v_fma_f32 v109, v159, v109, -v101
	v_fma_f32 v218, v159, v218, -v102
	v_fma_f32 v219, v159, v219, -v103
	v_fma_f32 v220, v159, v220, -v104
	v_fma_f32 v221, v159, v221, -v105
	v_cvt_pk_bf16_f32 v106, v106, v107
	v_cvt_pk_bf16_f32 v107, v108, v109
	v_cvt_pk_bf16_f32 v108, v218, v219
	v_cvt_pk_bf16_f32 v109, v220, v221
	s_and_saveexec_b64 s[28:29], s[6:7]
	s_cbranch_execz .Lpu0_1
	global_store_dwordx4 v[192:193], v[98:101], off offset:64
	global_store_dwordx4 v[192:193], v[102:105], off offset:80
.Lpu0_1:
	s_or_b64 exec, exec, s[28:29]
	s_waitcnt vmcnt(8)
	v_mfma_f32_32x32x16_bf16 v[2:17], v[106:109], v[82:85], v[2:17]
	v_mfma_f32_32x32x16_bf16 v[18:33], v[106:109], v[86:89], v[18:33]
	v_mfma_f32_32x32x16_bf16 v[34:49], v[106:109], v[90:93], v[34:49]
	v_mfma_f32_32x32x16_bf16 v[50:65], v[106:109], v[94:97], v[50:65]
	global_load_dwordx4 v[82:85], v[144:145], off offset:2048
	global_load_dwordx4 v[86:89], v[146:147], off offset:2048
	global_load_dwordx4 v[90:93], v[148:149], off offset:2048
	global_load_dwordx4 v[94:97], v[150:151], off offset:2048
	s_waitcnt lgkmcnt(7)
	v_lshlrev_b32_e32 v98, 16, v222
	v_and_b32_e32 v99, 0xffff0000, v222
	v_lshlrev_b32_e32 v100, 16, v223
	v_and_b32_e32 v101, 0xffff0000, v223
	v_lshlrev_b32_e32 v102, 16, v224
	v_and_b32_e32 v103, 0xffff0000, v224
	v_lshlrev_b32_e32 v104, 16, v225
	v_and_b32_e32 v105, 0xffff0000, v225
	ds_read_b128 v[222:225], v163 offset:1968
	s_waitcnt lgkmcnt(7)
	v_lshlrev_b32_e32 v216, 16, v226
	v_and_b32_e32 v217, 0xffff0000, v226
	v_lshlrev_b32_e32 v226, 16, v227
	v_and_b32_e32 v227, 0xffff0000, v227
	v_pk_add_f32 v[106:107], v[98:99], v[216:217]
	v_pk_add_f32 v[108:109], v[100:101], v[226:227]
	v_lshlrev_b32_e32 v216, 16, v228
	v_and_b32_e32 v217, 0xffff0000, v228
	v_lshlrev_b32_e32 v228, 16, v229
	v_and_b32_e32 v229, 0xffff0000, v229
	v_pk_add_f32 v[218:219], v[102:103], v[216:217]
	v_pk_add_f32 v[220:221], v[104:105], v[228:229]
	ds_read_b128 v[226:229], v163 offset:1696
	s_waitcnt lgkmcnt(7)
	v_lshlrev_b32_e32 v216, 16, v230
	v_and_b32_e32 v217, 0xffff0000, v230
	v_lshlrev_b32_e32 v230, 16, v231
	v_and_b32_e32 v231, 0xffff0000, v231
	v_pk_add_f32 v[106:107], v[106:107], v[216:217]
	v_pk_add_f32 v[108:109], v[108:109], v[230:231]
	v_lshlrev_b32_e32 v216, 16, v232
	v_and_b32_e32 v217, 0xffff0000, v232
	v_lshlrev_b32_e32 v232, 16, v233
	v_and_b32_e32 v233, 0xffff0000, v233
	v_pk_add_f32 v[218:219], v[218:219], v[216:217]
	v_pk_add_f32 v[220:221], v[220:221], v[232:233]
	ds_read_b128 v[230:233], v163 offset:1424
	s_waitcnt lgkmcnt(7)
	v_lshlrev_b32_e32 v216, 16, v234
	v_and_b32_e32 v217, 0xffff0000, v234
	v_lshlrev_b32_e32 v234, 16, v235
	v_and_b32_e32 v235, 0xffff0000, v235
	v_pk_add_f32 v[106:107], v[106:107], v[216:217]
	v_pk_add_f32 v[108:109], v[108:109], v[234:235]
	v_lshlrev_b32_e32 v216, 16, v236
	v_and_b32_e32 v217, 0xffff0000, v236
	v_lshlrev_b32_e32 v236, 16, v237
	v_and_b32_e32 v237, 0xffff0000, v237
	v_pk_add_f32 v[218:219], v[218:219], v[216:217]
	v_pk_add_f32 v[220:221], v[220:221], v[236:237]
	ds_read_b128 v[234:237], v163 offset:1152
	s_waitcnt lgkmcnt(7)
	v_lshlrev_b32_e32 v216, 16, v238
	v_and_b32_e32 v217, 0xffff0000, v238
	v_lshlrev_b32_e32 v238, 16, v239
	v_and_b32_e32 v239, 0xffff0000, v239
	v_pk_add_f32 v[106:107], v[106:107], v[216:217]
	v_pk_add_f32 v[108:109], v[108:109], v[238:239]
	v_lshlrev_b32_e32 v216, 16, v240
	v_and_b32_e32 v217, 0xffff0000, v240
	v_lshlrev_b32_e32 v240, 16, v241
	v_and_b32_e32 v241, 0xffff0000, v241
	v_pk_add_f32 v[218:219], v[218:219], v[216:217]
	v_pk_add_f32 v[220:221], v[220:221], v[240:241]
	ds_read_b128 v[238:241], v163 offset:880
	s_waitcnt lgkmcnt(7)
	v_lshlrev_b32_e32 v216, 16, v242
	v_and_b32_e32 v217, 0xffff0000, v242
	v_lshlrev_b32_e32 v242, 16, v243
	v_and_b32_e32 v243, 0xffff0000, v243
	v_pk_add_f32 v[106:107], v[106:107], v[216:217]
	v_pk_add_f32 v[108:109], v[108:109], v[242:243]
	v_lshlrev_b32_e32 v216, 16, v244
	v_and_b32_e32 v217, 0xffff0000, v244
	v_lshlrev_b32_e32 v244, 16, v245
	v_and_b32_e32 v245, 0xffff0000, v245
	v_pk_add_f32 v[218:219], v[218:219], v[216:217]
	v_pk_add_f32 v[220:221], v[220:221], v[244:245]
	ds_read_b128 v[242:245], v163 offset:608
	s_waitcnt lgkmcnt(7)
	v_lshlrev_b32_e32 v216, 16, v248
	v_and_b32_e32 v217, 0xffff0000, v248
	v_lshlrev_b32_e32 v248, 16, v249
	v_and_b32_e32 v249, 0xffff0000, v249
	v_pk_add_f32 v[106:107], v[106:107], v[216:217]
	v_pk_add_f32 v[108:109], v[108:109], v[248:249]
	v_lshlrev_b32_e32 v216, 16, v250
	v_and_b32_e32 v217, 0xffff0000, v250
	v_lshlrev_b32_e32 v250, 16, v251
	v_and_b32_e32 v251, 0xffff0000, v251
	v_pk_add_f32 v[218:219], v[218:219], v[216:217]
	v_pk_add_f32 v[220:221], v[220:221], v[250:251]
	ds_read_b128 v[248:251], v163 offset:336
	s_waitcnt lgkmcnt(7)
	v_lshlrev_b32_e32 v216, 16, v252
	v_and_b32_e32 v217, 0xffff0000, v252
	v_lshlrev_b32_e32 v252, 16, v253
	v_and_b32_e32 v253, 0xffff0000, v253
	v_pk_add_f32 v[106:107], v[106:107], v[216:217]
	v_pk_add_f32 v[108:109], v[108:109], v[252:253]
	v_lshlrev_b32_e32 v216, 16, v254
	v_and_b32_e32 v217, 0xffff0000, v254
	v_lshlrev_b32_e32 v254, 16, v255
	v_and_b32_e32 v255, 0xffff0000, v255
	v_pk_add_f32 v[218:219], v[218:219], v[216:217]
	v_pk_add_f32 v[220:221], v[220:221], v[254:255]
	ds_read_b128 v[252:255], v163 offset:64
	s_waitcnt lgkmcnt(7)
	v_lshlrev_b32_e32 v216, 16, v222
	v_and_b32_e32 v217, 0xffff0000, v222
	v_lshlrev_b32_e32 v222, 16, v223
	v_and_b32_e32 v223, 0xffff0000, v223
	v_pk_add_f32 v[106:107], v[106:107], v[216:217]
	v_pk_add_f32 v[108:109], v[108:109], v[222:223]
	v_lshlrev_b32_e32 v216, 16, v224
	v_and_b32_e32 v217, 0xffff0000, v224
	v_lshlrev_b32_e32 v224, 16, v225
	v_and_b32_e32 v225, 0xffff0000, v225
	v_pk_add_f32 v[218:219], v[218:219], v[216:217]
	v_pk_add_f32 v[220:221], v[220:221], v[224:225]
	ds_read_b128 v[222:225], v163 offset:4176
	s_waitcnt lgkmcnt(7)
	v_lshlrev_b32_e32 v216, 16, v226
	v_and_b32_e32 v217, 0xffff0000, v226
	v_lshlrev_b32_e32 v226, 16, v227
	v_and_b32_e32 v227, 0xffff0000, v227
	v_pk_add_f32 v[106:107], v[106:107], v[216:217]
	v_pk_add_f32 v[108:109], v[108:109], v[226:227]
	v_lshlrev_b32_e32 v216, 16, v228
	v_and_b32_e32 v217, 0xffff0000, v228
	v_lshlrev_b32_e32 v228, 16, v229
	v_and_b32_e32 v229, 0xffff0000, v229
	v_pk_add_f32 v[218:219], v[218:219], v[216:217]
	v_pk_add_f32 v[220:221], v[220:221], v[228:229]
	ds_read_b128 v[226:229], v163 offset:3904
	s_waitcnt lgkmcnt(7)
	v_lshlrev_b32_e32 v216, 16, v230
	v_and_b32_e32 v217, 0xffff0000, v230
	v_lshlrev_b32_e32 v230, 16, v231
	v_and_b32_e32 v231, 0xffff0000, v231
	v_pk_add_f32 v[106:107], v[106:107], v[216:217]
	v_pk_add_f32 v[108:109], v[108:109], v[230:231]
	v_lshlrev_b32_e32 v216, 16, v232
	v_and_b32_e32 v217, 0xffff0000, v232
	v_lshlrev_b32_e32 v232, 16, v233
	v_and_b32_e32 v233, 0xffff0000, v233
	v_pk_add_f32 v[218:219], v[218:219], v[216:217]
	v_pk_add_f32 v[220:221], v[220:221], v[232:233]
	ds_read_b128 v[230:233], v163 offset:3632
	s_waitcnt lgkmcnt(7)
	v_lshlrev_b32_e32 v216, 16, v234
	v_and_b32_e32 v217, 0xffff0000, v234
	v_lshlrev_b32_e32 v234, 16, v235
	v_and_b32_e32 v235, 0xffff0000, v235
	v_pk_add_f32 v[106:107], v[106:107], v[216:217]
	v_pk_add_f32 v[108:109], v[108:109], v[234:235]
	v_lshlrev_b32_e32 v216, 16, v236
	v_and_b32_e32 v217, 0xffff0000, v236
	v_lshlrev_b32_e32 v236, 16, v237
	v_and_b32_e32 v237, 0xffff0000, v237
	v_pk_add_f32 v[218:219], v[218:219], v[216:217]
	v_pk_add_f32 v[220:221], v[220:221], v[236:237]
	ds_read_b128 v[234:237], v163 offset:3360
	s_waitcnt lgkmcnt(7)
	v_lshlrev_b32_e32 v216, 16, v238
	v_and_b32_e32 v217, 0xffff0000, v238
	v_lshlrev_b32_e32 v238, 16, v239
	v_and_b32_e32 v239, 0xffff0000, v239
	v_pk_add_f32 v[106:107], v[106:107], v[216:217]
	v_pk_add_f32 v[108:109], v[108:109], v[238:239]
	v_lshlrev_b32_e32 v216, 16, v240
	v_and_b32_e32 v217, 0xffff0000, v240
	v_lshlrev_b32_e32 v240, 16, v241
	v_and_b32_e32 v241, 0xffff0000, v241
	v_pk_add_f32 v[218:219], v[218:219], v[216:217]
	v_pk_add_f32 v[220:221], v[220:221], v[240:241]
	ds_read_b128 v[238:241], v163 offset:3088
	s_waitcnt lgkmcnt(7)
	v_lshlrev_b32_e32 v216, 16, v242
	v_and_b32_e32 v217, 0xffff0000, v242
	v_lshlrev_b32_e32 v242, 16, v243
	v_and_b32_e32 v243, 0xffff0000, v243
	v_pk_add_f32 v[106:107], v[106:107], v[216:217]
	v_pk_add_f32 v[108:109], v[108:109], v[242:243]
	v_lshlrev_b32_e32 v216, 16, v244
	v_and_b32_e32 v217, 0xffff0000, v244
	v_lshlrev_b32_e32 v244, 16, v245
	v_and_b32_e32 v245, 0xffff0000, v245
	v_pk_add_f32 v[218:219], v[218:219], v[216:217]
	v_pk_add_f32 v[220:221], v[220:221], v[244:245]
	ds_read_b128 v[242:245], v163 offset:2816
	s_waitcnt lgkmcnt(7)
	v_lshlrev_b32_e32 v216, 16, v248
	v_and_b32_e32 v217, 0xffff0000, v248
	v_lshlrev_b32_e32 v248, 16, v249
	v_and_b32_e32 v249, 0xffff0000, v249
	v_pk_add_f32 v[106:107], v[106:107], v[216:217]
	v_pk_add_f32 v[108:109], v[108:109], v[248:249]
	v_lshlrev_b32_e32 v216, 16, v250
	v_and_b32_e32 v217, 0xffff0000, v250
	v_lshlrev_b32_e32 v250, 16, v251
	v_and_b32_e32 v251, 0xffff0000, v251
	v_pk_add_f32 v[218:219], v[218:219], v[216:217]
	v_pk_add_f32 v[220:221], v[220:221], v[250:251]
	ds_read_b128 v[248:251], v163 offset:2544
	s_waitcnt lgkmcnt(7)
	v_lshlrev_b32_e32 v216, 16, v252
	v_and_b32_e32 v217, 0xffff0000, v252
	v_lshlrev_b32_e32 v252, 16, v253
	v_and_b32_e32 v253, 0xffff0000, v253
	v_pk_add_f32 v[106:107], v[106:107], v[216:217]
	v_pk_add_f32 v[108:109], v[108:109], v[252:253]
	v_lshlrev_b32_e32 v216, 16, v254
	v_and_b32_e32 v217, 0xffff0000, v254
	v_lshlrev_b32_e32 v254, 16, v255
	v_and_b32_e32 v255, 0xffff0000, v255
	v_pk_add_f32 v[218:219], v[218:219], v[216:217]
	v_pk_add_f32 v[220:221], v[220:221], v[254:255]
	ds_read_b128 v[252:255], v163 offset:2272
	v_fma_f32 v106, v159, v106, -v98
	v_fma_f32 v107, v159, v107, -v99
	v_fma_f32 v108, v159, v108, -v100
	v_fma_f32 v109, v159, v109, -v101
	v_fma_f32 v218, v159, v218, -v102
	v_fma_f32 v219, v159, v219, -v103
	v_fma_f32 v220, v159, v220, -v104
	v_fma_f32 v221, v159, v221, -v105
	v_cvt_pk_bf16_f32 v106, v106, v107
	v_cvt_pk_bf16_f32 v107, v108, v109
	v_cvt_pk_bf16_f32 v108, v218, v219
	v_cvt_pk_bf16_f32 v109, v220, v221
	s_and_saveexec_b64 s[28:29], s[6:7]
	s_cbranch_execz .Lpu0_2
	global_store_dwordx4 v[192:193], v[98:101], off offset:128
	global_store_dwordx4 v[192:193], v[102:105], off offset:144
.Lpu0_2:
	s_or_b64 exec, exec, s[28:29]
	s_waitcnt vmcnt(8)
	v_mfma_f32_32x32x16_bf16 v[2:17], v[106:109], v[112:115], v[2:17]
	v_mfma_f32_32x32x16_bf16 v[18:33], v[106:109], v[116:119], v[18:33]
	v_mfma_f32_32x32x16_bf16 v[34:49], v[106:109], v[122:125], v[34:49]
	v_mfma_f32_32x32x16_bf16 v[50:65], v[106:109], v[126:129], v[50:65]
	global_load_dwordx4 v[112:115], v[144:145], off offset:2560
	global_load_dwordx4 v[116:119], v[146:147], off offset:2560
	global_load_dwordx4 v[122:125], v[148:149], off offset:2560
	global_load_dwordx4 v[126:129], v[150:151], off offset:2560
	s_waitcnt lgkmcnt(7)
	v_lshlrev_b32_e32 v98, 16, v222
	v_and_b32_e32 v99, 0xffff0000, v222
	v_lshlrev_b32_e32 v100, 16, v223
	v_and_b32_e32 v101, 0xffff0000, v223
	v_lshlrev_b32_e32 v102, 16, v224
	v_and_b32_e32 v103, 0xffff0000, v224
	v_lshlrev_b32_e32 v104, 16, v225
	v_and_b32_e32 v105, 0xffff0000, v225
	ds_read_b128 v[222:225], v163 offset:2000
	s_waitcnt lgkmcnt(7)
	v_lshlrev_b32_e32 v216, 16, v226
	v_and_b32_e32 v217, 0xffff0000, v226
	v_lshlrev_b32_e32 v226, 16, v227
	v_and_b32_e32 v227, 0xffff0000, v227
	v_pk_add_f32 v[106:107], v[98:99], v[216:217]
	v_pk_add_f32 v[108:109], v[100:101], v[226:227]
	v_lshlrev_b32_e32 v216, 16, v228
	v_and_b32_e32 v217, 0xffff0000, v228
	v_lshlrev_b32_e32 v228, 16, v229
	v_and_b32_e32 v229, 0xffff0000, v229
	v_pk_add_f32 v[218:219], v[102:103], v[216:217]
	v_pk_add_f32 v[220:221], v[104:105], v[228:229]
	ds_read_b128 v[226:229], v163 offset:1728
	s_waitcnt lgkmcnt(7)
	v_lshlrev_b32_e32 v216, 16, v230
	v_and_b32_e32 v217, 0xffff0000, v230
	v_lshlrev_b32_e32 v230, 16, v231
	v_and_b32_e32 v231, 0xffff0000, v231
	v_pk_add_f32 v[106:107], v[106:107], v[216:217]
	v_pk_add_f32 v[108:109], v[108:109], v[230:231]
	v_lshlrev_b32_e32 v216, 16, v232
	v_and_b32_e32 v217, 0xffff0000, v232
	v_lshlrev_b32_e32 v232, 16, v233
	v_and_b32_e32 v233, 0xffff0000, v233
	v_pk_add_f32 v[218:219], v[218:219], v[216:217]
	v_pk_add_f32 v[220:221], v[220:221], v[232:233]
	ds_read_b128 v[230:233], v163 offset:1456
	s_waitcnt lgkmcnt(7)
	v_lshlrev_b32_e32 v216, 16, v234
	v_and_b32_e32 v217, 0xffff0000, v234
	v_lshlrev_b32_e32 v234, 16, v235
	v_and_b32_e32 v235, 0xffff0000, v235
	v_pk_add_f32 v[106:107], v[106:107], v[216:217]
	v_pk_add_f32 v[108:109], v[108:109], v[234:235]
	v_lshlrev_b32_e32 v216, 16, v236
	v_and_b32_e32 v217, 0xffff0000, v236
	v_lshlrev_b32_e32 v236, 16, v237
	v_and_b32_e32 v237, 0xffff0000, v237
	v_pk_add_f32 v[218:219], v[218:219], v[216:217]
	v_pk_add_f32 v[220:221], v[220:221], v[236:237]
	ds_read_b128 v[234:237], v163 offset:1184
	s_waitcnt lgkmcnt(7)
	v_lshlrev_b32_e32 v216, 16, v238
	v_and_b32_e32 v217, 0xffff0000, v238
	v_lshlrev_b32_e32 v238, 16, v239
	v_and_b32_e32 v239, 0xffff0000, v239
	v_pk_add_f32 v[106:107], v[106:107], v[216:217]
	v_pk_add_f32 v[108:109], v[108:109], v[238:239]
	v_lshlrev_b32_e32 v216, 16, v240
	v_and_b32_e32 v217, 0xffff0000, v240
	v_lshlrev_b32_e32 v240, 16, v241
	v_and_b32_e32 v241, 0xffff0000, v241
	v_pk_add_f32 v[218:219], v[218:219], v[216:217]
	v_pk_add_f32 v[220:221], v[220:221], v[240:241]
	ds_read_b128 v[238:241], v163 offset:912
	s_waitcnt lgkmcnt(7)
	v_lshlrev_b32_e32 v216, 16, v242
	v_and_b32_e32 v217, 0xffff0000, v242
	v_lshlrev_b32_e32 v242, 16, v243
	v_and_b32_e32 v243, 0xffff0000, v243
	v_pk_add_f32 v[106:107], v[106:107], v[216:217]
	v_pk_add_f32 v[108:109], v[108:109], v[242:243]
	v_lshlrev_b32_e32 v216, 16, v244
	v_and_b32_e32 v217, 0xffff0000, v244
	v_lshlrev_b32_e32 v244, 16, v245
	v_and_b32_e32 v245, 0xffff0000, v245
	v_pk_add_f32 v[218:219], v[218:219], v[216:217]
	v_pk_add_f32 v[220:221], v[220:221], v[244:245]
	ds_read_b128 v[242:245], v163 offset:640
	s_waitcnt lgkmcnt(7)
	v_lshlrev_b32_e32 v216, 16, v248
	v_and_b32_e32 v217, 0xffff0000, v248
	v_lshlrev_b32_e32 v248, 16, v249
	v_and_b32_e32 v249, 0xffff0000, v249
	v_pk_add_f32 v[106:107], v[106:107], v[216:217]
	v_pk_add_f32 v[108:109], v[108:109], v[248:249]
	v_lshlrev_b32_e32 v216, 16, v250
	v_and_b32_e32 v217, 0xffff0000, v250
	v_lshlrev_b32_e32 v250, 16, v251
	v_and_b32_e32 v251, 0xffff0000, v251
	v_pk_add_f32 v[218:219], v[218:219], v[216:217]
	v_pk_add_f32 v[220:221], v[220:221], v[250:251]
	ds_read_b128 v[248:251], v163 offset:368
	s_waitcnt lgkmcnt(7)
	v_lshlrev_b32_e32 v216, 16, v252
	v_and_b32_e32 v217, 0xffff0000, v252
	v_lshlrev_b32_e32 v252, 16, v253
	v_and_b32_e32 v253, 0xffff0000, v253
	v_pk_add_f32 v[106:107], v[106:107], v[216:217]
	v_pk_add_f32 v[108:109], v[108:109], v[252:253]
	v_lshlrev_b32_e32 v216, 16, v254
	v_and_b32_e32 v217, 0xffff0000, v254
	v_lshlrev_b32_e32 v254, 16, v255
	v_and_b32_e32 v255, 0xffff0000, v255
	v_pk_add_f32 v[218:219], v[218:219], v[216:217]
	v_pk_add_f32 v[220:221], v[220:221], v[254:255]
	ds_read_b128 v[252:255], v163 offset:96
	s_waitcnt lgkmcnt(7)
	v_lshlrev_b32_e32 v216, 16, v222
	v_and_b32_e32 v217, 0xffff0000, v222
	v_lshlrev_b32_e32 v222, 16, v223
	v_and_b32_e32 v223, 0xffff0000, v223
	v_pk_add_f32 v[106:107], v[106:107], v[216:217]
	v_pk_add_f32 v[108:109], v[108:109], v[222:223]
	v_lshlrev_b32_e32 v216, 16, v224
	v_and_b32_e32 v217, 0xffff0000, v224
	v_lshlrev_b32_e32 v224, 16, v225
	v_and_b32_e32 v225, 0xffff0000, v225
	v_pk_add_f32 v[218:219], v[218:219], v[216:217]
	v_pk_add_f32 v[220:221], v[220:221], v[224:225]
	ds_read_b128 v[222:225], v163 offset:4208
	s_waitcnt lgkmcnt(7)
	v_lshlrev_b32_e32 v216, 16, v226
	v_and_b32_e32 v217, 0xffff0000, v226
	v_lshlrev_b32_e32 v226, 16, v227
	v_and_b32_e32 v227, 0xffff0000, v227
	v_pk_add_f32 v[106:107], v[106:107], v[216:217]
	v_pk_add_f32 v[108:109], v[108:109], v[226:227]
	v_lshlrev_b32_e32 v216, 16, v228
	v_and_b32_e32 v217, 0xffff0000, v228
	v_lshlrev_b32_e32 v228, 16, v229
	v_and_b32_e32 v229, 0xffff0000, v229
	v_pk_add_f32 v[218:219], v[218:219], v[216:217]
	v_pk_add_f32 v[220:221], v[220:221], v[228:229]
	ds_read_b128 v[226:229], v163 offset:3936
	s_waitcnt lgkmcnt(7)
	v_lshlrev_b32_e32 v216, 16, v230
	v_and_b32_e32 v217, 0xffff0000, v230
	v_lshlrev_b32_e32 v230, 16, v231
	v_and_b32_e32 v231, 0xffff0000, v231
	v_pk_add_f32 v[106:107], v[106:107], v[216:217]
	v_pk_add_f32 v[108:109], v[108:109], v[230:231]
	v_lshlrev_b32_e32 v216, 16, v232
	v_and_b32_e32 v217, 0xffff0000, v232
	v_lshlrev_b32_e32 v232, 16, v233
	v_and_b32_e32 v233, 0xffff0000, v233
	v_pk_add_f32 v[218:219], v[218:219], v[216:217]
	v_pk_add_f32 v[220:221], v[220:221], v[232:233]
	ds_read_b128 v[230:233], v163 offset:3664
	s_waitcnt lgkmcnt(7)
	v_lshlrev_b32_e32 v216, 16, v234
	v_and_b32_e32 v217, 0xffff0000, v234
	v_lshlrev_b32_e32 v234, 16, v235
	v_and_b32_e32 v235, 0xffff0000, v235
	v_pk_add_f32 v[106:107], v[106:107], v[216:217]
	v_pk_add_f32 v[108:109], v[108:109], v[234:235]
	v_lshlrev_b32_e32 v216, 16, v236
	v_and_b32_e32 v217, 0xffff0000, v236
	v_lshlrev_b32_e32 v236, 16, v237
	v_and_b32_e32 v237, 0xffff0000, v237
	v_pk_add_f32 v[218:219], v[218:219], v[216:217]
	v_pk_add_f32 v[220:221], v[220:221], v[236:237]
	ds_read_b128 v[234:237], v163 offset:3392
	s_waitcnt lgkmcnt(7)
	v_lshlrev_b32_e32 v216, 16, v238
	v_and_b32_e32 v217, 0xffff0000, v238
	v_lshlrev_b32_e32 v238, 16, v239
	v_and_b32_e32 v239, 0xffff0000, v239
	v_pk_add_f32 v[106:107], v[106:107], v[216:217]
	v_pk_add_f32 v[108:109], v[108:109], v[238:239]
	v_lshlrev_b32_e32 v216, 16, v240
	v_and_b32_e32 v217, 0xffff0000, v240
	v_lshlrev_b32_e32 v240, 16, v241
	v_and_b32_e32 v241, 0xffff0000, v241
	v_pk_add_f32 v[218:219], v[218:219], v[216:217]
	v_pk_add_f32 v[220:221], v[220:221], v[240:241]
	ds_read_b128 v[238:241], v163 offset:3120
	s_waitcnt lgkmcnt(7)
	v_lshlrev_b32_e32 v216, 16, v242
	v_and_b32_e32 v217, 0xffff0000, v242
	v_lshlrev_b32_e32 v242, 16, v243
	v_and_b32_e32 v243, 0xffff0000, v243
	v_pk_add_f32 v[106:107], v[106:107], v[216:217]
	v_pk_add_f32 v[108:109], v[108:109], v[242:243]
	v_lshlrev_b32_e32 v216, 16, v244
	v_and_b32_e32 v217, 0xffff0000, v244
	v_lshlrev_b32_e32 v244, 16, v245
	v_and_b32_e32 v245, 0xffff0000, v245
	v_pk_add_f32 v[218:219], v[218:219], v[216:217]
	v_pk_add_f32 v[220:221], v[220:221], v[244:245]
	ds_read_b128 v[242:245], v163 offset:2848
	s_waitcnt lgkmcnt(7)
	v_lshlrev_b32_e32 v216, 16, v248
	v_and_b32_e32 v217, 0xffff0000, v248
	v_lshlrev_b32_e32 v248, 16, v249
	v_and_b32_e32 v249, 0xffff0000, v249
	v_pk_add_f32 v[106:107], v[106:107], v[216:217]
	v_pk_add_f32 v[108:109], v[108:109], v[248:249]
	v_lshlrev_b32_e32 v216, 16, v250
	v_and_b32_e32 v217, 0xffff0000, v250
	v_lshlrev_b32_e32 v250, 16, v251
	v_and_b32_e32 v251, 0xffff0000, v251
	v_pk_add_f32 v[218:219], v[218:219], v[216:217]
	v_pk_add_f32 v[220:221], v[220:221], v[250:251]
	ds_read_b128 v[248:251], v163 offset:2576
	s_waitcnt lgkmcnt(7)
	v_lshlrev_b32_e32 v216, 16, v252
	v_and_b32_e32 v217, 0xffff0000, v252
	v_lshlrev_b32_e32 v252, 16, v253
	v_and_b32_e32 v253, 0xffff0000, v253
	v_pk_add_f32 v[106:107], v[106:107], v[216:217]
	v_pk_add_f32 v[108:109], v[108:109], v[252:253]
	v_lshlrev_b32_e32 v216, 16, v254
	v_and_b32_e32 v217, 0xffff0000, v254
	v_lshlrev_b32_e32 v254, 16, v255
	v_and_b32_e32 v255, 0xffff0000, v255
	v_pk_add_f32 v[218:219], v[218:219], v[216:217]
	v_pk_add_f32 v[220:221], v[220:221], v[254:255]
	ds_read_b128 v[252:255], v163 offset:2304
	v_fma_f32 v106, v159, v106, -v98
	v_fma_f32 v107, v159, v107, -v99
	v_fma_f32 v108, v159, v108, -v100
	v_fma_f32 v109, v159, v109, -v101
	v_fma_f32 v218, v159, v218, -v102
	v_fma_f32 v219, v159, v219, -v103
	v_fma_f32 v220, v159, v220, -v104
	v_fma_f32 v221, v159, v221, -v105
	v_cvt_pk_bf16_f32 v106, v106, v107
	v_cvt_pk_bf16_f32 v107, v108, v109
	v_cvt_pk_bf16_f32 v108, v218, v219
	v_cvt_pk_bf16_f32 v109, v220, v221
	s_and_saveexec_b64 s[28:29], s[6:7]
	s_cbranch_execz .Lpu0_3
	global_store_dwordx4 v[192:193], v[98:101], off offset:192
	global_store_dwordx4 v[192:193], v[102:105], off offset:208
.Lpu0_3:
	s_or_b64 exec, exec, s[28:29]
	s_waitcnt vmcnt(8)
	v_mfma_f32_32x32x16_bf16 v[2:17], v[106:109], v[70:73], v[2:17]
	v_mfma_f32_32x32x16_bf16 v[18:33], v[106:109], v[74:77], v[18:33]
	v_mfma_f32_32x32x16_bf16 v[34:49], v[106:109], v[78:81], v[34:49]
	v_mfma_f32_32x32x16_bf16 v[50:65], v[106:109], v[66:69], v[50:65]
	global_load_dwordx4 v[70:73], v[144:145], off offset:3072
	global_load_dwordx4 v[74:77], v[146:147], off offset:3072
	global_load_dwordx4 v[78:81], v[148:149], off offset:3072
	global_load_dwordx4 v[66:69], v[150:151], off offset:3072
	s_waitcnt lgkmcnt(7)
	v_lshlrev_b32_e32 v98, 16, v222
	v_and_b32_e32 v99, 0xffff0000, v222
	v_lshlrev_b32_e32 v100, 16, v223
	v_and_b32_e32 v101, 0xffff0000, v223
	v_lshlrev_b32_e32 v102, 16, v224
	v_and_b32_e32 v103, 0xffff0000, v224
	v_lshlrev_b32_e32 v104, 16, v225
	v_and_b32_e32 v105, 0xffff0000, v225
	ds_read_b128 v[222:225], v163 offset:2032
	s_waitcnt lgkmcnt(7)
	v_lshlrev_b32_e32 v216, 16, v226
	v_and_b32_e32 v217, 0xffff0000, v226
	v_lshlrev_b32_e32 v226, 16, v227
	v_and_b32_e32 v227, 0xffff0000, v227
	v_pk_add_f32 v[106:107], v[98:99], v[216:217]
	v_pk_add_f32 v[108:109], v[100:101], v[226:227]
	v_lshlrev_b32_e32 v216, 16, v228
	v_and_b32_e32 v217, 0xffff0000, v228
	v_lshlrev_b32_e32 v228, 16, v229
	v_and_b32_e32 v229, 0xffff0000, v229
	v_pk_add_f32 v[218:219], v[102:103], v[216:217]
	v_pk_add_f32 v[220:221], v[104:105], v[228:229]
	ds_read_b128 v[226:229], v163 offset:1760
	s_waitcnt lgkmcnt(7)
	v_lshlrev_b32_e32 v216, 16, v230
	v_and_b32_e32 v217, 0xffff0000, v230
	v_lshlrev_b32_e32 v230, 16, v231
	v_and_b32_e32 v231, 0xffff0000, v231
	v_pk_add_f32 v[106:107], v[106:107], v[216:217]
	v_pk_add_f32 v[108:109], v[108:109], v[230:231]
	v_lshlrev_b32_e32 v216, 16, v232
	v_and_b32_e32 v217, 0xffff0000, v232
	v_lshlrev_b32_e32 v232, 16, v233
	v_and_b32_e32 v233, 0xffff0000, v233
	v_pk_add_f32 v[218:219], v[218:219], v[216:217]
	v_pk_add_f32 v[220:221], v[220:221], v[232:233]
	ds_read_b128 v[230:233], v163 offset:1488
	s_waitcnt lgkmcnt(7)
	v_lshlrev_b32_e32 v216, 16, v234
	v_and_b32_e32 v217, 0xffff0000, v234
	v_lshlrev_b32_e32 v234, 16, v235
	v_and_b32_e32 v235, 0xffff0000, v235
	v_pk_add_f32 v[106:107], v[106:107], v[216:217]
	v_pk_add_f32 v[108:109], v[108:109], v[234:235]
	v_lshlrev_b32_e32 v216, 16, v236
	v_and_b32_e32 v217, 0xffff0000, v236
	v_lshlrev_b32_e32 v236, 16, v237
	v_and_b32_e32 v237, 0xffff0000, v237
	v_pk_add_f32 v[218:219], v[218:219], v[216:217]
	v_pk_add_f32 v[220:221], v[220:221], v[236:237]
	ds_read_b128 v[234:237], v163 offset:1216
	s_waitcnt lgkmcnt(7)
	v_lshlrev_b32_e32 v216, 16, v238
	v_and_b32_e32 v217, 0xffff0000, v238
	v_lshlrev_b32_e32 v238, 16, v239
	v_and_b32_e32 v239, 0xffff0000, v239
	v_pk_add_f32 v[106:107], v[106:107], v[216:217]
	v_pk_add_f32 v[108:109], v[108:109], v[238:239]
	v_lshlrev_b32_e32 v216, 16, v240
	v_and_b32_e32 v217, 0xffff0000, v240
	v_lshlrev_b32_e32 v240, 16, v241
	v_and_b32_e32 v241, 0xffff0000, v241
	v_pk_add_f32 v[218:219], v[218:219], v[216:217]
	v_pk_add_f32 v[220:221], v[220:221], v[240:241]
	ds_read_b128 v[238:241], v163 offset:944
	s_waitcnt lgkmcnt(7)
	v_lshlrev_b32_e32 v216, 16, v242
	v_and_b32_e32 v217, 0xffff0000, v242
	v_lshlrev_b32_e32 v242, 16, v243
	v_and_b32_e32 v243, 0xffff0000, v243
	v_pk_add_f32 v[106:107], v[106:107], v[216:217]
	v_pk_add_f32 v[108:109], v[108:109], v[242:243]
	v_lshlrev_b32_e32 v216, 16, v244
	v_and_b32_e32 v217, 0xffff0000, v244
	v_lshlrev_b32_e32 v244, 16, v245
	v_and_b32_e32 v245, 0xffff0000, v245
	v_pk_add_f32 v[218:219], v[218:219], v[216:217]
	v_pk_add_f32 v[220:221], v[220:221], v[244:245]
	ds_read_b128 v[242:245], v163 offset:672
	s_waitcnt lgkmcnt(7)
	v_lshlrev_b32_e32 v216, 16, v248
	v_and_b32_e32 v217, 0xffff0000, v248
	v_lshlrev_b32_e32 v248, 16, v249
	v_and_b32_e32 v249, 0xffff0000, v249
	v_pk_add_f32 v[106:107], v[106:107], v[216:217]
	v_pk_add_f32 v[108:109], v[108:109], v[248:249]
	v_lshlrev_b32_e32 v216, 16, v250
	v_and_b32_e32 v217, 0xffff0000, v250
	v_lshlrev_b32_e32 v250, 16, v251
	v_and_b32_e32 v251, 0xffff0000, v251
	v_pk_add_f32 v[218:219], v[218:219], v[216:217]
	v_pk_add_f32 v[220:221], v[220:221], v[250:251]
	ds_read_b128 v[248:251], v163 offset:400
	s_waitcnt lgkmcnt(7)
	v_lshlrev_b32_e32 v216, 16, v252
	v_and_b32_e32 v217, 0xffff0000, v252
	v_lshlrev_b32_e32 v252, 16, v253
	v_and_b32_e32 v253, 0xffff0000, v253
	v_pk_add_f32 v[106:107], v[106:107], v[216:217]
	v_pk_add_f32 v[108:109], v[108:109], v[252:253]
	v_lshlrev_b32_e32 v216, 16, v254
	v_and_b32_e32 v217, 0xffff0000, v254
	v_lshlrev_b32_e32 v254, 16, v255
	v_and_b32_e32 v255, 0xffff0000, v255
	v_pk_add_f32 v[218:219], v[218:219], v[216:217]
	v_pk_add_f32 v[220:221], v[220:221], v[254:255]
	ds_read_b128 v[252:255], v163 offset:128
	s_waitcnt lgkmcnt(7)
	v_lshlrev_b32_e32 v216, 16, v222
	v_and_b32_e32 v217, 0xffff0000, v222
	v_lshlrev_b32_e32 v222, 16, v223
	v_and_b32_e32 v223, 0xffff0000, v223
	v_pk_add_f32 v[106:107], v[106:107], v[216:217]
	v_pk_add_f32 v[108:109], v[108:109], v[222:223]
	v_lshlrev_b32_e32 v216, 16, v224
	v_and_b32_e32 v217, 0xffff0000, v224
	v_lshlrev_b32_e32 v224, 16, v225
	v_and_b32_e32 v225, 0xffff0000, v225
	v_pk_add_f32 v[218:219], v[218:219], v[216:217]
	v_pk_add_f32 v[220:221], v[220:221], v[224:225]
	ds_read_b128 v[222:225], v163 offset:4240
	s_waitcnt lgkmcnt(7)
	v_lshlrev_b32_e32 v216, 16, v226
	v_and_b32_e32 v217, 0xffff0000, v226
	v_lshlrev_b32_e32 v226, 16, v227
	v_and_b32_e32 v227, 0xffff0000, v227
	v_pk_add_f32 v[106:107], v[106:107], v[216:217]
	v_pk_add_f32 v[108:109], v[108:109], v[226:227]
	v_lshlrev_b32_e32 v216, 16, v228
	v_and_b32_e32 v217, 0xffff0000, v228
	v_lshlrev_b32_e32 v228, 16, v229
	v_and_b32_e32 v229, 0xffff0000, v229
	v_pk_add_f32 v[218:219], v[218:219], v[216:217]
	v_pk_add_f32 v[220:221], v[220:221], v[228:229]
	ds_read_b128 v[226:229], v163 offset:3968
	s_waitcnt lgkmcnt(7)
	v_lshlrev_b32_e32 v216, 16, v230
	v_and_b32_e32 v217, 0xffff0000, v230
	v_lshlrev_b32_e32 v230, 16, v231
	v_and_b32_e32 v231, 0xffff0000, v231
	v_pk_add_f32 v[106:107], v[106:107], v[216:217]
	v_pk_add_f32 v[108:109], v[108:109], v[230:231]
	v_lshlrev_b32_e32 v216, 16, v232
	v_and_b32_e32 v217, 0xffff0000, v232
	v_lshlrev_b32_e32 v232, 16, v233
	v_and_b32_e32 v233, 0xffff0000, v233
	v_pk_add_f32 v[218:219], v[218:219], v[216:217]
	v_pk_add_f32 v[220:221], v[220:221], v[232:233]
	ds_read_b128 v[230:233], v163 offset:3696
	s_waitcnt lgkmcnt(7)
	v_lshlrev_b32_e32 v216, 16, v234
	v_and_b32_e32 v217, 0xffff0000, v234
	v_lshlrev_b32_e32 v234, 16, v235
	v_and_b32_e32 v235, 0xffff0000, v235
	v_pk_add_f32 v[106:107], v[106:107], v[216:217]
	v_pk_add_f32 v[108:109], v[108:109], v[234:235]
	v_lshlrev_b32_e32 v216, 16, v236
	v_and_b32_e32 v217, 0xffff0000, v236
	v_lshlrev_b32_e32 v236, 16, v237
	v_and_b32_e32 v237, 0xffff0000, v237
	v_pk_add_f32 v[218:219], v[218:219], v[216:217]
	v_pk_add_f32 v[220:221], v[220:221], v[236:237]
	ds_read_b128 v[234:237], v163 offset:3424
	s_waitcnt lgkmcnt(7)
	v_lshlrev_b32_e32 v216, 16, v238
	v_and_b32_e32 v217, 0xffff0000, v238
	v_lshlrev_b32_e32 v238, 16, v239
	v_and_b32_e32 v239, 0xffff0000, v239
	v_pk_add_f32 v[106:107], v[106:107], v[216:217]
	v_pk_add_f32 v[108:109], v[108:109], v[238:239]
	v_lshlrev_b32_e32 v216, 16, v240
	v_and_b32_e32 v217, 0xffff0000, v240
	v_lshlrev_b32_e32 v240, 16, v241
	v_and_b32_e32 v241, 0xffff0000, v241
	v_pk_add_f32 v[218:219], v[218:219], v[216:217]
	v_pk_add_f32 v[220:221], v[220:221], v[240:241]
	ds_read_b128 v[238:241], v163 offset:3152
	s_waitcnt lgkmcnt(7)
	v_lshlrev_b32_e32 v216, 16, v242
	v_and_b32_e32 v217, 0xffff0000, v242
	v_lshlrev_b32_e32 v242, 16, v243
	v_and_b32_e32 v243, 0xffff0000, v243
	v_pk_add_f32 v[106:107], v[106:107], v[216:217]
	v_pk_add_f32 v[108:109], v[108:109], v[242:243]
	v_lshlrev_b32_e32 v216, 16, v244
	v_and_b32_e32 v217, 0xffff0000, v244
	v_lshlrev_b32_e32 v244, 16, v245
	v_and_b32_e32 v245, 0xffff0000, v245
	v_pk_add_f32 v[218:219], v[218:219], v[216:217]
	v_pk_add_f32 v[220:221], v[220:221], v[244:245]
	ds_read_b128 v[242:245], v163 offset:2880
	s_waitcnt lgkmcnt(7)
	v_lshlrev_b32_e32 v216, 16, v248
	v_and_b32_e32 v217, 0xffff0000, v248
	v_lshlrev_b32_e32 v248, 16, v249
	v_and_b32_e32 v249, 0xffff0000, v249
	v_pk_add_f32 v[106:107], v[106:107], v[216:217]
	v_pk_add_f32 v[108:109], v[108:109], v[248:249]
	v_lshlrev_b32_e32 v216, 16, v250
	v_and_b32_e32 v217, 0xffff0000, v250
	v_lshlrev_b32_e32 v250, 16, v251
	v_and_b32_e32 v251, 0xffff0000, v251
	v_pk_add_f32 v[218:219], v[218:219], v[216:217]
	v_pk_add_f32 v[220:221], v[220:221], v[250:251]
	ds_read_b128 v[248:251], v163 offset:2608
	s_waitcnt lgkmcnt(7)
	v_lshlrev_b32_e32 v216, 16, v252
	v_and_b32_e32 v217, 0xffff0000, v252
	v_lshlrev_b32_e32 v252, 16, v253
	v_and_b32_e32 v253, 0xffff0000, v253
	v_pk_add_f32 v[106:107], v[106:107], v[216:217]
	v_pk_add_f32 v[108:109], v[108:109], v[252:253]
	v_lshlrev_b32_e32 v216, 16, v254
	v_and_b32_e32 v217, 0xffff0000, v254
	v_lshlrev_b32_e32 v254, 16, v255
	v_and_b32_e32 v255, 0xffff0000, v255
	v_pk_add_f32 v[218:219], v[218:219], v[216:217]
	v_pk_add_f32 v[220:221], v[220:221], v[254:255]
	ds_read_b128 v[252:255], v163 offset:2336
	v_fma_f32 v106, v159, v106, -v98
	v_fma_f32 v107, v159, v107, -v99
	v_fma_f32 v108, v159, v108, -v100
	v_fma_f32 v109, v159, v109, -v101
	v_fma_f32 v218, v159, v218, -v102
	v_fma_f32 v219, v159, v219, -v103
	v_fma_f32 v220, v159, v220, -v104
	v_fma_f32 v221, v159, v221, -v105
	v_cvt_pk_bf16_f32 v106, v106, v107
	v_cvt_pk_bf16_f32 v107, v108, v109
	v_cvt_pk_bf16_f32 v108, v218, v219
	v_cvt_pk_bf16_f32 v109, v220, v221
	s_and_saveexec_b64 s[28:29], s[6:7]
	s_cbranch_execz .Lpu0_4
	global_store_dwordx4 v[192:193], v[98:101], off offset:256
	global_store_dwordx4 v[192:193], v[102:105], off offset:272
.Lpu0_4:
	s_or_b64 exec, exec, s[28:29]
	s_waitcnt vmcnt(8)
	v_mfma_f32_32x32x16_bf16 v[2:17], v[106:109], v[82:85], v[2:17]
	v_mfma_f32_32x32x16_bf16 v[18:33], v[106:109], v[86:89], v[18:33]
	v_mfma_f32_32x32x16_bf16 v[34:49], v[106:109], v[90:93], v[34:49]
	v_mfma_f32_32x32x16_bf16 v[50:65], v[106:109], v[94:97], v[50:65]
	global_load_dwordx4 v[82:85], v[144:145], off offset:3584
	global_load_dwordx4 v[86:89], v[146:147], off offset:3584
	global_load_dwordx4 v[90:93], v[148:149], off offset:3584
	global_load_dwordx4 v[94:97], v[150:151], off offset:3584
	s_waitcnt lgkmcnt(7)
	v_lshlrev_b32_e32 v98, 16, v222
	v_and_b32_e32 v99, 0xffff0000, v222
	v_lshlrev_b32_e32 v100, 16, v223
	v_and_b32_e32 v101, 0xffff0000, v223
	v_lshlrev_b32_e32 v102, 16, v224
	v_and_b32_e32 v103, 0xffff0000, v224
	v_lshlrev_b32_e32 v104, 16, v225
	v_and_b32_e32 v105, 0xffff0000, v225
	ds_read_b128 v[222:225], v163 offset:2064
	s_waitcnt lgkmcnt(7)
	v_lshlrev_b32_e32 v216, 16, v226
	v_and_b32_e32 v217, 0xffff0000, v226
	v_lshlrev_b32_e32 v226, 16, v227
	v_and_b32_e32 v227, 0xffff0000, v227
	v_pk_add_f32 v[106:107], v[98:99], v[216:217]
	v_pk_add_f32 v[108:109], v[100:101], v[226:227]
	v_lshlrev_b32_e32 v216, 16, v228
	v_and_b32_e32 v217, 0xffff0000, v228
	v_lshlrev_b32_e32 v228, 16, v229
	v_and_b32_e32 v229, 0xffff0000, v229
	v_pk_add_f32 v[218:219], v[102:103], v[216:217]
	v_pk_add_f32 v[220:221], v[104:105], v[228:229]
	ds_read_b128 v[226:229], v163 offset:1792
	s_waitcnt lgkmcnt(7)
	v_lshlrev_b32_e32 v216, 16, v230
	v_and_b32_e32 v217, 0xffff0000, v230
	v_lshlrev_b32_e32 v230, 16, v231
	v_and_b32_e32 v231, 0xffff0000, v231
	v_pk_add_f32 v[106:107], v[106:107], v[216:217]
	v_pk_add_f32 v[108:109], v[108:109], v[230:231]
	v_lshlrev_b32_e32 v216, 16, v232
	v_and_b32_e32 v217, 0xffff0000, v232
	v_lshlrev_b32_e32 v232, 16, v233
	v_and_b32_e32 v233, 0xffff0000, v233
	v_pk_add_f32 v[218:219], v[218:219], v[216:217]
	v_pk_add_f32 v[220:221], v[220:221], v[232:233]
	ds_read_b128 v[230:233], v163 offset:1520
	s_waitcnt lgkmcnt(7)
	v_lshlrev_b32_e32 v216, 16, v234
	v_and_b32_e32 v217, 0xffff0000, v234
	v_lshlrev_b32_e32 v234, 16, v235
	v_and_b32_e32 v235, 0xffff0000, v235
	v_pk_add_f32 v[106:107], v[106:107], v[216:217]
	v_pk_add_f32 v[108:109], v[108:109], v[234:235]
	v_lshlrev_b32_e32 v216, 16, v236
	v_and_b32_e32 v217, 0xffff0000, v236
	v_lshlrev_b32_e32 v236, 16, v237
	v_and_b32_e32 v237, 0xffff0000, v237
	v_pk_add_f32 v[218:219], v[218:219], v[216:217]
	v_pk_add_f32 v[220:221], v[220:221], v[236:237]
	ds_read_b128 v[234:237], v163 offset:1248
	s_waitcnt lgkmcnt(7)
	v_lshlrev_b32_e32 v216, 16, v238
	v_and_b32_e32 v217, 0xffff0000, v238
	v_lshlrev_b32_e32 v238, 16, v239
	v_and_b32_e32 v239, 0xffff0000, v239
	v_pk_add_f32 v[106:107], v[106:107], v[216:217]
	v_pk_add_f32 v[108:109], v[108:109], v[238:239]
	v_lshlrev_b32_e32 v216, 16, v240
	v_and_b32_e32 v217, 0xffff0000, v240
	v_lshlrev_b32_e32 v240, 16, v241
	v_and_b32_e32 v241, 0xffff0000, v241
	v_pk_add_f32 v[218:219], v[218:219], v[216:217]
	v_pk_add_f32 v[220:221], v[220:221], v[240:241]
	ds_read_b128 v[238:241], v163 offset:976
	s_waitcnt lgkmcnt(7)
	v_lshlrev_b32_e32 v216, 16, v242
	v_and_b32_e32 v217, 0xffff0000, v242
	v_lshlrev_b32_e32 v242, 16, v243
	v_and_b32_e32 v243, 0xffff0000, v243
	v_pk_add_f32 v[106:107], v[106:107], v[216:217]
	v_pk_add_f32 v[108:109], v[108:109], v[242:243]
	v_lshlrev_b32_e32 v216, 16, v244
	v_and_b32_e32 v217, 0xffff0000, v244
	v_lshlrev_b32_e32 v244, 16, v245
	v_and_b32_e32 v245, 0xffff0000, v245
	v_pk_add_f32 v[218:219], v[218:219], v[216:217]
	v_pk_add_f32 v[220:221], v[220:221], v[244:245]
	ds_read_b128 v[242:245], v163 offset:704
	s_waitcnt lgkmcnt(7)
	v_lshlrev_b32_e32 v216, 16, v248
	v_and_b32_e32 v217, 0xffff0000, v248
	v_lshlrev_b32_e32 v248, 16, v249
	v_and_b32_e32 v249, 0xffff0000, v249
	v_pk_add_f32 v[106:107], v[106:107], v[216:217]
	v_pk_add_f32 v[108:109], v[108:109], v[248:249]
	v_lshlrev_b32_e32 v216, 16, v250
	v_and_b32_e32 v217, 0xffff0000, v250
	v_lshlrev_b32_e32 v250, 16, v251
	v_and_b32_e32 v251, 0xffff0000, v251
	v_pk_add_f32 v[218:219], v[218:219], v[216:217]
	v_pk_add_f32 v[220:221], v[220:221], v[250:251]
	ds_read_b128 v[248:251], v163 offset:432
	s_waitcnt lgkmcnt(7)
	v_lshlrev_b32_e32 v216, 16, v252
	v_and_b32_e32 v217, 0xffff0000, v252
	v_lshlrev_b32_e32 v252, 16, v253
	v_and_b32_e32 v253, 0xffff0000, v253
	v_pk_add_f32 v[106:107], v[106:107], v[216:217]
	v_pk_add_f32 v[108:109], v[108:109], v[252:253]
	v_lshlrev_b32_e32 v216, 16, v254
	v_and_b32_e32 v217, 0xffff0000, v254
	v_lshlrev_b32_e32 v254, 16, v255
	v_and_b32_e32 v255, 0xffff0000, v255
	v_pk_add_f32 v[218:219], v[218:219], v[216:217]
	v_pk_add_f32 v[220:221], v[220:221], v[254:255]
	ds_read_b128 v[252:255], v163 offset:160
	s_waitcnt lgkmcnt(7)
	v_lshlrev_b32_e32 v216, 16, v222
	v_and_b32_e32 v217, 0xffff0000, v222
	v_lshlrev_b32_e32 v222, 16, v223
	v_and_b32_e32 v223, 0xffff0000, v223
	v_pk_add_f32 v[106:107], v[106:107], v[216:217]
	v_pk_add_f32 v[108:109], v[108:109], v[222:223]
	v_lshlrev_b32_e32 v216, 16, v224
	v_and_b32_e32 v217, 0xffff0000, v224
	v_lshlrev_b32_e32 v224, 16, v225
	v_and_b32_e32 v225, 0xffff0000, v225
	v_pk_add_f32 v[218:219], v[218:219], v[216:217]
	v_pk_add_f32 v[220:221], v[220:221], v[224:225]
	ds_read_b128 v[222:225], v163 offset:4272
	s_waitcnt lgkmcnt(7)
	v_lshlrev_b32_e32 v216, 16, v226
	v_and_b32_e32 v217, 0xffff0000, v226
	v_lshlrev_b32_e32 v226, 16, v227
	v_and_b32_e32 v227, 0xffff0000, v227
	v_pk_add_f32 v[106:107], v[106:107], v[216:217]
	v_pk_add_f32 v[108:109], v[108:109], v[226:227]
	v_lshlrev_b32_e32 v216, 16, v228
	v_and_b32_e32 v217, 0xffff0000, v228
	v_lshlrev_b32_e32 v228, 16, v229
	v_and_b32_e32 v229, 0xffff0000, v229
	v_pk_add_f32 v[218:219], v[218:219], v[216:217]
	v_pk_add_f32 v[220:221], v[220:221], v[228:229]
	ds_read_b128 v[226:229], v163 offset:4000
	s_waitcnt lgkmcnt(7)
	v_lshlrev_b32_e32 v216, 16, v230
	v_and_b32_e32 v217, 0xffff0000, v230
	v_lshlrev_b32_e32 v230, 16, v231
	v_and_b32_e32 v231, 0xffff0000, v231
	v_pk_add_f32 v[106:107], v[106:107], v[216:217]
	v_pk_add_f32 v[108:109], v[108:109], v[230:231]
	v_lshlrev_b32_e32 v216, 16, v232
	v_and_b32_e32 v217, 0xffff0000, v232
	v_lshlrev_b32_e32 v232, 16, v233
	v_and_b32_e32 v233, 0xffff0000, v233
	v_pk_add_f32 v[218:219], v[218:219], v[216:217]
	v_pk_add_f32 v[220:221], v[220:221], v[232:233]
	ds_read_b128 v[230:233], v163 offset:3728
	s_waitcnt lgkmcnt(7)
	v_lshlrev_b32_e32 v216, 16, v234
	v_and_b32_e32 v217, 0xffff0000, v234
	v_lshlrev_b32_e32 v234, 16, v235
	v_and_b32_e32 v235, 0xffff0000, v235
	v_pk_add_f32 v[106:107], v[106:107], v[216:217]
	v_pk_add_f32 v[108:109], v[108:109], v[234:235]
	v_lshlrev_b32_e32 v216, 16, v236
	v_and_b32_e32 v217, 0xffff0000, v236
	v_lshlrev_b32_e32 v236, 16, v237
	v_and_b32_e32 v237, 0xffff0000, v237
	v_pk_add_f32 v[218:219], v[218:219], v[216:217]
	v_pk_add_f32 v[220:221], v[220:221], v[236:237]
	ds_read_b128 v[234:237], v163 offset:3456
	s_waitcnt lgkmcnt(7)
	v_lshlrev_b32_e32 v216, 16, v238
	v_and_b32_e32 v217, 0xffff0000, v238
	v_lshlrev_b32_e32 v238, 16, v239
	v_and_b32_e32 v239, 0xffff0000, v239
	v_pk_add_f32 v[106:107], v[106:107], v[216:217]
	v_pk_add_f32 v[108:109], v[108:109], v[238:239]
	v_lshlrev_b32_e32 v216, 16, v240
	v_and_b32_e32 v217, 0xffff0000, v240
	v_lshlrev_b32_e32 v240, 16, v241
	v_and_b32_e32 v241, 0xffff0000, v241
	v_pk_add_f32 v[218:219], v[218:219], v[216:217]
	v_pk_add_f32 v[220:221], v[220:221], v[240:241]
	ds_read_b128 v[238:241], v163 offset:3184
	s_waitcnt lgkmcnt(7)
	v_lshlrev_b32_e32 v216, 16, v242
	v_and_b32_e32 v217, 0xffff0000, v242
	v_lshlrev_b32_e32 v242, 16, v243
	v_and_b32_e32 v243, 0xffff0000, v243
	v_pk_add_f32 v[106:107], v[106:107], v[216:217]
	v_pk_add_f32 v[108:109], v[108:109], v[242:243]
	v_lshlrev_b32_e32 v216, 16, v244
	v_and_b32_e32 v217, 0xffff0000, v244
	v_lshlrev_b32_e32 v244, 16, v245
	v_and_b32_e32 v245, 0xffff0000, v245
	v_pk_add_f32 v[218:219], v[218:219], v[216:217]
	v_pk_add_f32 v[220:221], v[220:221], v[244:245]
	ds_read_b128 v[242:245], v163 offset:2912
	s_waitcnt lgkmcnt(7)
	v_lshlrev_b32_e32 v216, 16, v248
	v_and_b32_e32 v217, 0xffff0000, v248
	v_lshlrev_b32_e32 v248, 16, v249
	v_and_b32_e32 v249, 0xffff0000, v249
	v_pk_add_f32 v[106:107], v[106:107], v[216:217]
	v_pk_add_f32 v[108:109], v[108:109], v[248:249]
	v_lshlrev_b32_e32 v216, 16, v250
	v_and_b32_e32 v217, 0xffff0000, v250
	v_lshlrev_b32_e32 v250, 16, v251
	v_and_b32_e32 v251, 0xffff0000, v251
	v_pk_add_f32 v[218:219], v[218:219], v[216:217]
	v_pk_add_f32 v[220:221], v[220:221], v[250:251]
	ds_read_b128 v[248:251], v163 offset:2640
	s_waitcnt lgkmcnt(7)
	v_lshlrev_b32_e32 v216, 16, v252
	v_and_b32_e32 v217, 0xffff0000, v252
	v_lshlrev_b32_e32 v252, 16, v253
	v_and_b32_e32 v253, 0xffff0000, v253
	v_pk_add_f32 v[106:107], v[106:107], v[216:217]
	v_pk_add_f32 v[108:109], v[108:109], v[252:253]
	v_lshlrev_b32_e32 v216, 16, v254
	v_and_b32_e32 v217, 0xffff0000, v254
	v_lshlrev_b32_e32 v254, 16, v255
	v_and_b32_e32 v255, 0xffff0000, v255
	v_pk_add_f32 v[218:219], v[218:219], v[216:217]
	v_pk_add_f32 v[220:221], v[220:221], v[254:255]
	ds_read_b128 v[252:255], v163 offset:2368
	v_fma_f32 v106, v159, v106, -v98
	v_fma_f32 v107, v159, v107, -v99
	v_fma_f32 v108, v159, v108, -v100
	v_fma_f32 v109, v159, v109, -v101
	v_fma_f32 v218, v159, v218, -v102
	v_fma_f32 v219, v159, v219, -v103
	v_fma_f32 v220, v159, v220, -v104
	v_fma_f32 v221, v159, v221, -v105
	v_cvt_pk_bf16_f32 v106, v106, v107
	v_cvt_pk_bf16_f32 v107, v108, v109
	v_cvt_pk_bf16_f32 v108, v218, v219
	v_cvt_pk_bf16_f32 v109, v220, v221
	s_and_saveexec_b64 s[28:29], s[6:7]
	s_cbranch_execz .Lpu0_5
	global_store_dwordx4 v[192:193], v[98:101], off offset:320
	global_store_dwordx4 v[192:193], v[102:105], off offset:336
.Lpu0_5:
	s_or_b64 exec, exec, s[28:29]
	s_waitcnt vmcnt(8)
	v_mfma_f32_32x32x16_bf16 v[2:17], v[106:109], v[112:115], v[2:17]
	v_mfma_f32_32x32x16_bf16 v[18:33], v[106:109], v[116:119], v[18:33]
	v_mfma_f32_32x32x16_bf16 v[34:49], v[106:109], v[122:125], v[34:49]
	v_mfma_f32_32x32x16_bf16 v[50:65], v[106:109], v[126:129], v[50:65]
	s_waitcnt lgkmcnt(7)
	v_lshlrev_b32_e32 v98, 16, v222
	v_and_b32_e32 v99, 0xffff0000, v222
	v_lshlrev_b32_e32 v100, 16, v223
	v_and_b32_e32 v101, 0xffff0000, v223
	v_lshlrev_b32_e32 v102, 16, v224
	v_and_b32_e32 v103, 0xffff0000, v224
	v_lshlrev_b32_e32 v104, 16, v225
	v_and_b32_e32 v105, 0xffff0000, v225
	ds_read_b128 v[222:225], v163 offset:2096
	s_waitcnt lgkmcnt(7)
	v_lshlrev_b32_e32 v216, 16, v226
	v_and_b32_e32 v217, 0xffff0000, v226
	v_lshlrev_b32_e32 v226, 16, v227
	v_and_b32_e32 v227, 0xffff0000, v227
	v_pk_add_f32 v[106:107], v[98:99], v[216:217]
	v_pk_add_f32 v[108:109], v[100:101], v[226:227]
	v_lshlrev_b32_e32 v216, 16, v228
	v_and_b32_e32 v217, 0xffff0000, v228
	v_lshlrev_b32_e32 v228, 16, v229
	v_and_b32_e32 v229, 0xffff0000, v229
	v_pk_add_f32 v[218:219], v[102:103], v[216:217]
	v_pk_add_f32 v[220:221], v[104:105], v[228:229]
	ds_read_b128 v[226:229], v163 offset:1824
	s_waitcnt lgkmcnt(7)
	v_lshlrev_b32_e32 v216, 16, v230
	v_and_b32_e32 v217, 0xffff0000, v230
	v_lshlrev_b32_e32 v230, 16, v231
	v_and_b32_e32 v231, 0xffff0000, v231
	v_pk_add_f32 v[106:107], v[106:107], v[216:217]
	v_pk_add_f32 v[108:109], v[108:109], v[230:231]
	v_lshlrev_b32_e32 v216, 16, v232
	v_and_b32_e32 v217, 0xffff0000, v232
	v_lshlrev_b32_e32 v232, 16, v233
	v_and_b32_e32 v233, 0xffff0000, v233
	v_pk_add_f32 v[218:219], v[218:219], v[216:217]
	v_pk_add_f32 v[220:221], v[220:221], v[232:233]
	ds_read_b128 v[230:233], v163 offset:1552
	s_waitcnt lgkmcnt(7)
	v_lshlrev_b32_e32 v216, 16, v234
	v_and_b32_e32 v217, 0xffff0000, v234
	v_lshlrev_b32_e32 v234, 16, v235
	v_and_b32_e32 v235, 0xffff0000, v235
	v_pk_add_f32 v[106:107], v[106:107], v[216:217]
	v_pk_add_f32 v[108:109], v[108:109], v[234:235]
	v_lshlrev_b32_e32 v216, 16, v236
	v_and_b32_e32 v217, 0xffff0000, v236
	v_lshlrev_b32_e32 v236, 16, v237
	v_and_b32_e32 v237, 0xffff0000, v237
	v_pk_add_f32 v[218:219], v[218:219], v[216:217]
	v_pk_add_f32 v[220:221], v[220:221], v[236:237]
	ds_read_b128 v[234:237], v163 offset:1280
	s_waitcnt lgkmcnt(7)
	v_lshlrev_b32_e32 v216, 16, v238
	v_and_b32_e32 v217, 0xffff0000, v238
	v_lshlrev_b32_e32 v238, 16, v239
	v_and_b32_e32 v239, 0xffff0000, v239
	v_pk_add_f32 v[106:107], v[106:107], v[216:217]
	v_pk_add_f32 v[108:109], v[108:109], v[238:239]
	v_lshlrev_b32_e32 v216, 16, v240
	v_and_b32_e32 v217, 0xffff0000, v240
	v_lshlrev_b32_e32 v240, 16, v241
	v_and_b32_e32 v241, 0xffff0000, v241
	v_pk_add_f32 v[218:219], v[218:219], v[216:217]
	v_pk_add_f32 v[220:221], v[220:221], v[240:241]
	ds_read_b128 v[238:241], v163 offset:1008
	s_waitcnt lgkmcnt(7)
	v_lshlrev_b32_e32 v216, 16, v242
	v_and_b32_e32 v217, 0xffff0000, v242
	v_lshlrev_b32_e32 v242, 16, v243
	v_and_b32_e32 v243, 0xffff0000, v243
	v_pk_add_f32 v[106:107], v[106:107], v[216:217]
	v_pk_add_f32 v[108:109], v[108:109], v[242:243]
	v_lshlrev_b32_e32 v216, 16, v244
	v_and_b32_e32 v217, 0xffff0000, v244
	v_lshlrev_b32_e32 v244, 16, v245
	v_and_b32_e32 v245, 0xffff0000, v245
	v_pk_add_f32 v[218:219], v[218:219], v[216:217]
	v_pk_add_f32 v[220:221], v[220:221], v[244:245]
	ds_read_b128 v[242:245], v163 offset:736
	s_waitcnt lgkmcnt(7)
	v_lshlrev_b32_e32 v216, 16, v248
	v_and_b32_e32 v217, 0xffff0000, v248
	v_lshlrev_b32_e32 v248, 16, v249
	v_and_b32_e32 v249, 0xffff0000, v249
	v_pk_add_f32 v[106:107], v[106:107], v[216:217]
	v_pk_add_f32 v[108:109], v[108:109], v[248:249]
	v_lshlrev_b32_e32 v216, 16, v250
	v_and_b32_e32 v217, 0xffff0000, v250
	v_lshlrev_b32_e32 v250, 16, v251
	v_and_b32_e32 v251, 0xffff0000, v251
	v_pk_add_f32 v[218:219], v[218:219], v[216:217]
	v_pk_add_f32 v[220:221], v[220:221], v[250:251]
	ds_read_b128 v[248:251], v163 offset:464
	s_waitcnt lgkmcnt(7)
	v_lshlrev_b32_e32 v216, 16, v252
	v_and_b32_e32 v217, 0xffff0000, v252
	v_lshlrev_b32_e32 v252, 16, v253
	v_and_b32_e32 v253, 0xffff0000, v253
	v_pk_add_f32 v[106:107], v[106:107], v[216:217]
	v_pk_add_f32 v[108:109], v[108:109], v[252:253]
	v_lshlrev_b32_e32 v216, 16, v254
	v_and_b32_e32 v217, 0xffff0000, v254
	v_lshlrev_b32_e32 v254, 16, v255
	v_and_b32_e32 v255, 0xffff0000, v255
	v_pk_add_f32 v[218:219], v[218:219], v[216:217]
	v_pk_add_f32 v[220:221], v[220:221], v[254:255]
	ds_read_b128 v[252:255], v163 offset:192
	s_waitcnt lgkmcnt(7)
	v_lshlrev_b32_e32 v216, 16, v222
	v_and_b32_e32 v217, 0xffff0000, v222
	v_lshlrev_b32_e32 v222, 16, v223
	v_and_b32_e32 v223, 0xffff0000, v223
	v_pk_add_f32 v[106:107], v[106:107], v[216:217]
	v_pk_add_f32 v[108:109], v[108:109], v[222:223]
	v_lshlrev_b32_e32 v216, 16, v224
	v_and_b32_e32 v217, 0xffff0000, v224
	v_lshlrev_b32_e32 v224, 16, v225
	v_and_b32_e32 v225, 0xffff0000, v225
	v_pk_add_f32 v[218:219], v[218:219], v[216:217]
	v_pk_add_f32 v[220:221], v[220:221], v[224:225]
	ds_read_b128 v[222:225], v163 offset:4304
	s_waitcnt lgkmcnt(7)
	v_lshlrev_b32_e32 v216, 16, v226
	v_and_b32_e32 v217, 0xffff0000, v226
	v_lshlrev_b32_e32 v226, 16, v227
	v_and_b32_e32 v227, 0xffff0000, v227
	v_pk_add_f32 v[106:107], v[106:107], v[216:217]
	v_pk_add_f32 v[108:109], v[108:109], v[226:227]
	v_lshlrev_b32_e32 v216, 16, v228
	v_and_b32_e32 v217, 0xffff0000, v228
	v_lshlrev_b32_e32 v228, 16, v229
	v_and_b32_e32 v229, 0xffff0000, v229
	v_pk_add_f32 v[218:219], v[218:219], v[216:217]
	v_pk_add_f32 v[220:221], v[220:221], v[228:229]
	ds_read_b128 v[226:229], v163 offset:4032
	s_waitcnt lgkmcnt(7)
	v_lshlrev_b32_e32 v216, 16, v230
	v_and_b32_e32 v217, 0xffff0000, v230
	v_lshlrev_b32_e32 v230, 16, v231
	v_and_b32_e32 v231, 0xffff0000, v231
	v_pk_add_f32 v[106:107], v[106:107], v[216:217]
	v_pk_add_f32 v[108:109], v[108:109], v[230:231]
	v_lshlrev_b32_e32 v216, 16, v232
	v_and_b32_e32 v217, 0xffff0000, v232
	v_lshlrev_b32_e32 v232, 16, v233
	v_and_b32_e32 v233, 0xffff0000, v233
	v_pk_add_f32 v[218:219], v[218:219], v[216:217]
	v_pk_add_f32 v[220:221], v[220:221], v[232:233]
	ds_read_b128 v[230:233], v163 offset:3760
	s_waitcnt lgkmcnt(7)
	v_lshlrev_b32_e32 v216, 16, v234
	v_and_b32_e32 v217, 0xffff0000, v234
	v_lshlrev_b32_e32 v234, 16, v235
	v_and_b32_e32 v235, 0xffff0000, v235
	v_pk_add_f32 v[106:107], v[106:107], v[216:217]
	v_pk_add_f32 v[108:109], v[108:109], v[234:235]
	v_lshlrev_b32_e32 v216, 16, v236
	v_and_b32_e32 v217, 0xffff0000, v236
	v_lshlrev_b32_e32 v236, 16, v237
	v_and_b32_e32 v237, 0xffff0000, v237
	v_pk_add_f32 v[218:219], v[218:219], v[216:217]
	v_pk_add_f32 v[220:221], v[220:221], v[236:237]
	ds_read_b128 v[234:237], v163 offset:3488
	s_waitcnt lgkmcnt(7)
	v_lshlrev_b32_e32 v216, 16, v238
	v_and_b32_e32 v217, 0xffff0000, v238
	v_lshlrev_b32_e32 v238, 16, v239
	v_and_b32_e32 v239, 0xffff0000, v239
	v_pk_add_f32 v[106:107], v[106:107], v[216:217]
	v_pk_add_f32 v[108:109], v[108:109], v[238:239]
	v_lshlrev_b32_e32 v216, 16, v240
	v_and_b32_e32 v217, 0xffff0000, v240
	v_lshlrev_b32_e32 v240, 16, v241
	v_and_b32_e32 v241, 0xffff0000, v241
	v_pk_add_f32 v[218:219], v[218:219], v[216:217]
	v_pk_add_f32 v[220:221], v[220:221], v[240:241]
	ds_read_b128 v[238:241], v163 offset:3216
	s_waitcnt lgkmcnt(7)
	v_lshlrev_b32_e32 v216, 16, v242
	v_and_b32_e32 v217, 0xffff0000, v242
	v_lshlrev_b32_e32 v242, 16, v243
	v_and_b32_e32 v243, 0xffff0000, v243
	v_pk_add_f32 v[106:107], v[106:107], v[216:217]
	v_pk_add_f32 v[108:109], v[108:109], v[242:243]
	v_lshlrev_b32_e32 v216, 16, v244
	v_and_b32_e32 v217, 0xffff0000, v244
	v_lshlrev_b32_e32 v244, 16, v245
	v_and_b32_e32 v245, 0xffff0000, v245
	v_pk_add_f32 v[218:219], v[218:219], v[216:217]
	v_pk_add_f32 v[220:221], v[220:221], v[244:245]
	ds_read_b128 v[242:245], v163 offset:2944
	s_waitcnt lgkmcnt(7)
	v_lshlrev_b32_e32 v216, 16, v248
	v_and_b32_e32 v217, 0xffff0000, v248
	v_lshlrev_b32_e32 v248, 16, v249
	v_and_b32_e32 v249, 0xffff0000, v249
	v_pk_add_f32 v[106:107], v[106:107], v[216:217]
	v_pk_add_f32 v[108:109], v[108:109], v[248:249]
	v_lshlrev_b32_e32 v216, 16, v250
	v_and_b32_e32 v217, 0xffff0000, v250
	v_lshlrev_b32_e32 v250, 16, v251
	v_and_b32_e32 v251, 0xffff0000, v251
	v_pk_add_f32 v[218:219], v[218:219], v[216:217]
	v_pk_add_f32 v[220:221], v[220:221], v[250:251]
	ds_read_b128 v[248:251], v163 offset:2672
	s_waitcnt lgkmcnt(7)
	v_lshlrev_b32_e32 v216, 16, v252
	v_and_b32_e32 v217, 0xffff0000, v252
	v_lshlrev_b32_e32 v252, 16, v253
	v_and_b32_e32 v253, 0xffff0000, v253
	v_pk_add_f32 v[106:107], v[106:107], v[216:217]
	v_pk_add_f32 v[108:109], v[108:109], v[252:253]
	v_lshlrev_b32_e32 v216, 16, v254
	v_and_b32_e32 v217, 0xffff0000, v254
	v_lshlrev_b32_e32 v254, 16, v255
	v_and_b32_e32 v255, 0xffff0000, v255
	v_pk_add_f32 v[218:219], v[218:219], v[216:217]
	v_pk_add_f32 v[220:221], v[220:221], v[254:255]
	ds_read_b128 v[252:255], v163 offset:2400
	v_fma_f32 v106, v159, v106, -v98
	v_fma_f32 v107, v159, v107, -v99
	v_fma_f32 v108, v159, v108, -v100
	v_fma_f32 v109, v159, v109, -v101
	v_fma_f32 v218, v159, v218, -v102
	v_fma_f32 v219, v159, v219, -v103
	v_fma_f32 v220, v159, v220, -v104
	v_fma_f32 v221, v159, v221, -v105
	v_cvt_pk_bf16_f32 v106, v106, v107
	v_cvt_pk_bf16_f32 v107, v108, v109
	v_cvt_pk_bf16_f32 v108, v218, v219
	v_cvt_pk_bf16_f32 v109, v220, v221
	s_and_saveexec_b64 s[28:29], s[6:7]
	s_cbranch_execz .Lpu0_6
	global_store_dwordx4 v[192:193], v[98:101], off offset:384
	global_store_dwordx4 v[192:193], v[102:105], off offset:400
.Lpu0_6:
	s_or_b64 exec, exec, s[28:29]
	s_waitcnt vmcnt(4)
	v_mfma_f32_32x32x16_bf16 v[2:17], v[106:109], v[70:73], v[2:17]
	v_mfma_f32_32x32x16_bf16 v[18:33], v[106:109], v[74:77], v[18:33]
	v_mfma_f32_32x32x16_bf16 v[34:49], v[106:109], v[78:81], v[34:49]
	v_mfma_f32_32x32x16_bf16 v[50:65], v[106:109], v[66:69], v[50:65]
	s_waitcnt lgkmcnt(7)
	v_lshlrev_b32_e32 v98, 16, v222
	v_and_b32_e32 v99, 0xffff0000, v222
	v_lshlrev_b32_e32 v100, 16, v223
	v_and_b32_e32 v101, 0xffff0000, v223
	v_lshlrev_b32_e32 v102, 16, v224
	v_and_b32_e32 v103, 0xffff0000, v224
	v_lshlrev_b32_e32 v104, 16, v225
	v_and_b32_e32 v105, 0xffff0000, v225
	ds_read_b128 v[222:225], v163 offset:2128
	s_waitcnt lgkmcnt(7)
	v_lshlrev_b32_e32 v216, 16, v226
	v_and_b32_e32 v217, 0xffff0000, v226
	v_lshlrev_b32_e32 v226, 16, v227
	v_and_b32_e32 v227, 0xffff0000, v227
	v_pk_add_f32 v[106:107], v[98:99], v[216:217]
	v_pk_add_f32 v[108:109], v[100:101], v[226:227]
	v_lshlrev_b32_e32 v216, 16, v228
	v_and_b32_e32 v217, 0xffff0000, v228
	v_lshlrev_b32_e32 v228, 16, v229
	v_and_b32_e32 v229, 0xffff0000, v229
	v_pk_add_f32 v[218:219], v[102:103], v[216:217]
	v_pk_add_f32 v[220:221], v[104:105], v[228:229]
	ds_read_b128 v[226:229], v163 offset:1856
	s_waitcnt lgkmcnt(7)
	v_lshlrev_b32_e32 v216, 16, v230
	v_and_b32_e32 v217, 0xffff0000, v230
	v_lshlrev_b32_e32 v230, 16, v231
	v_and_b32_e32 v231, 0xffff0000, v231
	v_pk_add_f32 v[106:107], v[106:107], v[216:217]
	v_pk_add_f32 v[108:109], v[108:109], v[230:231]
	v_lshlrev_b32_e32 v216, 16, v232
	v_and_b32_e32 v217, 0xffff0000, v232
	v_lshlrev_b32_e32 v232, 16, v233
	v_and_b32_e32 v233, 0xffff0000, v233
	v_pk_add_f32 v[218:219], v[218:219], v[216:217]
	v_pk_add_f32 v[220:221], v[220:221], v[232:233]
	ds_read_b128 v[230:233], v163 offset:1584
	s_waitcnt lgkmcnt(7)
	v_lshlrev_b32_e32 v216, 16, v234
	v_and_b32_e32 v217, 0xffff0000, v234
	v_lshlrev_b32_e32 v234, 16, v235
	v_and_b32_e32 v235, 0xffff0000, v235
	v_pk_add_f32 v[106:107], v[106:107], v[216:217]
	v_pk_add_f32 v[108:109], v[108:109], v[234:235]
	v_lshlrev_b32_e32 v216, 16, v236
	v_and_b32_e32 v217, 0xffff0000, v236
	v_lshlrev_b32_e32 v236, 16, v237
	v_and_b32_e32 v237, 0xffff0000, v237
	v_pk_add_f32 v[218:219], v[218:219], v[216:217]
	v_pk_add_f32 v[220:221], v[220:221], v[236:237]
	ds_read_b128 v[234:237], v163 offset:1312
	s_waitcnt lgkmcnt(7)
	v_lshlrev_b32_e32 v216, 16, v238
	v_and_b32_e32 v217, 0xffff0000, v238
	v_lshlrev_b32_e32 v238, 16, v239
	v_and_b32_e32 v239, 0xffff0000, v239
	v_pk_add_f32 v[106:107], v[106:107], v[216:217]
	v_pk_add_f32 v[108:109], v[108:109], v[238:239]
	v_lshlrev_b32_e32 v216, 16, v240
	v_and_b32_e32 v217, 0xffff0000, v240
	v_lshlrev_b32_e32 v240, 16, v241
	v_and_b32_e32 v241, 0xffff0000, v241
	v_pk_add_f32 v[218:219], v[218:219], v[216:217]
	v_pk_add_f32 v[220:221], v[220:221], v[240:241]
	ds_read_b128 v[238:241], v163 offset:1040
	s_waitcnt lgkmcnt(7)
	v_lshlrev_b32_e32 v216, 16, v242
	v_and_b32_e32 v217, 0xffff0000, v242
	v_lshlrev_b32_e32 v242, 16, v243
	v_and_b32_e32 v243, 0xffff0000, v243
	v_pk_add_f32 v[106:107], v[106:107], v[216:217]
	v_pk_add_f32 v[108:109], v[108:109], v[242:243]
	v_lshlrev_b32_e32 v216, 16, v244
	v_and_b32_e32 v217, 0xffff0000, v244
	v_lshlrev_b32_e32 v244, 16, v245
	v_and_b32_e32 v245, 0xffff0000, v245
	v_pk_add_f32 v[218:219], v[218:219], v[216:217]
	v_pk_add_f32 v[220:221], v[220:221], v[244:245]
	ds_read_b128 v[242:245], v163 offset:768
	s_waitcnt lgkmcnt(7)
	v_lshlrev_b32_e32 v216, 16, v248
	v_and_b32_e32 v217, 0xffff0000, v248
	v_lshlrev_b32_e32 v248, 16, v249
	v_and_b32_e32 v249, 0xffff0000, v249
	v_pk_add_f32 v[106:107], v[106:107], v[216:217]
	v_pk_add_f32 v[108:109], v[108:109], v[248:249]
	v_lshlrev_b32_e32 v216, 16, v250
	v_and_b32_e32 v217, 0xffff0000, v250
	v_lshlrev_b32_e32 v250, 16, v251
	v_and_b32_e32 v251, 0xffff0000, v251
	v_pk_add_f32 v[218:219], v[218:219], v[216:217]
	v_pk_add_f32 v[220:221], v[220:221], v[250:251]
	ds_read_b128 v[248:251], v163 offset:496
	s_waitcnt lgkmcnt(7)
	v_lshlrev_b32_e32 v216, 16, v252
	v_and_b32_e32 v217, 0xffff0000, v252
	v_lshlrev_b32_e32 v252, 16, v253
	v_and_b32_e32 v253, 0xffff0000, v253
	v_pk_add_f32 v[106:107], v[106:107], v[216:217]
	v_pk_add_f32 v[108:109], v[108:109], v[252:253]
	v_lshlrev_b32_e32 v216, 16, v254
	v_and_b32_e32 v217, 0xffff0000, v254
	v_lshlrev_b32_e32 v254, 16, v255
	v_and_b32_e32 v255, 0xffff0000, v255
	v_pk_add_f32 v[218:219], v[218:219], v[216:217]
	v_pk_add_f32 v[220:221], v[220:221], v[254:255]
	ds_read_b128 v[252:255], v163 offset:224
	s_waitcnt lgkmcnt(7)
	v_lshlrev_b32_e32 v216, 16, v222
	v_and_b32_e32 v217, 0xffff0000, v222
	v_lshlrev_b32_e32 v222, 16, v223
	v_and_b32_e32 v223, 0xffff0000, v223
	v_pk_add_f32 v[106:107], v[106:107], v[216:217]
	v_pk_add_f32 v[108:109], v[108:109], v[222:223]
	v_lshlrev_b32_e32 v216, 16, v224
	v_and_b32_e32 v217, 0xffff0000, v224
	v_lshlrev_b32_e32 v224, 16, v225
	v_and_b32_e32 v225, 0xffff0000, v225
	v_pk_add_f32 v[218:219], v[218:219], v[216:217]
	v_pk_add_f32 v[220:221], v[220:221], v[224:225]
	s_waitcnt lgkmcnt(6)
	v_lshlrev_b32_e32 v216, 16, v226
	v_and_b32_e32 v217, 0xffff0000, v226
	v_lshlrev_b32_e32 v226, 16, v227
	v_and_b32_e32 v227, 0xffff0000, v227
	v_pk_add_f32 v[106:107], v[106:107], v[216:217]
	v_pk_add_f32 v[108:109], v[108:109], v[226:227]
	v_lshlrev_b32_e32 v216, 16, v228
	v_and_b32_e32 v217, 0xffff0000, v228
	v_lshlrev_b32_e32 v228, 16, v229
	v_and_b32_e32 v229, 0xffff0000, v229
	v_pk_add_f32 v[218:219], v[218:219], v[216:217]
	v_pk_add_f32 v[220:221], v[220:221], v[228:229]
	s_waitcnt lgkmcnt(5)
	v_lshlrev_b32_e32 v216, 16, v230
	v_and_b32_e32 v217, 0xffff0000, v230
	v_lshlrev_b32_e32 v230, 16, v231
	v_and_b32_e32 v231, 0xffff0000, v231
	v_pk_add_f32 v[106:107], v[106:107], v[216:217]
	v_pk_add_f32 v[108:109], v[108:109], v[230:231]
	v_lshlrev_b32_e32 v216, 16, v232
	v_and_b32_e32 v217, 0xffff0000, v232
	v_lshlrev_b32_e32 v232, 16, v233
	v_and_b32_e32 v233, 0xffff0000, v233
	v_pk_add_f32 v[218:219], v[218:219], v[216:217]
	v_pk_add_f32 v[220:221], v[220:221], v[232:233]
	s_waitcnt lgkmcnt(4)
	v_lshlrev_b32_e32 v216, 16, v234
	v_and_b32_e32 v217, 0xffff0000, v234
	v_lshlrev_b32_e32 v234, 16, v235
	v_and_b32_e32 v235, 0xffff0000, v235
	v_pk_add_f32 v[106:107], v[106:107], v[216:217]
	v_pk_add_f32 v[108:109], v[108:109], v[234:235]
	v_lshlrev_b32_e32 v216, 16, v236
	v_and_b32_e32 v217, 0xffff0000, v236
	v_lshlrev_b32_e32 v236, 16, v237
	v_and_b32_e32 v237, 0xffff0000, v237
	v_pk_add_f32 v[218:219], v[218:219], v[216:217]
	v_pk_add_f32 v[220:221], v[220:221], v[236:237]
	s_waitcnt lgkmcnt(3)
	v_lshlrev_b32_e32 v216, 16, v238
	v_and_b32_e32 v217, 0xffff0000, v238
	v_lshlrev_b32_e32 v238, 16, v239
	v_and_b32_e32 v239, 0xffff0000, v239
	v_pk_add_f32 v[106:107], v[106:107], v[216:217]
	v_pk_add_f32 v[108:109], v[108:109], v[238:239]
	v_lshlrev_b32_e32 v216, 16, v240
	v_and_b32_e32 v217, 0xffff0000, v240
	v_lshlrev_b32_e32 v240, 16, v241
	v_and_b32_e32 v241, 0xffff0000, v241
	v_pk_add_f32 v[218:219], v[218:219], v[216:217]
	v_pk_add_f32 v[220:221], v[220:221], v[240:241]
	s_waitcnt lgkmcnt(2)
	v_lshlrev_b32_e32 v216, 16, v242
	v_and_b32_e32 v217, 0xffff0000, v242
	v_lshlrev_b32_e32 v242, 16, v243
	v_and_b32_e32 v243, 0xffff0000, v243
	v_pk_add_f32 v[106:107], v[106:107], v[216:217]
	v_pk_add_f32 v[108:109], v[108:109], v[242:243]
	v_lshlrev_b32_e32 v216, 16, v244
	v_and_b32_e32 v217, 0xffff0000, v244
	v_lshlrev_b32_e32 v244, 16, v245
	v_and_b32_e32 v245, 0xffff0000, v245
	v_pk_add_f32 v[218:219], v[218:219], v[216:217]
	v_pk_add_f32 v[220:221], v[220:221], v[244:245]
	s_waitcnt lgkmcnt(1)
	v_lshlrev_b32_e32 v216, 16, v248
	v_and_b32_e32 v217, 0xffff0000, v248
	v_lshlrev_b32_e32 v248, 16, v249
	v_and_b32_e32 v249, 0xffff0000, v249
	v_pk_add_f32 v[106:107], v[106:107], v[216:217]
	v_pk_add_f32 v[108:109], v[108:109], v[248:249]
	v_lshlrev_b32_e32 v216, 16, v250
	v_and_b32_e32 v217, 0xffff0000, v250
	v_lshlrev_b32_e32 v250, 16, v251
	v_and_b32_e32 v251, 0xffff0000, v251
	v_pk_add_f32 v[218:219], v[218:219], v[216:217]
	v_pk_add_f32 v[220:221], v[220:221], v[250:251]
	s_waitcnt lgkmcnt(0)
	v_lshlrev_b32_e32 v216, 16, v252
	v_and_b32_e32 v217, 0xffff0000, v252
	v_lshlrev_b32_e32 v252, 16, v253
	v_and_b32_e32 v253, 0xffff0000, v253
	v_pk_add_f32 v[106:107], v[106:107], v[216:217]
	v_pk_add_f32 v[108:109], v[108:109], v[252:253]
	v_lshlrev_b32_e32 v216, 16, v254
	v_and_b32_e32 v217, 0xffff0000, v254
	v_lshlrev_b32_e32 v254, 16, v255
	v_and_b32_e32 v255, 0xffff0000, v255
	v_pk_add_f32 v[218:219], v[218:219], v[216:217]
	v_pk_add_f32 v[220:221], v[220:221], v[254:255]
	v_fma_f32 v106, v159, v106, -v98
	v_fma_f32 v107, v159, v107, -v99
	v_fma_f32 v108, v159, v108, -v100
	v_fma_f32 v109, v159, v109, -v101
	v_fma_f32 v218, v159, v218, -v102
	v_fma_f32 v219, v159, v219, -v103
	v_fma_f32 v220, v159, v220, -v104
	v_fma_f32 v221, v159, v221, -v105
	v_cvt_pk_bf16_f32 v106, v106, v107
	v_cvt_pk_bf16_f32 v107, v108, v109
	v_cvt_pk_bf16_f32 v108, v218, v219
	v_cvt_pk_bf16_f32 v109, v220, v221
	s_and_saveexec_b64 s[28:29], s[6:7]
	s_cbranch_execz .Lpu0_7
	global_store_dwordx4 v[192:193], v[98:101], off offset:448
	global_store_dwordx4 v[192:193], v[102:105], off offset:464

.LBB0_355:
	s_or_b64 exec, exec, s[6:7]
	s_waitcnt lgkmcnt(0)
	global_load_dwordx4 v[82:85], v[112:113], off offset:512
	global_load_dwordx4 v[86:89], v[114:115], off offset:512
	global_load_dwordx4 v[90:93], v[116:117], off offset:512
	global_load_dwordx4 v[94:97], v[118:119], off offset:512
	global_load_dwordx4 v[222:225], v[112:113], off offset:1024
	global_load_dwordx4 v[226:229], v[114:115], off offset:1024
	global_load_dwordx4 v[230:233], v[116:117], off offset:1024
	global_load_dwordx4 v[234:237], v[118:119], off offset:1024
	v_or_b32_e32 v2, s28, v1
	v_min_u32_e32 v3, 7, v2
	v_add_u32_e32 v3, 1, v3
	v_cvt_f32_ubyte0_e32 v3, v3
	v_div_scale_f32 v4, s[6:7], v3, v3, 1.0
	v_rcp_f32_e32 v5, v4
	s_ashr_i32 s8, s30, 6
	s_mul_i32 s10, s8, 15
	v_cmp_lt_u32_e64 s[6:7], s41, v2
	v_fma_f32 v6, -v4, v5, 1.0
	v_fmac_f32_e32 v5, v6, v5
	v_div_scale_f32 v6, vcc, 1.0, v3, 1.0
	v_mul_f32_e32 v7, v6, v5
	v_fma_f32 v8, -v4, v7, v6
	v_fmac_f32_e32 v7, v8, v5
	v_fma_f32 v4, -v4, v7, v6
	v_div_fmas_f32 v4, v4, v5, v7
	v_div_fixup_f32 v159, v4, v3, 1.0
	s_ashr_i32 s11, s10, 31
	v_add_u32_e32 v2, 0xfffff80f, v2
	v_mov_b32_e32 v3, v155
	v_lshl_add_u64 v[2:3], v[2:3], 0, s[10:11]
	v_lshlrev_b64 v[2:3], 11, v[2:3]
	v_lshl_add_u64 v[2:3], s[70:71], 0, v[2:3]
	v_mov_b32_e32 v163, v155
	v_lshl_add_u64 v[2:3], v[2:3], 0, v[162:163]
	v_lshl_add_u64 v[192:193], v[2:3], 0, s[20:21]
	v_mov_b32_e32 v2, 0
	s_mov_b32 s49, 0
	s_mov_b64 s[10:11], 0
	v_mov_b32_e32 v3, v2
	v_mov_b32_e32 v4, v2
	v_mov_b32_e32 v5, v2
	v_mov_b32_e32 v6, v2
	v_mov_b32_e32 v7, v2
	v_mov_b32_e32 v8, v2
	v_mov_b32_e32 v9, v2
	v_mov_b32_e32 v10, v2
	v_mov_b32_e32 v11, v2
	v_mov_b32_e32 v12, v2
	v_mov_b32_e32 v13, v2
	v_mov_b32_e32 v14, v2
	v_mov_b32_e32 v15, v2
	v_mov_b32_e32 v16, v2
	v_mov_b32_e32 v17, v2
	v_mov_b32_e32 v18, v2
	v_mov_b32_e32 v19, v2
	v_mov_b32_e32 v20, v2
	v_mov_b32_e32 v21, v2
	v_mov_b32_e32 v22, v2
	v_mov_b32_e32 v23, v2
	v_mov_b32_e32 v24, v2
	v_mov_b32_e32 v25, v2
	v_mov_b32_e32 v26, v2
	v_mov_b32_e32 v27, v2
	v_mov_b32_e32 v28, v2
	v_mov_b32_e32 v29, v2
	v_mov_b32_e32 v30, v2
	v_mov_b32_e32 v31, v2
	v_mov_b32_e32 v32, v2
	v_mov_b32_e32 v33, v2
	v_mov_b32_e32 v34, v2
	v_mov_b32_e32 v35, v2
	v_mov_b32_e32 v36, v2
	v_mov_b32_e32 v37, v2
	v_mov_b32_e32 v38, v2
	v_mov_b32_e32 v39, v2
	v_mov_b32_e32 v40, v2
	v_mov_b32_e32 v41, v2
	v_mov_b32_e32 v42, v2
	v_mov_b32_e32 v43, v2
	v_mov_b32_e32 v44, v2
	v_mov_b32_e32 v45, v2
	v_mov_b32_e32 v46, v2
	v_mov_b32_e32 v47, v2
	v_mov_b32_e32 v48, v2
	v_mov_b32_e32 v49, v2
	v_mov_b32_e32 v50, v2
	v_mov_b32_e32 v51, v2
	v_mov_b32_e32 v52, v2
	v_mov_b32_e32 v53, v2
	v_mov_b32_e32 v54, v2
	v_mov_b32_e32 v55, v2
	v_mov_b32_e32 v56, v2
	v_mov_b32_e32 v57, v2
	v_mov_b32_e32 v58, v2
	v_mov_b32_e32 v59, v2
	v_mov_b32_e32 v60, v2
	v_mov_b32_e32 v61, v2
	v_mov_b32_e32 v62, v2
	v_mov_b32_e32 v63, v2
	v_mov_b32_e32 v64, v2
	v_mov_b32_e32 v65, v2
	v_lshl_add_u32 v163, v197, 1, v214
	ds_read_b128 v[238:241], v163 offset:4080
	ds_read_b128 v[242:245], v163 offset:3808
	ds_read_b128 v[248:251], v163 offset:3536
	ds_read_b128 v[252:255], v163 offset:3264
	s_waitcnt lgkmcnt(3)
	v_lshlrev_b32_e32 v98, 16, v238
	v_and_b32_e32 v99, 0xffff0000, v238
	v_lshlrev_b32_e32 v100, 16, v239
	v_and_b32_e32 v101, 0xffff0000, v239
	v_lshlrev_b32_e32 v102, 16, v240
	v_and_b32_e32 v103, 0xffff0000, v240
	v_lshlrev_b32_e32 v104, 16, v241
	v_and_b32_e32 v105, 0xffff0000, v241
	ds_read_b128 v[238:241], v163 offset:2992
	s_waitcnt lgkmcnt(3)
	v_lshlrev_b32_e32 v216, 16, v242
	v_and_b32_e32 v217, 0xffff0000, v242
	v_lshlrev_b32_e32 v242, 16, v243
	v_and_b32_e32 v243, 0xffff0000, v243
	v_pk_add_f32 v[106:107], v[98:99], v[216:217]
	v_pk_add_f32 v[108:109], v[100:101], v[242:243]
	v_lshlrev_b32_e32 v216, 16, v244
	v_and_b32_e32 v217, 0xffff0000, v244
	v_lshlrev_b32_e32 v244, 16, v245
	v_and_b32_e32 v245, 0xffff0000, v245
	v_pk_add_f32 v[218:219], v[102:103], v[216:217]
	v_pk_add_f32 v[220:221], v[104:105], v[244:245]
	ds_read_b128 v[242:245], v163 offset:2720
	s_waitcnt lgkmcnt(3)
	v_lshlrev_b32_e32 v216, 16, v248
	v_and_b32_e32 v217, 0xffff0000, v248
	v_lshlrev_b32_e32 v248, 16, v249
	v_and_b32_e32 v249, 0xffff0000, v249
	v_pk_add_f32 v[106:107], v[106:107], v[216:217]
	v_pk_add_f32 v[108:109], v[108:109], v[248:249]
	v_lshlrev_b32_e32 v216, 16, v250
	v_and_b32_e32 v217, 0xffff0000, v250
	v_lshlrev_b32_e32 v250, 16, v251
	v_and_b32_e32 v251, 0xffff0000, v251
	v_pk_add_f32 v[218:219], v[218:219], v[216:217]
	v_pk_add_f32 v[220:221], v[220:221], v[250:251]
	ds_read_b128 v[248:251], v163 offset:2448
	s_waitcnt lgkmcnt(3)
	v_lshlrev_b32_e32 v216, 16, v252
	v_and_b32_e32 v217, 0xffff0000, v252
	v_lshlrev_b32_e32 v252, 16, v253
	v_and_b32_e32 v253, 0xffff0000, v253
	v_pk_add_f32 v[106:107], v[106:107], v[216:217]
	v_pk_add_f32 v[108:109], v[108:109], v[252:253]
	v_lshlrev_b32_e32 v216, 16, v254
	v_and_b32_e32 v217, 0xffff0000, v254
	v_lshlrev_b32_e32 v254, 16, v255
	v_and_b32_e32 v255, 0xffff0000, v255
	v_pk_add_f32 v[218:219], v[218:219], v[216:217]
	v_pk_add_f32 v[220:221], v[220:221], v[254:255]
	ds_read_b128 v[252:255], v163 offset:2176
	s_waitcnt lgkmcnt(3)
	v_lshlrev_b32_e32 v216, 16, v238
	v_and_b32_e32 v217, 0xffff0000, v238
	v_lshlrev_b32_e32 v238, 16, v239
	v_and_b32_e32 v239, 0xffff0000, v239
	v_pk_add_f32 v[106:107], v[106:107], v[216:217]
	v_pk_add_f32 v[108:109], v[108:109], v[238:239]
	v_lshlrev_b32_e32 v216, 16, v240
	v_and_b32_e32 v217, 0xffff0000, v240
	v_lshlrev_b32_e32 v240, 16, v241
	v_and_b32_e32 v241, 0xffff0000, v241
	v_pk_add_f32 v[218:219], v[218:219], v[216:217]
	v_pk_add_f32 v[220:221], v[220:221], v[240:241]
	ds_read_b128 v[238:241], v163 offset:4112
	s_waitcnt lgkmcnt(3)
	v_lshlrev_b32_e32 v216, 16, v242
	v_and_b32_e32 v217, 0xffff0000, v242
	v_lshlrev_b32_e32 v242, 16, v243
	v_and_b32_e32 v243, 0xffff0000, v243
	v_pk_add_f32 v[106:107], v[106:107], v[216:217]
	v_pk_add_f32 v[108:109], v[108:109], v[242:243]
	v_lshlrev_b32_e32 v216, 16, v244
	v_and_b32_e32 v217, 0xffff0000, v244
	v_lshlrev_b32_e32 v244, 16, v245
	v_and_b32_e32 v245, 0xffff0000, v245
	v_pk_add_f32 v[218:219], v[218:219], v[216:217]
	v_pk_add_f32 v[220:221], v[220:221], v[244:245]
	ds_read_b128 v[242:245], v163 offset:3840
	s_waitcnt lgkmcnt(3)
	v_lshlrev_b32_e32 v216, 16, v248
	v_and_b32_e32 v217, 0xffff0000, v248
	v_lshlrev_b32_e32 v248, 16, v249
	v_and_b32_e32 v249, 0xffff0000, v249
	v_pk_add_f32 v[106:107], v[106:107], v[216:217]
	v_pk_add_f32 v[108:109], v[108:109], v[248:249]
	v_lshlrev_b32_e32 v216, 16, v250
	v_and_b32_e32 v217, 0xffff0000, v250
	v_lshlrev_b32_e32 v250, 16, v251
	v_and_b32_e32 v251, 0xffff0000, v251
	v_pk_add_f32 v[218:219], v[218:219], v[216:217]
	v_pk_add_f32 v[220:221], v[220:221], v[250:251]
	ds_read_b128 v[248:251], v163 offset:3568
	s_waitcnt lgkmcnt(3)
	v_lshlrev_b32_e32 v216, 16, v252
	v_and_b32_e32 v217, 0xffff0000, v252
	v_lshlrev_b32_e32 v252, 16, v253
	v_and_b32_e32 v253, 0xffff0000, v253
	v_pk_add_f32 v[106:107], v[106:107], v[216:217]
	v_pk_add_f32 v[108:109], v[108:109], v[252:253]
	v_lshlrev_b32_e32 v216, 16, v254
	v_and_b32_e32 v217, 0xffff0000, v254
	v_lshlrev_b32_e32 v254, 16, v255
	v_and_b32_e32 v255, 0xffff0000, v255
	v_pk_add_f32 v[218:219], v[218:219], v[216:217]
	v_pk_add_f32 v[220:221], v[220:221], v[254:255]
	ds_read_b128 v[252:255], v163 offset:3296
	v_fma_f32 v106, v159, v106, -v98
	v_fma_f32 v107, v159, v107, -v99
	v_fma_f32 v108, v159, v108, -v100
	v_fma_f32 v109, v159, v109, -v101
	v_fma_f32 v218, v159, v218, -v102
	v_fma_f32 v219, v159, v219, -v103
	v_fma_f32 v220, v159, v220, -v104
	v_fma_f32 v221, v159, v221, -v105
	v_cvt_pk_bf16_f32 v106, v106, v107
	v_cvt_pk_bf16_f32 v107, v108, v109
	v_cvt_pk_bf16_f32 v108, v218, v219
	v_cvt_pk_bf16_f32 v109, v220, v221
	s_and_saveexec_b64 s[28:29], s[6:7]
	s_cbranch_execz .Lpu1_0
	global_store_dwordx4 v[192:193], v[98:101], off offset:0
	global_store_dwordx4 v[192:193], v[102:105], off offset:16
.Lpu1_0:
	s_or_b64 exec, exec, s[28:29]
	s_waitcnt vmcnt(8)
	v_mfma_f32_32x32x16_bf16 v[2:17], v[106:109], v[70:73], v[2:17]
	v_mfma_f32_32x32x16_bf16 v[18:33], v[106:109], v[74:77], v[18:33]
	v_mfma_f32_32x32x16_bf16 v[34:49], v[106:109], v[78:81], v[34:49]
	v_mfma_f32_32x32x16_bf16 v[50:65], v[106:109], v[66:69], v[50:65]
	global_load_dwordx4 v[70:73], v[112:113], off offset:1536
	global_load_dwordx4 v[74:77], v[114:115], off offset:1536
	global_load_dwordx4 v[78:81], v[116:117], off offset:1536
	global_load_dwordx4 v[66:69], v[118:119], off offset:1536
	s_waitcnt lgkmcnt(3)
	v_lshlrev_b32_e32 v98, 16, v238
	v_and_b32_e32 v99, 0xffff0000, v238
	v_lshlrev_b32_e32 v100, 16, v239
	v_and_b32_e32 v101, 0xffff0000, v239
	v_lshlrev_b32_e32 v102, 16, v240
	v_and_b32_e32 v103, 0xffff0000, v240
	v_lshlrev_b32_e32 v104, 16, v241
	v_and_b32_e32 v105, 0xffff0000, v241
	ds_read_b128 v[238:241], v163 offset:3024
	s_waitcnt lgkmcnt(3)
	v_lshlrev_b32_e32 v216, 16, v242
	v_and_b32_e32 v217, 0xffff0000, v242
	v_lshlrev_b32_e32 v242, 16, v243
	v_and_b32_e32 v243, 0xffff0000, v243
	v_pk_add_f32 v[106:107], v[98:99], v[216:217]
	v_pk_add_f32 v[108:109], v[100:101], v[242:243]
	v_lshlrev_b32_e32 v216, 16, v244
	v_and_b32_e32 v217, 0xffff0000, v244
	v_lshlrev_b32_e32 v244, 16, v245
	v_and_b32_e32 v245, 0xffff0000, v245
	v_pk_add_f32 v[218:219], v[102:103], v[216:217]
	v_pk_add_f32 v[220:221], v[104:105], v[244:245]
	ds_read_b128 v[242:245], v163 offset:2752
	s_waitcnt lgkmcnt(3)
	v_lshlrev_b32_e32 v216, 16, v248
	v_and_b32_e32 v217, 0xffff0000, v248
	v_lshlrev_b32_e32 v248, 16, v249
	v_and_b32_e32 v249, 0xffff0000, v249
	v_pk_add_f32 v[106:107], v[106:107], v[216:217]
	v_pk_add_f32 v[108:109], v[108:109], v[248:249]
	v_lshlrev_b32_e32 v216, 16, v250
	v_and_b32_e32 v217, 0xffff0000, v250
	v_lshlrev_b32_e32 v250, 16, v251
	v_and_b32_e32 v251, 0xffff0000, v251
	v_pk_add_f32 v[218:219], v[218:219], v[216:217]
	v_pk_add_f32 v[220:221], v[220:221], v[250:251]
	ds_read_b128 v[248:251], v163 offset:2480
	s_waitcnt lgkmcnt(3)
	v_lshlrev_b32_e32 v216, 16, v252
	v_and_b32_e32 v217, 0xffff0000, v252
	v_lshlrev_b32_e32 v252, 16, v253
	v_and_b32_e32 v253, 0xffff0000, v253
	v_pk_add_f32 v[106:107], v[106:107], v[216:217]
	v_pk_add_f32 v[108:109], v[108:109], v[252:253]
	v_lshlrev_b32_e32 v216, 16, v254
	v_and_b32_e32 v217, 0xffff0000, v254
	v_lshlrev_b32_e32 v254, 16, v255
	v_and_b32_e32 v255, 0xffff0000, v255
	v_pk_add_f32 v[218:219], v[218:219], v[216:217]
	v_pk_add_f32 v[220:221], v[220:221], v[254:255]
	ds_read_b128 v[252:255], v163 offset:2208
	s_waitcnt lgkmcnt(3)
	v_lshlrev_b32_e32 v216, 16, v238
	v_and_b32_e32 v217, 0xffff0000, v238
	v_lshlrev_b32_e32 v238, 16, v239
	v_and_b32_e32 v239, 0xffff0000, v239
	v_pk_add_f32 v[106:107], v[106:107], v[216:217]
	v_pk_add_f32 v[108:109], v[108:109], v[238:239]
	v_lshlrev_b32_e32 v216, 16, v240
	v_and_b32_e32 v217, 0xffff0000, v240
	v_lshlrev_b32_e32 v240, 16, v241
	v_and_b32_e32 v241, 0xffff0000, v241
	v_pk_add_f32 v[218:219], v[218:219], v[216:217]
	v_pk_add_f32 v[220:221], v[220:221], v[240:241]
	ds_read_b128 v[238:241], v163 offset:4144
	s_waitcnt lgkmcnt(3)
	v_lshlrev_b32_e32 v216, 16, v242
	v_and_b32_e32 v217, 0xffff0000, v242
	v_lshlrev_b32_e32 v242, 16, v243
	v_and_b32_e32 v243, 0xffff0000, v243
	v_pk_add_f32 v[106:107], v[106:107], v[216:217]
	v_pk_add_f32 v[108:109], v[108:109], v[242:243]
	v_lshlrev_b32_e32 v216, 16, v244
	v_and_b32_e32 v217, 0xffff0000, v244
	v_lshlrev_b32_e32 v244, 16, v245
	v_and_b32_e32 v245, 0xffff0000, v245
	v_pk_add_f32 v[218:219], v[218:219], v[216:217]
	v_pk_add_f32 v[220:221], v[220:221], v[244:245]
	ds_read_b128 v[242:245], v163 offset:3872
	s_waitcnt lgkmcnt(3)
	v_lshlrev_b32_e32 v216, 16, v248
	v_and_b32_e32 v217, 0xffff0000, v248
	v_lshlrev_b32_e32 v248, 16, v249
	v_and_b32_e32 v249, 0xffff0000, v249
	v_pk_add_f32 v[106:107], v[106:107], v[216:217]
	v_pk_add_f32 v[108:109], v[108:109], v[248:249]
	v_lshlrev_b32_e32 v216, 16, v250
	v_and_b32_e32 v217, 0xffff0000, v250
	v_lshlrev_b32_e32 v250, 16, v251
	v_and_b32_e32 v251, 0xffff0000, v251
	v_pk_add_f32 v[218:219], v[218:219], v[216:217]
	v_pk_add_f32 v[220:221], v[220:221], v[250:251]
	ds_read_b128 v[248:251], v163 offset:3600
	s_waitcnt lgkmcnt(3)
	v_lshlrev_b32_e32 v216, 16, v252
	v_and_b32_e32 v217, 0xffff0000, v252
	v_lshlrev_b32_e32 v252, 16, v253
	v_and_b32_e32 v253, 0xffff0000, v253
	v_pk_add_f32 v[106:107], v[106:107], v[216:217]
	v_pk_add_f32 v[108:109], v[108:109], v[252:253]
	v_lshlrev_b32_e32 v216, 16, v254
	v_and_b32_e32 v217, 0xffff0000, v254
	v_lshlrev_b32_e32 v254, 16, v255
	v_and_b32_e32 v255, 0xffff0000, v255
	v_pk_add_f32 v[218:219], v[218:219], v[216:217]
	v_pk_add_f32 v[220:221], v[220:221], v[254:255]
	ds_read_b128 v[252:255], v163 offset:3328
	v_fma_f32 v106, v159, v106, -v98
	v_fma_f32 v107, v159, v107, -v99
	v_fma_f32 v108, v159, v108, -v100
	v_fma_f32 v109, v159, v109, -v101
	v_fma_f32 v218, v159, v218, -v102
	v_fma_f32 v219, v159, v219, -v103
	v_fma_f32 v220, v159, v220, -v104
	v_fma_f32 v221, v159, v221, -v105
	v_cvt_pk_bf16_f32 v106, v106, v107
	v_cvt_pk_bf16_f32 v107, v108, v109
	v_cvt_pk_bf16_f32 v108, v218, v219
	v_cvt_pk_bf16_f32 v109, v220, v221
	s_and_saveexec_b64 s[28:29], s[6:7]
	s_cbranch_execz .Lpu1_1
	global_store_dwordx4 v[192:193], v[98:101], off offset:64
	global_store_dwordx4 v[192:193], v[102:105], off offset:80
.Lpu1_1:
	s_or_b64 exec, exec, s[28:29]
	s_waitcnt vmcnt(8)
	v_mfma_f32_32x32x16_bf16 v[2:17], v[106:109], v[82:85], v[2:17]
	v_mfma_f32_32x32x16_bf16 v[18:33], v[106:109], v[86:89], v[18:33]
	v_mfma_f32_32x32x16_bf16 v[34:49], v[106:109], v[90:93], v[34:49]
	v_mfma_f32_32x32x16_bf16 v[50:65], v[106:109], v[94:97], v[50:65]
	global_load_dwordx4 v[82:85], v[112:113], off offset:2048
	global_load_dwordx4 v[86:89], v[114:115], off offset:2048
	global_load_dwordx4 v[90:93], v[116:117], off offset:2048
	global_load_dwordx4 v[94:97], v[118:119], off offset:2048
	s_waitcnt lgkmcnt(3)
	v_lshlrev_b32_e32 v98, 16, v238
	v_and_b32_e32 v99, 0xffff0000, v238
	v_lshlrev_b32_e32 v100, 16, v239
	v_and_b32_e32 v101, 0xffff0000, v239
	v_lshlrev_b32_e32 v102, 16, v240
	v_and_b32_e32 v103, 0xffff0000, v240
	v_lshlrev_b32_e32 v104, 16, v241
	v_and_b32_e32 v105, 0xffff0000, v241
	ds_read_b128 v[238:241], v163 offset:3056
	s_waitcnt lgkmcnt(3)
	v_lshlrev_b32_e32 v216, 16, v242
	v_and_b32_e32 v217, 0xffff0000, v242
	v_lshlrev_b32_e32 v242, 16, v243
	v_and_b32_e32 v243, 0xffff0000, v243
	v_pk_add_f32 v[106:107], v[98:99], v[216:217]
	v_pk_add_f32 v[108:109], v[100:101], v[242:243]
	v_lshlrev_b32_e32 v216, 16, v244
	v_and_b32_e32 v217, 0xffff0000, v244
	v_lshlrev_b32_e32 v244, 16, v245
	v_and_b32_e32 v245, 0xffff0000, v245
	v_pk_add_f32 v[218:219], v[102:103], v[216:217]
	v_pk_add_f32 v[220:221], v[104:105], v[244:245]
	ds_read_b128 v[242:245], v163 offset:2784
	s_waitcnt lgkmcnt(3)
	v_lshlrev_b32_e32 v216, 16, v248
	v_and_b32_e32 v217, 0xffff0000, v248
	v_lshlrev_b32_e32 v248, 16, v249
	v_and_b32_e32 v249, 0xffff0000, v249
	v_pk_add_f32 v[106:107], v[106:107], v[216:217]
	v_pk_add_f32 v[108:109], v[108:109], v[248:249]
	v_lshlrev_b32_e32 v216, 16, v250
	v_and_b32_e32 v217, 0xffff0000, v250
	v_lshlrev_b32_e32 v250, 16, v251
	v_and_b32_e32 v251, 0xffff0000, v251
	v_pk_add_f32 v[218:219], v[218:219], v[216:217]
	v_pk_add_f32 v[220:221], v[220:221], v[250:251]
	ds_read_b128 v[248:251], v163 offset:2512
	s_waitcnt lgkmcnt(3)
	v_lshlrev_b32_e32 v216, 16, v252
	v_and_b32_e32 v217, 0xffff0000, v252
	v_lshlrev_b32_e32 v252, 16, v253
	v_and_b32_e32 v253, 0xffff0000, v253
	v_pk_add_f32 v[106:107], v[106:107], v[216:217]
	v_pk_add_f32 v[108:109], v[108:109], v[252:253]
	v_lshlrev_b32_e32 v216, 16, v254
	v_and_b32_e32 v217, 0xffff0000, v254
	v_lshlrev_b32_e32 v254, 16, v255
	v_and_b32_e32 v255, 0xffff0000, v255
	v_pk_add_f32 v[218:219], v[218:219], v[216:217]
	v_pk_add_f32 v[220:221], v[220:221], v[254:255]
	ds_read_b128 v[252:255], v163 offset:2240
	s_waitcnt lgkmcnt(3)
	v_lshlrev_b32_e32 v216, 16, v238
	v_and_b32_e32 v217, 0xffff0000, v238
	v_lshlrev_b32_e32 v238, 16, v239
	v_and_b32_e32 v239, 0xffff0000, v239
	v_pk_add_f32 v[106:107], v[106:107], v[216:217]
	v_pk_add_f32 v[108:109], v[108:109], v[238:239]
	v_lshlrev_b32_e32 v216, 16, v240
	v_and_b32_e32 v217, 0xffff0000, v240
	v_lshlrev_b32_e32 v240, 16, v241
	v_and_b32_e32 v241, 0xffff0000, v241
	v_pk_add_f32 v[218:219], v[218:219], v[216:217]
	v_pk_add_f32 v[220:221], v[220:221], v[240:241]
	ds_read_b128 v[238:241], v163 offset:4176
	s_waitcnt lgkmcnt(3)
	v_lshlrev_b32_e32 v216, 16, v242
	v_and_b32_e32 v217, 0xffff0000, v242
	v_lshlrev_b32_e32 v242, 16, v243
	v_and_b32_e32 v243, 0xffff0000, v243
	v_pk_add_f32 v[106:107], v[106:107], v[216:217]
	v_pk_add_f32 v[108:109], v[108:109], v[242:243]
	v_lshlrev_b32_e32 v216, 16, v244
	v_and_b32_e32 v217, 0xffff0000, v244
	v_lshlrev_b32_e32 v244, 16, v245
	v_and_b32_e32 v245, 0xffff0000, v245
	v_pk_add_f32 v[218:219], v[218:219], v[216:217]
	v_pk_add_f32 v[220:221], v[220:221], v[244:245]
	ds_read_b128 v[242:245], v163 offset:3904
	s_waitcnt lgkmcnt(3)
	v_lshlrev_b32_e32 v216, 16, v248
	v_and_b32_e32 v217, 0xffff0000, v248
	v_lshlrev_b32_e32 v248, 16, v249
	v_and_b32_e32 v249, 0xffff0000, v249
	v_pk_add_f32 v[106:107], v[106:107], v[216:217]
	v_pk_add_f32 v[108:109], v[108:109], v[248:249]
	v_lshlrev_b32_e32 v216, 16, v250
	v_and_b32_e32 v217, 0xffff0000, v250
	v_lshlrev_b32_e32 v250, 16, v251
	v_and_b32_e32 v251, 0xffff0000, v251
	v_pk_add_f32 v[218:219], v[218:219], v[216:217]
	v_pk_add_f32 v[220:221], v[220:221], v[250:251]
	ds_read_b128 v[248:251], v163 offset:3632
	s_waitcnt lgkmcnt(3)
	v_lshlrev_b32_e32 v216, 16, v252
	v_and_b32_e32 v217, 0xffff0000, v252
	v_lshlrev_b32_e32 v252, 16, v253
	v_and_b32_e32 v253, 0xffff0000, v253
	v_pk_add_f32 v[106:107], v[106:107], v[216:217]
	v_pk_add_f32 v[108:109], v[108:109], v[252:253]
	v_lshlrev_b32_e32 v216, 16, v254
	v_and_b32_e32 v217, 0xffff0000, v254
	v_lshlrev_b32_e32 v254, 16, v255
	v_and_b32_e32 v255, 0xffff0000, v255
	v_pk_add_f32 v[218:219], v[218:219], v[216:217]
	v_pk_add_f32 v[220:221], v[220:221], v[254:255]
	ds_read_b128 v[252:255], v163 offset:3360
	v_fma_f32 v106, v159, v106, -v98
	v_fma_f32 v107, v159, v107, -v99
	v_fma_f32 v108, v159, v108, -v100
	v_fma_f32 v109, v159, v109, -v101
	v_fma_f32 v218, v159, v218, -v102
	v_fma_f32 v219, v159, v219, -v103
	v_fma_f32 v220, v159, v220, -v104
	v_fma_f32 v221, v159, v221, -v105
	v_cvt_pk_bf16_f32 v106, v106, v107
	v_cvt_pk_bf16_f32 v107, v108, v109
	v_cvt_pk_bf16_f32 v108, v218, v219
	v_cvt_pk_bf16_f32 v109, v220, v221
	s_and_saveexec_b64 s[28:29], s[6:7]
	s_cbranch_execz .Lpu1_2
	global_store_dwordx4 v[192:193], v[98:101], off offset:128
	global_store_dwordx4 v[192:193], v[102:105], off offset:144
.Lpu1_2:
	s_or_b64 exec, exec, s[28:29]
	s_waitcnt vmcnt(8)
	v_mfma_f32_32x32x16_bf16 v[2:17], v[106:109], v[222:225], v[2:17]
	v_mfma_f32_32x32x16_bf16 v[18:33], v[106:109], v[226:229], v[18:33]
	v_mfma_f32_32x32x16_bf16 v[34:49], v[106:109], v[230:233], v[34:49]
	v_mfma_f32_32x32x16_bf16 v[50:65], v[106:109], v[234:237], v[50:65]
	global_load_dwordx4 v[222:225], v[112:113], off offset:2560
	global_load_dwordx4 v[226:229], v[114:115], off offset:2560
	global_load_dwordx4 v[230:233], v[116:117], off offset:2560
	global_load_dwordx4 v[234:237], v[118:119], off offset:2560
	s_waitcnt lgkmcnt(3)
	v_lshlrev_b32_e32 v98, 16, v238
	v_and_b32_e32 v99, 0xffff0000, v238
	v_lshlrev_b32_e32 v100, 16, v239
	v_and_b32_e32 v101, 0xffff0000, v239
	v_lshlrev_b32_e32 v102, 16, v240
	v_and_b32_e32 v103, 0xffff0000, v240
	v_lshlrev_b32_e32 v104, 16, v241
	v_and_b32_e32 v105, 0xffff0000, v241
	ds_read_b128 v[238:241], v163 offset:3088
	s_waitcnt lgkmcnt(3)
	v_lshlrev_b32_e32 v216, 16, v242
	v_and_b32_e32 v217, 0xffff0000, v242
	v_lshlrev_b32_e32 v242, 16, v243
	v_and_b32_e32 v243, 0xffff0000, v243
	v_pk_add_f32 v[106:107], v[98:99], v[216:217]
	v_pk_add_f32 v[108:109], v[100:101], v[242:243]
	v_lshlrev_b32_e32 v216, 16, v244
	v_and_b32_e32 v217, 0xffff0000, v244
	v_lshlrev_b32_e32 v244, 16, v245
	v_and_b32_e32 v245, 0xffff0000, v245
	v_pk_add_f32 v[218:219], v[102:103], v[216:217]
	v_pk_add_f32 v[220:221], v[104:105], v[244:245]
	ds_read_b128 v[242:245], v163 offset:2816
	s_waitcnt lgkmcnt(3)
	v_lshlrev_b32_e32 v216, 16, v248
	v_and_b32_e32 v217, 0xffff0000, v248
	v_lshlrev_b32_e32 v248, 16, v249
	v_and_b32_e32 v249, 0xffff0000, v249
	v_pk_add_f32 v[106:107], v[106:107], v[216:217]
	v_pk_add_f32 v[108:109], v[108:109], v[248:249]
	v_lshlrev_b32_e32 v216, 16, v250
	v_and_b32_e32 v217, 0xffff0000, v250
	v_lshlrev_b32_e32 v250, 16, v251
	v_and_b32_e32 v251, 0xffff0000, v251
	v_pk_add_f32 v[218:219], v[218:219], v[216:217]
	v_pk_add_f32 v[220:221], v[220:221], v[250:251]
	ds_read_b128 v[248:251], v163 offset:2544
	s_waitcnt lgkmcnt(3)
	v_lshlrev_b32_e32 v216, 16, v252
	v_and_b32_e32 v217, 0xffff0000, v252
	v_lshlrev_b32_e32 v252, 16, v253
	v_and_b32_e32 v253, 0xffff0000, v253
	v_pk_add_f32 v[106:107], v[106:107], v[216:217]
	v_pk_add_f32 v[108:109], v[108:109], v[252:253]
	v_lshlrev_b32_e32 v216, 16, v254
	v_and_b32_e32 v217, 0xffff0000, v254
	v_lshlrev_b32_e32 v254, 16, v255
	v_and_b32_e32 v255, 0xffff0000, v255
	v_pk_add_f32 v[218:219], v[218:219], v[216:217]
	v_pk_add_f32 v[220:221], v[220:221], v[254:255]
	ds_read_b128 v[252:255], v163 offset:2272
	s_waitcnt lgkmcnt(3)
	v_lshlrev_b32_e32 v216, 16, v238
	v_and_b32_e32 v217, 0xffff0000, v238
	v_lshlrev_b32_e32 v238, 16, v239
	v_and_b32_e32 v239, 0xffff0000, v239
	v_pk_add_f32 v[106:107], v[106:107], v[216:217]
	v_pk_add_f32 v[108:109], v[108:109], v[238:239]
	v_lshlrev_b32_e32 v216, 16, v240
	v_and_b32_e32 v217, 0xffff0000, v240
	v_lshlrev_b32_e32 v240, 16, v241
	v_and_b32_e32 v241, 0xffff0000, v241
	v_pk_add_f32 v[218:219], v[218:219], v[216:217]
	v_pk_add_f32 v[220:221], v[220:221], v[240:241]
	ds_read_b128 v[238:241], v163 offset:4208
	s_waitcnt lgkmcnt(3)
	v_lshlrev_b32_e32 v216, 16, v242
	v_and_b32_e32 v217, 0xffff0000, v242
	v_lshlrev_b32_e32 v242, 16, v243
	v_and_b32_e32 v243, 0xffff0000, v243
	v_pk_add_f32 v[106:107], v[106:107], v[216:217]
	v_pk_add_f32 v[108:109], v[108:109], v[242:243]
	v_lshlrev_b32_e32 v216, 16, v244
	v_and_b32_e32 v217, 0xffff0000, v244
	v_lshlrev_b32_e32 v244, 16, v245
	v_and_b32_e32 v245, 0xffff0000, v245
	v_pk_add_f32 v[218:219], v[218:219], v[216:217]
	v_pk_add_f32 v[220:221], v[220:221], v[244:245]
	ds_read_b128 v[242:245], v163 offset:3936
	s_waitcnt lgkmcnt(3)
	v_lshlrev_b32_e32 v216, 16, v248
	v_and_b32_e32 v217, 0xffff0000, v248
	v_lshlrev_b32_e32 v248, 16, v249
	v_and_b32_e32 v249, 0xffff0000, v249
	v_pk_add_f32 v[106:107], v[106:107], v[216:217]
	v_pk_add_f32 v[108:109], v[108:109], v[248:249]
	v_lshlrev_b32_e32 v216, 16, v250
	v_and_b32_e32 v217, 0xffff0000, v250
	v_lshlrev_b32_e32 v250, 16, v251
	v_and_b32_e32 v251, 0xffff0000, v251
	v_pk_add_f32 v[218:219], v[218:219], v[216:217]
	v_pk_add_f32 v[220:221], v[220:221], v[250:251]
	ds_read_b128 v[248:251], v163 offset:3664
	s_waitcnt lgkmcnt(3)
	v_lshlrev_b32_e32 v216, 16, v252
	v_and_b32_e32 v217, 0xffff0000, v252
	v_lshlrev_b32_e32 v252, 16, v253
	v_and_b32_e32 v253, 0xffff0000, v253
	v_pk_add_f32 v[106:107], v[106:107], v[216:217]
	v_pk_add_f32 v[108:109], v[108:109], v[252:253]
	v_lshlrev_b32_e32 v216, 16, v254
	v_and_b32_e32 v217, 0xffff0000, v254
	v_lshlrev_b32_e32 v254, 16, v255
	v_and_b32_e32 v255, 0xffff0000, v255
	v_pk_add_f32 v[218:219], v[218:219], v[216:217]
	v_pk_add_f32 v[220:221], v[220:221], v[254:255]
	ds_read_b128 v[252:255], v163 offset:3392
	v_fma_f32 v106, v159, v106, -v98
	v_fma_f32 v107, v159, v107, -v99
	v_fma_f32 v108, v159, v108, -v100
	v_fma_f32 v109, v159, v109, -v101
	v_fma_f32 v218, v159, v218, -v102
	v_fma_f32 v219, v159, v219, -v103
	v_fma_f32 v220, v159, v220, -v104
	v_fma_f32 v221, v159, v221, -v105
	v_cvt_pk_bf16_f32 v106, v106, v107
	v_cvt_pk_bf16_f32 v107, v108, v109
	v_cvt_pk_bf16_f32 v108, v218, v219
	v_cvt_pk_bf16_f32 v109, v220, v221
	s_and_saveexec_b64 s[28:29], s[6:7]
	s_cbranch_execz .Lpu1_3
	global_store_dwordx4 v[192:193], v[98:101], off offset:192
	global_store_dwordx4 v[192:193], v[102:105], off offset:208
.Lpu1_3:
	s_or_b64 exec, exec, s[28:29]
	s_waitcnt vmcnt(8)
	v_mfma_f32_32x32x16_bf16 v[2:17], v[106:109], v[70:73], v[2:17]
	v_mfma_f32_32x32x16_bf16 v[18:33], v[106:109], v[74:77], v[18:33]
	v_mfma_f32_32x32x16_bf16 v[34:49], v[106:109], v[78:81], v[34:49]
	v_mfma_f32_32x32x16_bf16 v[50:65], v[106:109], v[66:69], v[50:65]
	global_load_dwordx4 v[70:73], v[112:113], off offset:3072
	global_load_dwordx4 v[74:77], v[114:115], off offset:3072
	global_load_dwordx4 v[78:81], v[116:117], off offset:3072
	global_load_dwordx4 v[66:69], v[118:119], off offset:3072
	s_waitcnt lgkmcnt(3)
	v_lshlrev_b32_e32 v98, 16, v238
	v_and_b32_e32 v99, 0xffff0000, v238
	v_lshlrev_b32_e32 v100, 16, v239
	v_and_b32_e32 v101, 0xffff0000, v239
	v_lshlrev_b32_e32 v102, 16, v240
	v_and_b32_e32 v103, 0xffff0000, v240
	v_lshlrev_b32_e32 v104, 16, v241
	v_and_b32_e32 v105, 0xffff0000, v241
	ds_read_b128 v[238:241], v163 offset:3120
	s_waitcnt lgkmcnt(3)
	v_lshlrev_b32_e32 v216, 16, v242
	v_and_b32_e32 v217, 0xffff0000, v242
	v_lshlrev_b32_e32 v242, 16, v243
	v_and_b32_e32 v243, 0xffff0000, v243
	v_pk_add_f32 v[106:107], v[98:99], v[216:217]
	v_pk_add_f32 v[108:109], v[100:101], v[242:243]
	v_lshlrev_b32_e32 v216, 16, v244
	v_and_b32_e32 v217, 0xffff0000, v244
	v_lshlrev_b32_e32 v244, 16, v245
	v_and_b32_e32 v245, 0xffff0000, v245
	v_pk_add_f32 v[218:219], v[102:103], v[216:217]
	v_pk_add_f32 v[220:221], v[104:105], v[244:245]
	ds_read_b128 v[242:245], v163 offset:2848
	s_waitcnt lgkmcnt(3)
	v_lshlrev_b32_e32 v216, 16, v248
	v_and_b32_e32 v217, 0xffff0000, v248
	v_lshlrev_b32_e32 v248, 16, v249
	v_and_b32_e32 v249, 0xffff0000, v249
	v_pk_add_f32 v[106:107], v[106:107], v[216:217]
	v_pk_add_f32 v[108:109], v[108:109], v[248:249]
	v_lshlrev_b32_e32 v216, 16, v250
	v_and_b32_e32 v217, 0xffff0000, v250
	v_lshlrev_b32_e32 v250, 16, v251
	v_and_b32_e32 v251, 0xffff0000, v251
	v_pk_add_f32 v[218:219], v[218:219], v[216:217]
	v_pk_add_f32 v[220:221], v[220:221], v[250:251]
	ds_read_b128 v[248:251], v163 offset:2576
	s_waitcnt lgkmcnt(3)
	v_lshlrev_b32_e32 v216, 16, v252
	v_and_b32_e32 v217, 0xffff0000, v252
	v_lshlrev_b32_e32 v252, 16, v253
	v_and_b32_e32 v253, 0xffff0000, v253
	v_pk_add_f32 v[106:107], v[106:107], v[216:217]
	v_pk_add_f32 v[108:109], v[108:109], v[252:253]
	v_lshlrev_b32_e32 v216, 16, v254
	v_and_b32_e32 v217, 0xffff0000, v254
	v_lshlrev_b32_e32 v254, 16, v255
	v_and_b32_e32 v255, 0xffff0000, v255
	v_pk_add_f32 v[218:219], v[218:219], v[216:217]
	v_pk_add_f32 v[220:221], v[220:221], v[254:255]
	ds_read_b128 v[252:255], v163 offset:2304
	s_waitcnt lgkmcnt(3)
	v_lshlrev_b32_e32 v216, 16, v238
	v_and_b32_e32 v217, 0xffff0000, v238
	v_lshlrev_b32_e32 v238, 16, v239
	v_and_b32_e32 v239, 0xffff0000, v239
	v_pk_add_f32 v[106:107], v[106:107], v[216:217]
	v_pk_add_f32 v[108:109], v[108:109], v[238:239]
	v_lshlrev_b32_e32 v216, 16, v240
	v_and_b32_e32 v217, 0xffff0000, v240
	v_lshlrev_b32_e32 v240, 16, v241
	v_and_b32_e32 v241, 0xffff0000, v241
	v_pk_add_f32 v[218:219], v[218:219], v[216:217]
	v_pk_add_f32 v[220:221], v[220:221], v[240:241]
	ds_read_b128 v[238:241], v163 offset:4240
	s_waitcnt lgkmcnt(3)
	v_lshlrev_b32_e32 v216, 16, v242
	v_and_b32_e32 v217, 0xffff0000, v242
	v_lshlrev_b32_e32 v242, 16, v243
	v_and_b32_e32 v243, 0xffff0000, v243
	v_pk_add_f32 v[106:107], v[106:107], v[216:217]
	v_pk_add_f32 v[108:109], v[108:109], v[242:243]
	v_lshlrev_b32_e32 v216, 16, v244
	v_and_b32_e32 v217, 0xffff0000, v244
	v_lshlrev_b32_e32 v244, 16, v245
	v_and_b32_e32 v245, 0xffff0000, v245
	v_pk_add_f32 v[218:219], v[218:219], v[216:217]
	v_pk_add_f32 v[220:221], v[220:221], v[244:245]
	ds_read_b128 v[242:245], v163 offset:3968
	s_waitcnt lgkmcnt(3)
	v_lshlrev_b32_e32 v216, 16, v248
	v_and_b32_e32 v217, 0xffff0000, v248
	v_lshlrev_b32_e32 v248, 16, v249
	v_and_b32_e32 v249, 0xffff0000, v249
	v_pk_add_f32 v[106:107], v[106:107], v[216:217]
	v_pk_add_f32 v[108:109], v[108:109], v[248:249]
	v_lshlrev_b32_e32 v216, 16, v250
	v_and_b32_e32 v217, 0xffff0000, v250
	v_lshlrev_b32_e32 v250, 16, v251
	v_and_b32_e32 v251, 0xffff0000, v251
	v_pk_add_f32 v[218:219], v[218:219], v[216:217]
	v_pk_add_f32 v[220:221], v[220:221], v[250:251]
	ds_read_b128 v[248:251], v163 offset:3696
	s_waitcnt lgkmcnt(3)
	v_lshlrev_b32_e32 v216, 16, v252
	v_and_b32_e32 v217, 0xffff0000, v252
	v_lshlrev_b32_e32 v252, 16, v253
	v_and_b32_e32 v253, 0xffff0000, v253
	v_pk_add_f32 v[106:107], v[106:107], v[216:217]
	v_pk_add_f32 v[108:109], v[108:109], v[252:253]
	v_lshlrev_b32_e32 v216, 16, v254
	v_and_b32_e32 v217, 0xffff0000, v254
	v_lshlrev_b32_e32 v254, 16, v255
	v_and_b32_e32 v255, 0xffff0000, v255
	v_pk_add_f32 v[218:219], v[218:219], v[216:217]
	v_pk_add_f32 v[220:221], v[220:221], v[254:255]
	ds_read_b128 v[252:255], v163 offset:3424
	v_fma_f32 v106, v159, v106, -v98
	v_fma_f32 v107, v159, v107, -v99
	v_fma_f32 v108, v159, v108, -v100
	v_fma_f32 v109, v159, v109, -v101
	v_fma_f32 v218, v159, v218, -v102
	v_fma_f32 v219, v159, v219, -v103
	v_fma_f32 v220, v159, v220, -v104
	v_fma_f32 v221, v159, v221, -v105
	v_cvt_pk_bf16_f32 v106, v106, v107
	v_cvt_pk_bf16_f32 v107, v108, v109
	v_cvt_pk_bf16_f32 v108, v218, v219
	v_cvt_pk_bf16_f32 v109, v220, v221
	s_and_saveexec_b64 s[28:29], s[6:7]
	s_cbranch_execz .Lpu1_4
	global_store_dwordx4 v[192:193], v[98:101], off offset:256
	global_store_dwordx4 v[192:193], v[102:105], off offset:272
.Lpu1_4:
	s_or_b64 exec, exec, s[28:29]
	s_waitcnt vmcnt(8)
	v_mfma_f32_32x32x16_bf16 v[2:17], v[106:109], v[82:85], v[2:17]
	v_mfma_f32_32x32x16_bf16 v[18:33], v[106:109], v[86:89], v[18:33]
	v_mfma_f32_32x32x16_bf16 v[34:49], v[106:109], v[90:93], v[34:49]
	v_mfma_f32_32x32x16_bf16 v[50:65], v[106:109], v[94:97], v[50:65]
	global_load_dwordx4 v[82:85], v[112:113], off offset:3584
	global_load_dwordx4 v[86:89], v[114:115], off offset:3584
	global_load_dwordx4 v[90:93], v[116:117], off offset:3584
	global_load_dwordx4 v[94:97], v[118:119], off offset:3584
	s_waitcnt lgkmcnt(3)
	v_lshlrev_b32_e32 v98, 16, v238
	v_and_b32_e32 v99, 0xffff0000, v238
	v_lshlrev_b32_e32 v100, 16, v239
	v_and_b32_e32 v101, 0xffff0000, v239
	v_lshlrev_b32_e32 v102, 16, v240
	v_and_b32_e32 v103, 0xffff0000, v240
	v_lshlrev_b32_e32 v104, 16, v241
	v_and_b32_e32 v105, 0xffff0000, v241
	ds_read_b128 v[238:241], v163 offset:3152
	s_waitcnt lgkmcnt(3)
	v_lshlrev_b32_e32 v216, 16, v242
	v_and_b32_e32 v217, 0xffff0000, v242
	v_lshlrev_b32_e32 v242, 16, v243
	v_and_b32_e32 v243, 0xffff0000, v243
	v_pk_add_f32 v[106:107], v[98:99], v[216:217]
	v_pk_add_f32 v[108:109], v[100:101], v[242:243]
	v_lshlrev_b32_e32 v216, 16, v244
	v_and_b32_e32 v217, 0xffff0000, v244
	v_lshlrev_b32_e32 v244, 16, v245
	v_and_b32_e32 v245, 0xffff0000, v245
	v_pk_add_f32 v[218:219], v[102:103], v[216:217]
	v_pk_add_f32 v[220:221], v[104:105], v[244:245]
	ds_read_b128 v[242:245], v163 offset:2880
	s_waitcnt lgkmcnt(3)
	v_lshlrev_b32_e32 v216, 16, v248
	v_and_b32_e32 v217, 0xffff0000, v248
	v_lshlrev_b32_e32 v248, 16, v249
	v_and_b32_e32 v249, 0xffff0000, v249
	v_pk_add_f32 v[106:107], v[106:107], v[216:217]
	v_pk_add_f32 v[108:109], v[108:109], v[248:249]
	v_lshlrev_b32_e32 v216, 16, v250
	v_and_b32_e32 v217, 0xffff0000, v250
	v_lshlrev_b32_e32 v250, 16, v251
	v_and_b32_e32 v251, 0xffff0000, v251
	v_pk_add_f32 v[218:219], v[218:219], v[216:217]
	v_pk_add_f32 v[220:221], v[220:221], v[250:251]
	ds_read_b128 v[248:251], v163 offset:2608
	s_waitcnt lgkmcnt(3)
	v_lshlrev_b32_e32 v216, 16, v252
	v_and_b32_e32 v217, 0xffff0000, v252
	v_lshlrev_b32_e32 v252, 16, v253
	v_and_b32_e32 v253, 0xffff0000, v253
	v_pk_add_f32 v[106:107], v[106:107], v[216:217]
	v_pk_add_f32 v[108:109], v[108:109], v[252:253]
	v_lshlrev_b32_e32 v216, 16, v254
	v_and_b32_e32 v217, 0xffff0000, v254
	v_lshlrev_b32_e32 v254, 16, v255
	v_and_b32_e32 v255, 0xffff0000, v255
	v_pk_add_f32 v[218:219], v[218:219], v[216:217]
	v_pk_add_f32 v[220:221], v[220:221], v[254:255]
	ds_read_b128 v[252:255], v163 offset:2336
	s_waitcnt lgkmcnt(3)
	v_lshlrev_b32_e32 v216, 16, v238
	v_and_b32_e32 v217, 0xffff0000, v238
	v_lshlrev_b32_e32 v238, 16, v239
	v_and_b32_e32 v239, 0xffff0000, v239
	v_pk_add_f32 v[106:107], v[106:107], v[216:217]
	v_pk_add_f32 v[108:109], v[108:109], v[238:239]
	v_lshlrev_b32_e32 v216, 16, v240
	v_and_b32_e32 v217, 0xffff0000, v240
	v_lshlrev_b32_e32 v240, 16, v241
	v_and_b32_e32 v241, 0xffff0000, v241
	v_pk_add_f32 v[218:219], v[218:219], v[216:217]
	v_pk_add_f32 v[220:221], v[220:221], v[240:241]
	ds_read_b128 v[238:241], v163 offset:4272
	s_waitcnt lgkmcnt(3)
	v_lshlrev_b32_e32 v216, 16, v242
	v_and_b32_e32 v217, 0xffff0000, v242
	v_lshlrev_b32_e32 v242, 16, v243
	v_and_b32_e32 v243, 0xffff0000, v243
	v_pk_add_f32 v[106:107], v[106:107], v[216:217]
	v_pk_add_f32 v[108:109], v[108:109], v[242:243]
	v_lshlrev_b32_e32 v216, 16, v244
	v_and_b32_e32 v217, 0xffff0000, v244
	v_lshlrev_b32_e32 v244, 16, v245
	v_and_b32_e32 v245, 0xffff0000, v245
	v_pk_add_f32 v[218:219], v[218:219], v[216:217]
	v_pk_add_f32 v[220:221], v[220:221], v[244:245]
	ds_read_b128 v[242:245], v163 offset:4000
	s_waitcnt lgkmcnt(3)
	v_lshlrev_b32_e32 v216, 16, v248
	v_and_b32_e32 v217, 0xffff0000, v248
	v_lshlrev_b32_e32 v248, 16, v249
	v_and_b32_e32 v249, 0xffff0000, v249
	v_pk_add_f32 v[106:107], v[106:107], v[216:217]
	v_pk_add_f32 v[108:109], v[108:109], v[248:249]
	v_lshlrev_b32_e32 v216, 16, v250
	v_and_b32_e32 v217, 0xffff0000, v250
	v_lshlrev_b32_e32 v250, 16, v251
	v_and_b32_e32 v251, 0xffff0000, v251
	v_pk_add_f32 v[218:219], v[218:219], v[216:217]
	v_pk_add_f32 v[220:221], v[220:221], v[250:251]
	ds_read_b128 v[248:251], v163 offset:3728
	s_waitcnt lgkmcnt(3)
	v_lshlrev_b32_e32 v216, 16, v252
	v_and_b32_e32 v217, 0xffff0000, v252
	v_lshlrev_b32_e32 v252, 16, v253
	v_and_b32_e32 v253, 0xffff0000, v253
	v_pk_add_f32 v[106:107], v[106:107], v[216:217]
	v_pk_add_f32 v[108:109], v[108:109], v[252:253]
	v_lshlrev_b32_e32 v216, 16, v254
	v_and_b32_e32 v217, 0xffff0000, v254
	v_lshlrev_b32_e32 v254, 16, v255
	v_and_b32_e32 v255, 0xffff0000, v255
	v_pk_add_f32 v[218:219], v[218:219], v[216:217]
	v_pk_add_f32 v[220:221], v[220:221], v[254:255]
	ds_read_b128 v[252:255], v163 offset:3456
	v_fma_f32 v106, v159, v106, -v98
	v_fma_f32 v107, v159, v107, -v99
	v_fma_f32 v108, v159, v108, -v100
	v_fma_f32 v109, v159, v109, -v101
	v_fma_f32 v218, v159, v218, -v102
	v_fma_f32 v219, v159, v219, -v103
	v_fma_f32 v220, v159, v220, -v104
	v_fma_f32 v221, v159, v221, -v105
	v_cvt_pk_bf16_f32 v106, v106, v107
	v_cvt_pk_bf16_f32 v107, v108, v109
	v_cvt_pk_bf16_f32 v108, v218, v219
	v_cvt_pk_bf16_f32 v109, v220, v221
	s_and_saveexec_b64 s[28:29], s[6:7]
	s_cbranch_execz .Lpu1_5
	global_store_dwordx4 v[192:193], v[98:101], off offset:320
	global_store_dwordx4 v[192:193], v[102:105], off offset:336
.Lpu1_5:
	s_or_b64 exec, exec, s[28:29]
	s_waitcnt vmcnt(8)
	v_mfma_f32_32x32x16_bf16 v[2:17], v[106:109], v[222:225], v[2:17]
	v_mfma_f32_32x32x16_bf16 v[18:33], v[106:109], v[226:229], v[18:33]
	v_mfma_f32_32x32x16_bf16 v[34:49], v[106:109], v[230:233], v[34:49]
	v_mfma_f32_32x32x16_bf16 v[50:65], v[106:109], v[234:237], v[50:65]
	s_waitcnt lgkmcnt(3)
	v_lshlrev_b32_e32 v98, 16, v238
	v_and_b32_e32 v99, 0xffff0000, v238
	v_lshlrev_b32_e32 v100, 16, v239
	v_and_b32_e32 v101, 0xffff0000, v239
	v_lshlrev_b32_e32 v102, 16, v240
	v_and_b32_e32 v103, 0xffff0000, v240
	v_lshlrev_b32_e32 v104, 16, v241
	v_and_b32_e32 v105, 0xffff0000, v241
	ds_read_b128 v[238:241], v163 offset:3184
	s_waitcnt lgkmcnt(3)
	v_lshlrev_b32_e32 v216, 16, v242
	v_and_b32_e32 v217, 0xffff0000, v242
	v_lshlrev_b32_e32 v242, 16, v243
	v_and_b32_e32 v243, 0xffff0000, v243
	v_pk_add_f32 v[106:107], v[98:99], v[216:217]
	v_pk_add_f32 v[108:109], v[100:101], v[242:243]
	v_lshlrev_b32_e32 v216, 16, v244
	v_and_b32_e32 v217, 0xffff0000, v244
	v_lshlrev_b32_e32 v244, 16, v245
	v_and_b32_e32 v245, 0xffff0000, v245
	v_pk_add_f32 v[218:219], v[102:103], v[216:217]
	v_pk_add_f32 v[220:221], v[104:105], v[244:245]
	ds_read_b128 v[242:245], v163 offset:2912
	s_waitcnt lgkmcnt(3)
	v_lshlrev_b32_e32 v216, 16, v248
	v_and_b32_e32 v217, 0xffff0000, v248
	v_lshlrev_b32_e32 v248, 16, v249
	v_and_b32_e32 v249, 0xffff0000, v249
	v_pk_add_f32 v[106:107], v[106:107], v[216:217]
	v_pk_add_f32 v[108:109], v[108:109], v[248:249]
	v_lshlrev_b32_e32 v216, 16, v250
	v_and_b32_e32 v217, 0xffff0000, v250
	v_lshlrev_b32_e32 v250, 16, v251
	v_and_b32_e32 v251, 0xffff0000, v251
	v_pk_add_f32 v[218:219], v[218:219], v[216:217]
	v_pk_add_f32 v[220:221], v[220:221], v[250:251]
	ds_read_b128 v[248:251], v163 offset:2640
	s_waitcnt lgkmcnt(3)
	v_lshlrev_b32_e32 v216, 16, v252
	v_and_b32_e32 v217, 0xffff0000, v252
	v_lshlrev_b32_e32 v252, 16, v253
	v_and_b32_e32 v253, 0xffff0000, v253
	v_pk_add_f32 v[106:107], v[106:107], v[216:217]
	v_pk_add_f32 v[108:109], v[108:109], v[252:253]
	v_lshlrev_b32_e32 v216, 16, v254
	v_and_b32_e32 v217, 0xffff0000, v254
	v_lshlrev_b32_e32 v254, 16, v255
	v_and_b32_e32 v255, 0xffff0000, v255
	v_pk_add_f32 v[218:219], v[218:219], v[216:217]
	v_pk_add_f32 v[220:221], v[220:221], v[254:255]
	ds_read_b128 v[252:255], v163 offset:2368
	s_waitcnt lgkmcnt(3)
	v_lshlrev_b32_e32 v216, 16, v238
	v_and_b32_e32 v217, 0xffff0000, v238
	v_lshlrev_b32_e32 v238, 16, v239
	v_and_b32_e32 v239, 0xffff0000, v239
	v_pk_add_f32 v[106:107], v[106:107], v[216:217]
	v_pk_add_f32 v[108:109], v[108:109], v[238:239]
	v_lshlrev_b32_e32 v216, 16, v240
	v_and_b32_e32 v217, 0xffff0000, v240
	v_lshlrev_b32_e32 v240, 16, v241
	v_and_b32_e32 v241, 0xffff0000, v241
	v_pk_add_f32 v[218:219], v[218:219], v[216:217]
	v_pk_add_f32 v[220:221], v[220:221], v[240:241]
	ds_read_b128 v[238:241], v163 offset:4304
	s_waitcnt lgkmcnt(3)
	v_lshlrev_b32_e32 v216, 16, v242
	v_and_b32_e32 v217, 0xffff0000, v242
	v_lshlrev_b32_e32 v242, 16, v243
	v_and_b32_e32 v243, 0xffff0000, v243
	v_pk_add_f32 v[106:107], v[106:107], v[216:217]
	v_pk_add_f32 v[108:109], v[108:109], v[242:243]
	v_lshlrev_b32_e32 v216, 16, v244
	v_and_b32_e32 v217, 0xffff0000, v244
	v_lshlrev_b32_e32 v244, 16, v245
	v_and_b32_e32 v245, 0xffff0000, v245
	v_pk_add_f32 v[218:219], v[218:219], v[216:217]
	v_pk_add_f32 v[220:221], v[220:221], v[244:245]
	ds_read_b128 v[242:245], v163 offset:4032
	s_waitcnt lgkmcnt(3)
	v_lshlrev_b32_e32 v216, 16, v248
	v_and_b32_e32 v217, 0xffff0000, v248
	v_lshlrev_b32_e32 v248, 16, v249
	v_and_b32_e32 v249, 0xffff0000, v249
	v_pk_add_f32 v[106:107], v[106:107], v[216:217]
	v_pk_add_f32 v[108:109], v[108:109], v[248:249]
	v_lshlrev_b32_e32 v216, 16, v250
	v_and_b32_e32 v217, 0xffff0000, v250
	v_lshlrev_b32_e32 v250, 16, v251
	v_and_b32_e32 v251, 0xffff0000, v251
	v_pk_add_f32 v[218:219], v[218:219], v[216:217]
	v_pk_add_f32 v[220:221], v[220:221], v[250:251]
	ds_read_b128 v[248:251], v163 offset:3760
	s_waitcnt lgkmcnt(3)
	v_lshlrev_b32_e32 v216, 16, v252
	v_and_b32_e32 v217, 0xffff0000, v252
	v_lshlrev_b32_e32 v252, 16, v253
	v_and_b32_e32 v253, 0xffff0000, v253
	v_pk_add_f32 v[106:107], v[106:107], v[216:217]
	v_pk_add_f32 v[108:109], v[108:109], v[252:253]
	v_lshlrev_b32_e32 v216, 16, v254
	v_and_b32_e32 v217, 0xffff0000, v254
	v_lshlrev_b32_e32 v254, 16, v255
	v_and_b32_e32 v255, 0xffff0000, v255
	v_pk_add_f32 v[218:219], v[218:219], v[216:217]
	v_pk_add_f32 v[220:221], v[220:221], v[254:255]
	ds_read_b128 v[252:255], v163 offset:3488
	v_fma_f32 v106, v159, v106, -v98
	v_fma_f32 v107, v159, v107, -v99
	v_fma_f32 v108, v159, v108, -v100
	v_fma_f32 v109, v159, v109, -v101
	v_fma_f32 v218, v159, v218, -v102
	v_fma_f32 v219, v159, v219, -v103
	v_fma_f32 v220, v159, v220, -v104
	v_fma_f32 v221, v159, v221, -v105
	v_cvt_pk_bf16_f32 v106, v106, v107
	v_cvt_pk_bf16_f32 v107, v108, v109
	v_cvt_pk_bf16_f32 v108, v218, v219
	v_cvt_pk_bf16_f32 v109, v220, v221
	s_and_saveexec_b64 s[28:29], s[6:7]
	s_cbranch_execz .Lpu1_6
	global_store_dwordx4 v[192:193], v[98:101], off offset:384
	global_store_dwordx4 v[192:193], v[102:105], off offset:400
.Lpu1_6:
	s_or_b64 exec, exec, s[28:29]
	s_waitcnt vmcnt(4)
	v_mfma_f32_32x32x16_bf16 v[2:17], v[106:109], v[70:73], v[2:17]
	v_mfma_f32_32x32x16_bf16 v[18:33], v[106:109], v[74:77], v[18:33]
	v_mfma_f32_32x32x16_bf16 v[34:49], v[106:109], v[78:81], v[34:49]
	v_mfma_f32_32x32x16_bf16 v[50:65], v[106:109], v[66:69], v[50:65]
	s_waitcnt lgkmcnt(3)
	v_lshlrev_b32_e32 v98, 16, v238
	v_and_b32_e32 v99, 0xffff0000, v238
	v_lshlrev_b32_e32 v100, 16, v239
	v_and_b32_e32 v101, 0xffff0000, v239
	v_lshlrev_b32_e32 v102, 16, v240
	v_and_b32_e32 v103, 0xffff0000, v240
	v_lshlrev_b32_e32 v104, 16, v241
	v_and_b32_e32 v105, 0xffff0000, v241
	ds_read_b128 v[238:241], v163 offset:3216
	s_waitcnt lgkmcnt(3)
	v_lshlrev_b32_e32 v216, 16, v242
	v_and_b32_e32 v217, 0xffff0000, v242
	v_lshlrev_b32_e32 v242, 16, v243
	v_and_b32_e32 v243, 0xffff0000, v243
	v_pk_add_f32 v[106:107], v[98:99], v[216:217]
	v_pk_add_f32 v[108:109], v[100:101], v[242:243]
	v_lshlrev_b32_e32 v216, 16, v244
	v_and_b32_e32 v217, 0xffff0000, v244
	v_lshlrev_b32_e32 v244, 16, v245
	v_and_b32_e32 v245, 0xffff0000, v245
	v_pk_add_f32 v[218:219], v[102:103], v[216:217]
	v_pk_add_f32 v[220:221], v[104:105], v[244:245]
	ds_read_b128 v[242:245], v163 offset:2944
	s_waitcnt lgkmcnt(3)
	v_lshlrev_b32_e32 v216, 16, v248
	v_and_b32_e32 v217, 0xffff0000, v248
	v_lshlrev_b32_e32 v248, 16, v249
	v_and_b32_e32 v249, 0xffff0000, v249
	v_pk_add_f32 v[106:107], v[106:107], v[216:217]
	v_pk_add_f32 v[108:109], v[108:109], v[248:249]
	v_lshlrev_b32_e32 v216, 16, v250
	v_and_b32_e32 v217, 0xffff0000, v250
	v_lshlrev_b32_e32 v250, 16, v251
	v_and_b32_e32 v251, 0xffff0000, v251
	v_pk_add_f32 v[218:219], v[218:219], v[216:217]
	v_pk_add_f32 v[220:221], v[220:221], v[250:251]
	ds_read_b128 v[248:251], v163 offset:2672
	s_waitcnt lgkmcnt(3)
	v_lshlrev_b32_e32 v216, 16, v252
	v_and_b32_e32 v217, 0xffff0000, v252
	v_lshlrev_b32_e32 v252, 16, v253
	v_and_b32_e32 v253, 0xffff0000, v253
	v_pk_add_f32 v[106:107], v[106:107], v[216:217]
	v_pk_add_f32 v[108:109], v[108:109], v[252:253]
	v_lshlrev_b32_e32 v216, 16, v254
	v_and_b32_e32 v217, 0xffff0000, v254
	v_lshlrev_b32_e32 v254, 16, v255
	v_and_b32_e32 v255, 0xffff0000, v255
	v_pk_add_f32 v[218:219], v[218:219], v[216:217]
	v_pk_add_f32 v[220:221], v[220:221], v[254:255]
	ds_read_b128 v[252:255], v163 offset:2400
	s_waitcnt lgkmcnt(3)
	v_lshlrev_b32_e32 v216, 16, v238
	v_and_b32_e32 v217, 0xffff0000, v238
	v_lshlrev_b32_e32 v238, 16, v239
	v_and_b32_e32 v239, 0xffff0000, v239
	v_pk_add_f32 v[106:107], v[106:107], v[216:217]
	v_pk_add_f32 v[108:109], v[108:109], v[238:239]
	v_lshlrev_b32_e32 v216, 16, v240
	v_and_b32_e32 v217, 0xffff0000, v240
	v_lshlrev_b32_e32 v240, 16, v241
	v_and_b32_e32 v241, 0xffff0000, v241
	v_pk_add_f32 v[218:219], v[218:219], v[216:217]
	v_pk_add_f32 v[220:221], v[220:221], v[240:241]
	s_waitcnt lgkmcnt(2)
	v_lshlrev_b32_e32 v216, 16, v242
	v_and_b32_e32 v217, 0xffff0000, v242
	v_lshlrev_b32_e32 v242, 16, v243
	v_and_b32_e32 v243, 0xffff0000, v243
	v_pk_add_f32 v[106:107], v[106:107], v[216:217]
	v_pk_add_f32 v[108:109], v[108:109], v[242:243]
	v_lshlrev_b32_e32 v216, 16, v244
	v_and_b32_e32 v217, 0xffff0000, v244
	v_lshlrev_b32_e32 v244, 16, v245
	v_and_b32_e32 v245, 0xffff0000, v245
	v_pk_add_f32 v[218:219], v[218:219], v[216:217]
	v_pk_add_f32 v[220:221], v[220:221], v[244:245]
	s_waitcnt lgkmcnt(1)
	v_lshlrev_b32_e32 v216, 16, v248
	v_and_b32_e32 v217, 0xffff0000, v248
	v_lshlrev_b32_e32 v248, 16, v249
	v_and_b32_e32 v249, 0xffff0000, v249
	v_pk_add_f32 v[106:107], v[106:107], v[216:217]
	v_pk_add_f32 v[108:109], v[108:109], v[248:249]
	v_lshlrev_b32_e32 v216, 16, v250
	v_and_b32_e32 v217, 0xffff0000, v250
	v_lshlrev_b32_e32 v250, 16, v251
	v_and_b32_e32 v251, 0xffff0000, v251
	v_pk_add_f32 v[218:219], v[218:219], v[216:217]
	v_pk_add_f32 v[220:221], v[220:221], v[250:251]
	s_waitcnt lgkmcnt(0)
	v_lshlrev_b32_e32 v216, 16, v252
	v_and_b32_e32 v217, 0xffff0000, v252
	v_lshlrev_b32_e32 v252, 16, v253
	v_and_b32_e32 v253, 0xffff0000, v253
	v_pk_add_f32 v[106:107], v[106:107], v[216:217]
	v_pk_add_f32 v[108:109], v[108:109], v[252:253]
	v_lshlrev_b32_e32 v216, 16, v254
	v_and_b32_e32 v217, 0xffff0000, v254
	v_lshlrev_b32_e32 v254, 16, v255
	v_and_b32_e32 v255, 0xffff0000, v255
	v_pk_add_f32 v[218:219], v[218:219], v[216:217]
	v_pk_add_f32 v[220:221], v[220:221], v[254:255]
	v_fma_f32 v106, v159, v106, -v98
	v_fma_f32 v107, v159, v107, -v99
	v_fma_f32 v108, v159, v108, -v100
	v_fma_f32 v109, v159, v109, -v101
	v_fma_f32 v218, v159, v218, -v102
	v_fma_f32 v219, v159, v219, -v103
	v_fma_f32 v220, v159, v220, -v104
	v_fma_f32 v221, v159, v221, -v105
	v_cvt_pk_bf16_f32 v106, v106, v107
	v_cvt_pk_bf16_f32 v107, v108, v109
	v_cvt_pk_bf16_f32 v108, v218, v219
	v_cvt_pk_bf16_f32 v109, v220, v221
	s_and_saveexec_b64 s[28:29], s[6:7]
	s_cbranch_execz .Lpu1_7
	global_store_dwordx4 v[192:193], v[98:101], off offset:448
	global_store_dwordx4 v[192:193], v[102:105], off offset:464

.LBB0_379:
	s_or_b64 exec, exec, s[6:7]
	s_waitcnt lgkmcnt(0)
	global_load_dwordx4 v[82:85], v[122:123], off offset:512
	global_load_dwordx4 v[86:89], v[124:125], off offset:512
	global_load_dwordx4 v[90:93], v[126:127], off offset:512
	global_load_dwordx4 v[94:97], v[128:129], off offset:512
	global_load_dwordx4 v[222:225], v[122:123], off offset:1024
	global_load_dwordx4 v[226:229], v[124:125], off offset:1024
	global_load_dwordx4 v[230:233], v[126:127], off offset:1024
	global_load_dwordx4 v[234:237], v[128:129], off offset:1024
	v_or_b32_e32 v2, s28, v1
	v_min_u32_e32 v3, 3, v2
	v_add_u32_e32 v3, 1, v3
	v_cvt_f32_ubyte0_e32 v3, v3
	v_div_scale_f32 v4, s[6:7], v3, v3, 1.0
	v_rcp_f32_e32 v5, v4
	s_ashr_i32 s8, s30, 6
	s_mul_i32 s10, s8, 15
	v_cmp_lt_u32_e64 s[6:7], s41, v2
	v_fma_f32 v6, -v4, v5, 1.0
	v_fmac_f32_e32 v5, v6, v5
	v_div_scale_f32 v6, vcc, 1.0, v3, 1.0
	v_mul_f32_e32 v7, v6, v5
	v_fma_f32 v8, -v4, v7, v6
	v_fmac_f32_e32 v7, v8, v5
	v_fma_f32 v4, -v4, v7, v6
	v_div_fmas_f32 v4, v4, v5, v7
	v_div_fixup_f32 v159, v4, v3, 1.0
	s_ashr_i32 s11, s10, 31
	v_add_u32_e32 v2, 0xfffff80f, v2
	v_mov_b32_e32 v3, v155
	v_lshl_add_u64 v[2:3], v[2:3], 0, s[10:11]
	v_lshlrev_b64 v[2:3], 11, v[2:3]
	v_lshl_add_u64 v[2:3], s[70:71], 0, v[2:3]
	v_mov_b32_e32 v163, v155
	v_lshl_add_u64 v[2:3], v[2:3], 0, v[162:163]
	v_lshl_add_u64 v[190:191], v[2:3], 0, s[24:25]
	v_mov_b32_e32 v2, 0
	s_mov_b32 s49, 0
	s_mov_b64 s[10:11], 0
	v_mov_b32_e32 v3, v2
	v_mov_b32_e32 v4, v2
	v_mov_b32_e32 v5, v2
	v_mov_b32_e32 v6, v2
	v_mov_b32_e32 v7, v2
	v_mov_b32_e32 v8, v2
	v_mov_b32_e32 v9, v2
	v_mov_b32_e32 v10, v2
	v_mov_b32_e32 v11, v2
	v_mov_b32_e32 v12, v2
	v_mov_b32_e32 v13, v2
	v_mov_b32_e32 v14, v2
	v_mov_b32_e32 v15, v2
	v_mov_b32_e32 v16, v2
	v_mov_b32_e32 v17, v2
	v_mov_b32_e32 v18, v2
	v_mov_b32_e32 v19, v2
	v_mov_b32_e32 v20, v2
	v_mov_b32_e32 v21, v2
	v_mov_b32_e32 v22, v2
	v_mov_b32_e32 v23, v2
	v_mov_b32_e32 v24, v2
	v_mov_b32_e32 v25, v2
	v_mov_b32_e32 v26, v2
	v_mov_b32_e32 v27, v2
	v_mov_b32_e32 v28, v2
	v_mov_b32_e32 v29, v2
	v_mov_b32_e32 v30, v2
	v_mov_b32_e32 v31, v2
	v_mov_b32_e32 v32, v2
	v_mov_b32_e32 v33, v2
	v_mov_b32_e32 v34, v2
	v_mov_b32_e32 v35, v2
	v_mov_b32_e32 v36, v2
	v_mov_b32_e32 v37, v2
	v_mov_b32_e32 v38, v2
	v_mov_b32_e32 v39, v2
	v_mov_b32_e32 v40, v2
	v_mov_b32_e32 v41, v2
	v_mov_b32_e32 v42, v2
	v_mov_b32_e32 v43, v2
	v_mov_b32_e32 v44, v2
	v_mov_b32_e32 v45, v2
	v_mov_b32_e32 v46, v2
	v_mov_b32_e32 v47, v2
	v_mov_b32_e32 v48, v2
	v_mov_b32_e32 v49, v2
	v_mov_b32_e32 v50, v2
	v_mov_b32_e32 v51, v2
	v_mov_b32_e32 v52, v2
	v_mov_b32_e32 v53, v2
	v_mov_b32_e32 v54, v2
	v_mov_b32_e32 v55, v2
	v_mov_b32_e32 v56, v2
	v_mov_b32_e32 v57, v2
	v_mov_b32_e32 v58, v2
	v_mov_b32_e32 v59, v2
	v_mov_b32_e32 v60, v2
	v_mov_b32_e32 v61, v2
	v_mov_b32_e32 v62, v2
	v_mov_b32_e32 v63, v2
	v_mov_b32_e32 v64, v2
	v_mov_b32_e32 v65, v2
	v_lshl_add_u32 v163, v197, 1, v214
	ds_read_b128 v[238:241], v163 offset:4080
	ds_read_b128 v[242:245], v163 offset:3808
	ds_read_b128 v[248:251], v163 offset:3536
	ds_read_b128 v[252:255], v163 offset:3264
	s_waitcnt lgkmcnt(3)
	v_lshlrev_b32_e32 v98, 16, v238
	v_and_b32_e32 v99, 0xffff0000, v238
	v_lshlrev_b32_e32 v100, 16, v239
	v_and_b32_e32 v101, 0xffff0000, v239
	v_lshlrev_b32_e32 v102, 16, v240
	v_and_b32_e32 v103, 0xffff0000, v240
	v_lshlrev_b32_e32 v104, 16, v241
	v_and_b32_e32 v105, 0xffff0000, v241
	ds_read_b128 v[238:241], v163 offset:4112
	s_waitcnt lgkmcnt(3)
	v_lshlrev_b32_e32 v216, 16, v242
	v_and_b32_e32 v217, 0xffff0000, v242
	v_lshlrev_b32_e32 v242, 16, v243
	v_and_b32_e32 v243, 0xffff0000, v243
	v_pk_add_f32 v[106:107], v[98:99], v[216:217]
	v_pk_add_f32 v[108:109], v[100:101], v[242:243]
	v_lshlrev_b32_e32 v216, 16, v244
	v_and_b32_e32 v217, 0xffff0000, v244
	v_lshlrev_b32_e32 v244, 16, v245
	v_and_b32_e32 v245, 0xffff0000, v245
	v_pk_add_f32 v[218:219], v[102:103], v[216:217]
	v_pk_add_f32 v[220:221], v[104:105], v[244:245]
	ds_read_b128 v[242:245], v163 offset:3840
	s_waitcnt lgkmcnt(3)
	v_lshlrev_b32_e32 v216, 16, v248
	v_and_b32_e32 v217, 0xffff0000, v248
	v_lshlrev_b32_e32 v248, 16, v249
	v_and_b32_e32 v249, 0xffff0000, v249
	v_pk_add_f32 v[106:107], v[106:107], v[216:217]
	v_pk_add_f32 v[108:109], v[108:109], v[248:249]
	v_lshlrev_b32_e32 v216, 16, v250
	v_and_b32_e32 v217, 0xffff0000, v250
	v_lshlrev_b32_e32 v250, 16, v251
	v_and_b32_e32 v251, 0xffff0000, v251
	v_pk_add_f32 v[218:219], v[218:219], v[216:217]
	v_pk_add_f32 v[220:221], v[220:221], v[250:251]
	ds_read_b128 v[248:251], v163 offset:3568
	s_waitcnt lgkmcnt(3)
	v_lshlrev_b32_e32 v216, 16, v252
	v_and_b32_e32 v217, 0xffff0000, v252
	v_lshlrev_b32_e32 v252, 16, v253
	v_and_b32_e32 v253, 0xffff0000, v253
	v_pk_add_f32 v[106:107], v[106:107], v[216:217]
	v_pk_add_f32 v[108:109], v[108:109], v[252:253]
	v_lshlrev_b32_e32 v216, 16, v254
	v_and_b32_e32 v217, 0xffff0000, v254
	v_lshlrev_b32_e32 v254, 16, v255
	v_and_b32_e32 v255, 0xffff0000, v255
	v_pk_add_f32 v[218:219], v[218:219], v[216:217]
	v_pk_add_f32 v[220:221], v[220:221], v[254:255]
	ds_read_b128 v[252:255], v163 offset:3296
	v_fma_f32 v106, v159, v106, -v98
	v_fma_f32 v107, v159, v107, -v99
	v_fma_f32 v108, v159, v108, -v100
	v_fma_f32 v109, v159, v109, -v101
	v_fma_f32 v218, v159, v218, -v102
	v_fma_f32 v219, v159, v219, -v103
	v_fma_f32 v220, v159, v220, -v104
	v_fma_f32 v221, v159, v221, -v105
	v_cvt_pk_bf16_f32 v106, v106, v107
	v_cvt_pk_bf16_f32 v107, v108, v109
	v_cvt_pk_bf16_f32 v108, v218, v219
	v_cvt_pk_bf16_f32 v109, v220, v221
	s_and_saveexec_b64 s[28:29], s[6:7]
	s_cbranch_execz .Lpu2_0
	global_store_dwordx4 v[190:191], v[98:101], off offset:0
	global_store_dwordx4 v[190:191], v[102:105], off offset:16
.Lpu2_0:
	s_or_b64 exec, exec, s[28:29]
	s_waitcnt vmcnt(8)
	v_mfma_f32_32x32x16_bf16 v[2:17], v[106:109], v[70:73], v[2:17]
	v_mfma_f32_32x32x16_bf16 v[18:33], v[106:109], v[74:77], v[18:33]
	v_mfma_f32_32x32x16_bf16 v[34:49], v[106:109], v[78:81], v[34:49]
	v_mfma_f32_32x32x16_bf16 v[50:65], v[106:109], v[66:69], v[50:65]
	global_load_dwordx4 v[70:73], v[122:123], off offset:1536
	global_load_dwordx4 v[74:77], v[124:125], off offset:1536
	global_load_dwordx4 v[78:81], v[126:127], off offset:1536
	global_load_dwordx4 v[66:69], v[128:129], off offset:1536
	s_waitcnt lgkmcnt(3)
	v_lshlrev_b32_e32 v98, 16, v238
	v_and_b32_e32 v99, 0xffff0000, v238
	v_lshlrev_b32_e32 v100, 16, v239
	v_and_b32_e32 v101, 0xffff0000, v239
	v_lshlrev_b32_e32 v102, 16, v240
	v_and_b32_e32 v103, 0xffff0000, v240
	v_lshlrev_b32_e32 v104, 16, v241
	v_and_b32_e32 v105, 0xffff0000, v241
	ds_read_b128 v[238:241], v163 offset:4144
	s_waitcnt lgkmcnt(3)
	v_lshlrev_b32_e32 v216, 16, v242
	v_and_b32_e32 v217, 0xffff0000, v242
	v_lshlrev_b32_e32 v242, 16, v243
	v_and_b32_e32 v243, 0xffff0000, v243
	v_pk_add_f32 v[106:107], v[98:99], v[216:217]
	v_pk_add_f32 v[108:109], v[100:101], v[242:243]
	v_lshlrev_b32_e32 v216, 16, v244
	v_and_b32_e32 v217, 0xffff0000, v244
	v_lshlrev_b32_e32 v244, 16, v245
	v_and_b32_e32 v245, 0xffff0000, v245
	v_pk_add_f32 v[218:219], v[102:103], v[216:217]
	v_pk_add_f32 v[220:221], v[104:105], v[244:245]
	ds_read_b128 v[242:245], v163 offset:3872
	s_waitcnt lgkmcnt(3)
	v_lshlrev_b32_e32 v216, 16, v248
	v_and_b32_e32 v217, 0xffff0000, v248
	v_lshlrev_b32_e32 v248, 16, v249
	v_and_b32_e32 v249, 0xffff0000, v249
	v_pk_add_f32 v[106:107], v[106:107], v[216:217]
	v_pk_add_f32 v[108:109], v[108:109], v[248:249]
	v_lshlrev_b32_e32 v216, 16, v250
	v_and_b32_e32 v217, 0xffff0000, v250
	v_lshlrev_b32_e32 v250, 16, v251
	v_and_b32_e32 v251, 0xffff0000, v251
	v_pk_add_f32 v[218:219], v[218:219], v[216:217]
	v_pk_add_f32 v[220:221], v[220:221], v[250:251]
	ds_read_b128 v[248:251], v163 offset:3600
	s_waitcnt lgkmcnt(3)
	v_lshlrev_b32_e32 v216, 16, v252
	v_and_b32_e32 v217, 0xffff0000, v252
	v_lshlrev_b32_e32 v252, 16, v253
	v_and_b32_e32 v253, 0xffff0000, v253
	v_pk_add_f32 v[106:107], v[106:107], v[216:217]
	v_pk_add_f32 v[108:109], v[108:109], v[252:253]
	v_lshlrev_b32_e32 v216, 16, v254
	v_and_b32_e32 v217, 0xffff0000, v254
	v_lshlrev_b32_e32 v254, 16, v255
	v_and_b32_e32 v255, 0xffff0000, v255
	v_pk_add_f32 v[218:219], v[218:219], v[216:217]
	v_pk_add_f32 v[220:221], v[220:221], v[254:255]
	ds_read_b128 v[252:255], v163 offset:3328
	v_fma_f32 v106, v159, v106, -v98
	v_fma_f32 v107, v159, v107, -v99
	v_fma_f32 v108, v159, v108, -v100
	v_fma_f32 v109, v159, v109, -v101
	v_fma_f32 v218, v159, v218, -v102
	v_fma_f32 v219, v159, v219, -v103
	v_fma_f32 v220, v159, v220, -v104
	v_fma_f32 v221, v159, v221, -v105
	v_cvt_pk_bf16_f32 v106, v106, v107
	v_cvt_pk_bf16_f32 v107, v108, v109
	v_cvt_pk_bf16_f32 v108, v218, v219
	v_cvt_pk_bf16_f32 v109, v220, v221
	s_and_saveexec_b64 s[28:29], s[6:7]
	s_cbranch_execz .Lpu2_1
	global_store_dwordx4 v[190:191], v[98:101], off offset:64
	global_store_dwordx4 v[190:191], v[102:105], off offset:80
.Lpu2_1:
	s_or_b64 exec, exec, s[28:29]
	s_waitcnt vmcnt(8)
	v_mfma_f32_32x32x16_bf16 v[2:17], v[106:109], v[82:85], v[2:17]
	v_mfma_f32_32x32x16_bf16 v[18:33], v[106:109], v[86:89], v[18:33]
	v_mfma_f32_32x32x16_bf16 v[34:49], v[106:109], v[90:93], v[34:49]
	v_mfma_f32_32x32x16_bf16 v[50:65], v[106:109], v[94:97], v[50:65]
	global_load_dwordx4 v[82:85], v[122:123], off offset:2048
	global_load_dwordx4 v[86:89], v[124:125], off offset:2048
	global_load_dwordx4 v[90:93], v[126:127], off offset:2048
	global_load_dwordx4 v[94:97], v[128:129], off offset:2048
	s_waitcnt lgkmcnt(3)
	v_lshlrev_b32_e32 v98, 16, v238
	v_and_b32_e32 v99, 0xffff0000, v238
	v_lshlrev_b32_e32 v100, 16, v239
	v_and_b32_e32 v101, 0xffff0000, v239
	v_lshlrev_b32_e32 v102, 16, v240
	v_and_b32_e32 v103, 0xffff0000, v240
	v_lshlrev_b32_e32 v104, 16, v241
	v_and_b32_e32 v105, 0xffff0000, v241
	ds_read_b128 v[238:241], v163 offset:4176
	s_waitcnt lgkmcnt(3)
	v_lshlrev_b32_e32 v216, 16, v242
	v_and_b32_e32 v217, 0xffff0000, v242
	v_lshlrev_b32_e32 v242, 16, v243
	v_and_b32_e32 v243, 0xffff0000, v243
	v_pk_add_f32 v[106:107], v[98:99], v[216:217]
	v_pk_add_f32 v[108:109], v[100:101], v[242:243]
	v_lshlrev_b32_e32 v216, 16, v244
	v_and_b32_e32 v217, 0xffff0000, v244
	v_lshlrev_b32_e32 v244, 16, v245
	v_and_b32_e32 v245, 0xffff0000, v245
	v_pk_add_f32 v[218:219], v[102:103], v[216:217]
	v_pk_add_f32 v[220:221], v[104:105], v[244:245]
	ds_read_b128 v[242:245], v163 offset:3904
	s_waitcnt lgkmcnt(3)
	v_lshlrev_b32_e32 v216, 16, v248
	v_and_b32_e32 v217, 0xffff0000, v248
	v_lshlrev_b32_e32 v248, 16, v249
	v_and_b32_e32 v249, 0xffff0000, v249
	v_pk_add_f32 v[106:107], v[106:107], v[216:217]
	v_pk_add_f32 v[108:109], v[108:109], v[248:249]
	v_lshlrev_b32_e32 v216, 16, v250
	v_and_b32_e32 v217, 0xffff0000, v250
	v_lshlrev_b32_e32 v250, 16, v251
	v_and_b32_e32 v251, 0xffff0000, v251
	v_pk_add_f32 v[218:219], v[218:219], v[216:217]
	v_pk_add_f32 v[220:221], v[220:221], v[250:251]
	ds_read_b128 v[248:251], v163 offset:3632
	s_waitcnt lgkmcnt(3)
	v_lshlrev_b32_e32 v216, 16, v252
	v_and_b32_e32 v217, 0xffff0000, v252
	v_lshlrev_b32_e32 v252, 16, v253
	v_and_b32_e32 v253, 0xffff0000, v253
	v_pk_add_f32 v[106:107], v[106:107], v[216:217]
	v_pk_add_f32 v[108:109], v[108:109], v[252:253]
	v_lshlrev_b32_e32 v216, 16, v254
	v_and_b32_e32 v217, 0xffff0000, v254
	v_lshlrev_b32_e32 v254, 16, v255
	v_and_b32_e32 v255, 0xffff0000, v255
	v_pk_add_f32 v[218:219], v[218:219], v[216:217]
	v_pk_add_f32 v[220:221], v[220:221], v[254:255]
	ds_read_b128 v[252:255], v163 offset:3360
	v_fma_f32 v106, v159, v106, -v98
	v_fma_f32 v107, v159, v107, -v99
	v_fma_f32 v108, v159, v108, -v100
	v_fma_f32 v109, v159, v109, -v101
	v_fma_f32 v218, v159, v218, -v102
	v_fma_f32 v219, v159, v219, -v103
	v_fma_f32 v220, v159, v220, -v104
	v_fma_f32 v221, v159, v221, -v105
	v_cvt_pk_bf16_f32 v106, v106, v107
	v_cvt_pk_bf16_f32 v107, v108, v109
	v_cvt_pk_bf16_f32 v108, v218, v219
	v_cvt_pk_bf16_f32 v109, v220, v221
	s_and_saveexec_b64 s[28:29], s[6:7]
	s_cbranch_execz .Lpu2_2
	global_store_dwordx4 v[190:191], v[98:101], off offset:128
	global_store_dwordx4 v[190:191], v[102:105], off offset:144
.Lpu2_2:
	s_or_b64 exec, exec, s[28:29]
	s_waitcnt vmcnt(8)
	v_mfma_f32_32x32x16_bf16 v[2:17], v[106:109], v[222:225], v[2:17]
	v_mfma_f32_32x32x16_bf16 v[18:33], v[106:109], v[226:229], v[18:33]
	v_mfma_f32_32x32x16_bf16 v[34:49], v[106:109], v[230:233], v[34:49]
	v_mfma_f32_32x32x16_bf16 v[50:65], v[106:109], v[234:237], v[50:65]
	global_load_dwordx4 v[222:225], v[122:123], off offset:2560
	global_load_dwordx4 v[226:229], v[124:125], off offset:2560
	global_load_dwordx4 v[230:233], v[126:127], off offset:2560
	global_load_dwordx4 v[234:237], v[128:129], off offset:2560
	s_waitcnt lgkmcnt(3)
	v_lshlrev_b32_e32 v98, 16, v238
	v_and_b32_e32 v99, 0xffff0000, v238
	v_lshlrev_b32_e32 v100, 16, v239
	v_and_b32_e32 v101, 0xffff0000, v239
	v_lshlrev_b32_e32 v102, 16, v240
	v_and_b32_e32 v103, 0xffff0000, v240
	v_lshlrev_b32_e32 v104, 16, v241
	v_and_b32_e32 v105, 0xffff0000, v241
	ds_read_b128 v[238:241], v163 offset:4208
	s_waitcnt lgkmcnt(3)
	v_lshlrev_b32_e32 v216, 16, v242
	v_and_b32_e32 v217, 0xffff0000, v242
	v_lshlrev_b32_e32 v242, 16, v243
	v_and_b32_e32 v243, 0xffff0000, v243
	v_pk_add_f32 v[106:107], v[98:99], v[216:217]
	v_pk_add_f32 v[108:109], v[100:101], v[242:243]
	v_lshlrev_b32_e32 v216, 16, v244
	v_and_b32_e32 v217, 0xffff0000, v244
	v_lshlrev_b32_e32 v244, 16, v245
	v_and_b32_e32 v245, 0xffff0000, v245
	v_pk_add_f32 v[218:219], v[102:103], v[216:217]
	v_pk_add_f32 v[220:221], v[104:105], v[244:245]
	ds_read_b128 v[242:245], v163 offset:3936
	s_waitcnt lgkmcnt(3)
	v_lshlrev_b32_e32 v216, 16, v248
	v_and_b32_e32 v217, 0xffff0000, v248
	v_lshlrev_b32_e32 v248, 16, v249
	v_and_b32_e32 v249, 0xffff0000, v249
	v_pk_add_f32 v[106:107], v[106:107], v[216:217]
	v_pk_add_f32 v[108:109], v[108:109], v[248:249]
	v_lshlrev_b32_e32 v216, 16, v250
	v_and_b32_e32 v217, 0xffff0000, v250
	v_lshlrev_b32_e32 v250, 16, v251
	v_and_b32_e32 v251, 0xffff0000, v251
	v_pk_add_f32 v[218:219], v[218:219], v[216:217]
	v_pk_add_f32 v[220:221], v[220:221], v[250:251]
	ds_read_b128 v[248:251], v163 offset:3664
	s_waitcnt lgkmcnt(3)
	v_lshlrev_b32_e32 v216, 16, v252
	v_and_b32_e32 v217, 0xffff0000, v252
	v_lshlrev_b32_e32 v252, 16, v253
	v_and_b32_e32 v253, 0xffff0000, v253
	v_pk_add_f32 v[106:107], v[106:107], v[216:217]
	v_pk_add_f32 v[108:109], v[108:109], v[252:253]
	v_lshlrev_b32_e32 v216, 16, v254
	v_and_b32_e32 v217, 0xffff0000, v254
	v_lshlrev_b32_e32 v254, 16, v255
	v_and_b32_e32 v255, 0xffff0000, v255
	v_pk_add_f32 v[218:219], v[218:219], v[216:217]
	v_pk_add_f32 v[220:221], v[220:221], v[254:255]
	ds_read_b128 v[252:255], v163 offset:3392
	v_fma_f32 v106, v159, v106, -v98
	v_fma_f32 v107, v159, v107, -v99
	v_fma_f32 v108, v159, v108, -v100
	v_fma_f32 v109, v159, v109, -v101
	v_fma_f32 v218, v159, v218, -v102
	v_fma_f32 v219, v159, v219, -v103
	v_fma_f32 v220, v159, v220, -v104
	v_fma_f32 v221, v159, v221, -v105
	v_cvt_pk_bf16_f32 v106, v106, v107
	v_cvt_pk_bf16_f32 v107, v108, v109
	v_cvt_pk_bf16_f32 v108, v218, v219
	v_cvt_pk_bf16_f32 v109, v220, v221
	s_and_saveexec_b64 s[28:29], s[6:7]
	s_cbranch_execz .Lpu2_3
	global_store_dwordx4 v[190:191], v[98:101], off offset:192
	global_store_dwordx4 v[190:191], v[102:105], off offset:208
.Lpu2_3:
	s_or_b64 exec, exec, s[28:29]
	s_waitcnt vmcnt(8)
	v_mfma_f32_32x32x16_bf16 v[2:17], v[106:109], v[70:73], v[2:17]
	v_mfma_f32_32x32x16_bf16 v[18:33], v[106:109], v[74:77], v[18:33]
	v_mfma_f32_32x32x16_bf16 v[34:49], v[106:109], v[78:81], v[34:49]
	v_mfma_f32_32x32x16_bf16 v[50:65], v[106:109], v[66:69], v[50:65]
	global_load_dwordx4 v[70:73], v[122:123], off offset:3072
	global_load_dwordx4 v[74:77], v[124:125], off offset:3072
	global_load_dwordx4 v[78:81], v[126:127], off offset:3072
	global_load_dwordx4 v[66:69], v[128:129], off offset:3072
	s_waitcnt lgkmcnt(3)
	v_lshlrev_b32_e32 v98, 16, v238
	v_and_b32_e32 v99, 0xffff0000, v238
	v_lshlrev_b32_e32 v100, 16, v239
	v_and_b32_e32 v101, 0xffff0000, v239
	v_lshlrev_b32_e32 v102, 16, v240
	v_and_b32_e32 v103, 0xffff0000, v240
	v_lshlrev_b32_e32 v104, 16, v241
	v_and_b32_e32 v105, 0xffff0000, v241
	ds_read_b128 v[238:241], v163 offset:4240
	s_waitcnt lgkmcnt(3)
	v_lshlrev_b32_e32 v216, 16, v242
	v_and_b32_e32 v217, 0xffff0000, v242
	v_lshlrev_b32_e32 v242, 16, v243
	v_and_b32_e32 v243, 0xffff0000, v243
	v_pk_add_f32 v[106:107], v[98:99], v[216:217]
	v_pk_add_f32 v[108:109], v[100:101], v[242:243]
	v_lshlrev_b32_e32 v216, 16, v244
	v_and_b32_e32 v217, 0xffff0000, v244
	v_lshlrev_b32_e32 v244, 16, v245
	v_and_b32_e32 v245, 0xffff0000, v245
	v_pk_add_f32 v[218:219], v[102:103], v[216:217]
	v_pk_add_f32 v[220:221], v[104:105], v[244:245]
	ds_read_b128 v[242:245], v163 offset:3968
	s_waitcnt lgkmcnt(3)
	v_lshlrev_b32_e32 v216, 16, v248
	v_and_b32_e32 v217, 0xffff0000, v248
	v_lshlrev_b32_e32 v248, 16, v249
	v_and_b32_e32 v249, 0xffff0000, v249
	v_pk_add_f32 v[106:107], v[106:107], v[216:217]
	v_pk_add_f32 v[108:109], v[108:109], v[248:249]
	v_lshlrev_b32_e32 v216, 16, v250
	v_and_b32_e32 v217, 0xffff0000, v250
	v_lshlrev_b32_e32 v250, 16, v251
	v_and_b32_e32 v251, 0xffff0000, v251
	v_pk_add_f32 v[218:219], v[218:219], v[216:217]
	v_pk_add_f32 v[220:221], v[220:221], v[250:251]
	ds_read_b128 v[248:251], v163 offset:3696
	s_waitcnt lgkmcnt(3)
	v_lshlrev_b32_e32 v216, 16, v252
	v_and_b32_e32 v217, 0xffff0000, v252
	v_lshlrev_b32_e32 v252, 16, v253
	v_and_b32_e32 v253, 0xffff0000, v253
	v_pk_add_f32 v[106:107], v[106:107], v[216:217]
	v_pk_add_f32 v[108:109], v[108:109], v[252:253]
	v_lshlrev_b32_e32 v216, 16, v254
	v_and_b32_e32 v217, 0xffff0000, v254
	v_lshlrev_b32_e32 v254, 16, v255
	v_and_b32_e32 v255, 0xffff0000, v255
	v_pk_add_f32 v[218:219], v[218:219], v[216:217]
	v_pk_add_f32 v[220:221], v[220:221], v[254:255]
	ds_read_b128 v[252:255], v163 offset:3424
	v_fma_f32 v106, v159, v106, -v98
	v_fma_f32 v107, v159, v107, -v99
	v_fma_f32 v108, v159, v108, -v100
	v_fma_f32 v109, v159, v109, -v101
	v_fma_f32 v218, v159, v218, -v102
	v_fma_f32 v219, v159, v219, -v103
	v_fma_f32 v220, v159, v220, -v104
	v_fma_f32 v221, v159, v221, -v105
	v_cvt_pk_bf16_f32 v106, v106, v107
	v_cvt_pk_bf16_f32 v107, v108, v109
	v_cvt_pk_bf16_f32 v108, v218, v219
	v_cvt_pk_bf16_f32 v109, v220, v221
	s_and_saveexec_b64 s[28:29], s[6:7]
	s_cbranch_execz .Lpu2_4
	global_store_dwordx4 v[190:191], v[98:101], off offset:256
	global_store_dwordx4 v[190:191], v[102:105], off offset:272
.Lpu2_4:
	s_or_b64 exec, exec, s[28:29]
	s_waitcnt vmcnt(8)
	v_mfma_f32_32x32x16_bf16 v[2:17], v[106:109], v[82:85], v[2:17]
	v_mfma_f32_32x32x16_bf16 v[18:33], v[106:109], v[86:89], v[18:33]
	v_mfma_f32_32x32x16_bf16 v[34:49], v[106:109], v[90:93], v[34:49]
	v_mfma_f32_32x32x16_bf16 v[50:65], v[106:109], v[94:97], v[50:65]
	global_load_dwordx4 v[82:85], v[122:123], off offset:3584
	global_load_dwordx4 v[86:89], v[124:125], off offset:3584
	global_load_dwordx4 v[90:93], v[126:127], off offset:3584
	global_load_dwordx4 v[94:97], v[128:129], off offset:3584
	s_waitcnt lgkmcnt(3)
	v_lshlrev_b32_e32 v98, 16, v238
	v_and_b32_e32 v99, 0xffff0000, v238
	v_lshlrev_b32_e32 v100, 16, v239
	v_and_b32_e32 v101, 0xffff0000, v239
	v_lshlrev_b32_e32 v102, 16, v240
	v_and_b32_e32 v103, 0xffff0000, v240
	v_lshlrev_b32_e32 v104, 16, v241
	v_and_b32_e32 v105, 0xffff0000, v241
	ds_read_b128 v[238:241], v163 offset:4272
	s_waitcnt lgkmcnt(3)
	v_lshlrev_b32_e32 v216, 16, v242
	v_and_b32_e32 v217, 0xffff0000, v242
	v_lshlrev_b32_e32 v242, 16, v243
	v_and_b32_e32 v243, 0xffff0000, v243
	v_pk_add_f32 v[106:107], v[98:99], v[216:217]
	v_pk_add_f32 v[108:109], v[100:101], v[242:243]
	v_lshlrev_b32_e32 v216, 16, v244
	v_and_b32_e32 v217, 0xffff0000, v244
	v_lshlrev_b32_e32 v244, 16, v245
	v_and_b32_e32 v245, 0xffff0000, v245
	v_pk_add_f32 v[218:219], v[102:103], v[216:217]
	v_pk_add_f32 v[220:221], v[104:105], v[244:245]
	ds_read_b128 v[242:245], v163 offset:4000
	s_waitcnt lgkmcnt(3)
	v_lshlrev_b32_e32 v216, 16, v248
	v_and_b32_e32 v217, 0xffff0000, v248
	v_lshlrev_b32_e32 v248, 16, v249
	v_and_b32_e32 v249, 0xffff0000, v249
	v_pk_add_f32 v[106:107], v[106:107], v[216:217]
	v_pk_add_f32 v[108:109], v[108:109], v[248:249]
	v_lshlrev_b32_e32 v216, 16, v250
	v_and_b32_e32 v217, 0xffff0000, v250
	v_lshlrev_b32_e32 v250, 16, v251
	v_and_b32_e32 v251, 0xffff0000, v251
	v_pk_add_f32 v[218:219], v[218:219], v[216:217]
	v_pk_add_f32 v[220:221], v[220:221], v[250:251]
	ds_read_b128 v[248:251], v163 offset:3728
	s_waitcnt lgkmcnt(3)
	v_lshlrev_b32_e32 v216, 16, v252
	v_and_b32_e32 v217, 0xffff0000, v252
	v_lshlrev_b32_e32 v252, 16, v253
	v_and_b32_e32 v253, 0xffff0000, v253
	v_pk_add_f32 v[106:107], v[106:107], v[216:217]
	v_pk_add_f32 v[108:109], v[108:109], v[252:253]
	v_lshlrev_b32_e32 v216, 16, v254
	v_and_b32_e32 v217, 0xffff0000, v254
	v_lshlrev_b32_e32 v254, 16, v255
	v_and_b32_e32 v255, 0xffff0000, v255
	v_pk_add_f32 v[218:219], v[218:219], v[216:217]
	v_pk_add_f32 v[220:221], v[220:221], v[254:255]
	ds_read_b128 v[252:255], v163 offset:3456
	v_fma_f32 v106, v159, v106, -v98
	v_fma_f32 v107, v159, v107, -v99
	v_fma_f32 v108, v159, v108, -v100
	v_fma_f32 v109, v159, v109, -v101
	v_fma_f32 v218, v159, v218, -v102
	v_fma_f32 v219, v159, v219, -v103
	v_fma_f32 v220, v159, v220, -v104
	v_fma_f32 v221, v159, v221, -v105
	v_cvt_pk_bf16_f32 v106, v106, v107
	v_cvt_pk_bf16_f32 v107, v108, v109
	v_cvt_pk_bf16_f32 v108, v218, v219
	v_cvt_pk_bf16_f32 v109, v220, v221
	s_and_saveexec_b64 s[28:29], s[6:7]
	s_cbranch_execz .Lpu2_5
	global_store_dwordx4 v[190:191], v[98:101], off offset:320
	global_store_dwordx4 v[190:191], v[102:105], off offset:336
.Lpu2_5:
	s_or_b64 exec, exec, s[28:29]
	s_waitcnt vmcnt(8)
	v_mfma_f32_32x32x16_bf16 v[2:17], v[106:109], v[222:225], v[2:17]
	v_mfma_f32_32x32x16_bf16 v[18:33], v[106:109], v[226:229], v[18:33]
	v_mfma_f32_32x32x16_bf16 v[34:49], v[106:109], v[230:233], v[34:49]
	v_mfma_f32_32x32x16_bf16 v[50:65], v[106:109], v[234:237], v[50:65]
	s_waitcnt lgkmcnt(3)
	v_lshlrev_b32_e32 v98, 16, v238
	v_and_b32_e32 v99, 0xffff0000, v238
	v_lshlrev_b32_e32 v100, 16, v239
	v_and_b32_e32 v101, 0xffff0000, v239
	v_lshlrev_b32_e32 v102, 16, v240
	v_and_b32_e32 v103, 0xffff0000, v240
	v_lshlrev_b32_e32 v104, 16, v241
	v_and_b32_e32 v105, 0xffff0000, v241
	ds_read_b128 v[238:241], v163 offset:4304
	s_waitcnt lgkmcnt(3)
	v_lshlrev_b32_e32 v216, 16, v242
	v_and_b32_e32 v217, 0xffff0000, v242
	v_lshlrev_b32_e32 v242, 16, v243
	v_and_b32_e32 v243, 0xffff0000, v243
	v_pk_add_f32 v[106:107], v[98:99], v[216:217]
	v_pk_add_f32 v[108:109], v[100:101], v[242:243]
	v_lshlrev_b32_e32 v216, 16, v244
	v_and_b32_e32 v217, 0xffff0000, v244
	v_lshlrev_b32_e32 v244, 16, v245
	v_and_b32_e32 v245, 0xffff0000, v245
	v_pk_add_f32 v[218:219], v[102:103], v[216:217]
	v_pk_add_f32 v[220:221], v[104:105], v[244:245]
	ds_read_b128 v[242:245], v163 offset:4032
	s_waitcnt lgkmcnt(3)
	v_lshlrev_b32_e32 v216, 16, v248
	v_and_b32_e32 v217, 0xffff0000, v248
	v_lshlrev_b32_e32 v248, 16, v249
	v_and_b32_e32 v249, 0xffff0000, v249
	v_pk_add_f32 v[106:107], v[106:107], v[216:217]
	v_pk_add_f32 v[108:109], v[108:109], v[248:249]
	v_lshlrev_b32_e32 v216, 16, v250
	v_and_b32_e32 v217, 0xffff0000, v250
	v_lshlrev_b32_e32 v250, 16, v251
	v_and_b32_e32 v251, 0xffff0000, v251
	v_pk_add_f32 v[218:219], v[218:219], v[216:217]
	v_pk_add_f32 v[220:221], v[220:221], v[250:251]
	ds_read_b128 v[248:251], v163 offset:3760
	s_waitcnt lgkmcnt(3)
	v_lshlrev_b32_e32 v216, 16, v252
	v_and_b32_e32 v217, 0xffff0000, v252
	v_lshlrev_b32_e32 v252, 16, v253
	v_and_b32_e32 v253, 0xffff0000, v253
	v_pk_add_f32 v[106:107], v[106:107], v[216:217]
	v_pk_add_f32 v[108:109], v[108:109], v[252:253]
	v_lshlrev_b32_e32 v216, 16, v254
	v_and_b32_e32 v217, 0xffff0000, v254
	v_lshlrev_b32_e32 v254, 16, v255
	v_and_b32_e32 v255, 0xffff0000, v255
	v_pk_add_f32 v[218:219], v[218:219], v[216:217]
	v_pk_add_f32 v[220:221], v[220:221], v[254:255]
	ds_read_b128 v[252:255], v163 offset:3488
	v_fma_f32 v106, v159, v106, -v98
	v_fma_f32 v107, v159, v107, -v99
	v_fma_f32 v108, v159, v108, -v100
	v_fma_f32 v109, v159, v109, -v101
	v_fma_f32 v218, v159, v218, -v102
	v_fma_f32 v219, v159, v219, -v103
	v_fma_f32 v220, v159, v220, -v104
	v_fma_f32 v221, v159, v221, -v105
	v_cvt_pk_bf16_f32 v106, v106, v107
	v_cvt_pk_bf16_f32 v107, v108, v109
	v_cvt_pk_bf16_f32 v108, v218, v219
	v_cvt_pk_bf16_f32 v109, v220, v221
	s_and_saveexec_b64 s[28:29], s[6:7]
	s_cbranch_execz .Lpu2_6
	global_store_dwordx4 v[190:191], v[98:101], off offset:384
	global_store_dwordx4 v[190:191], v[102:105], off offset:400
.Lpu2_6:
	s_or_b64 exec, exec, s[28:29]
	s_waitcnt vmcnt(4)
	v_mfma_f32_32x32x16_bf16 v[2:17], v[106:109], v[70:73], v[2:17]
	v_mfma_f32_32x32x16_bf16 v[18:33], v[106:109], v[74:77], v[18:33]
	v_mfma_f32_32x32x16_bf16 v[34:49], v[106:109], v[78:81], v[34:49]
	v_mfma_f32_32x32x16_bf16 v[50:65], v[106:109], v[66:69], v[50:65]
	s_waitcnt lgkmcnt(3)
	v_lshlrev_b32_e32 v98, 16, v238
	v_and_b32_e32 v99, 0xffff0000, v238
	v_lshlrev_b32_e32 v100, 16, v239
	v_and_b32_e32 v101, 0xffff0000, v239
	v_lshlrev_b32_e32 v102, 16, v240
	v_and_b32_e32 v103, 0xffff0000, v240
	v_lshlrev_b32_e32 v104, 16, v241
	v_and_b32_e32 v105, 0xffff0000, v241
	s_waitcnt lgkmcnt(2)
	v_lshlrev_b32_e32 v216, 16, v242
	v_and_b32_e32 v217, 0xffff0000, v242
	v_lshlrev_b32_e32 v242, 16, v243
	v_and_b32_e32 v243, 0xffff0000, v243
	v_pk_add_f32 v[106:107], v[98:99], v[216:217]
	v_pk_add_f32 v[108:109], v[100:101], v[242:243]
	v_lshlrev_b32_e32 v216, 16, v244
	v_and_b32_e32 v217, 0xffff0000, v244
	v_lshlrev_b32_e32 v244, 16, v245
	v_and_b32_e32 v245, 0xffff0000, v245
	v_pk_add_f32 v[218:219], v[102:103], v[216:217]
	v_pk_add_f32 v[220:221], v[104:105], v[244:245]
	s_waitcnt lgkmcnt(1)
	v_lshlrev_b32_e32 v216, 16, v248
	v_and_b32_e32 v217, 0xffff0000, v248
	v_lshlrev_b32_e32 v248, 16, v249
	v_and_b32_e32 v249, 0xffff0000, v249
	v_pk_add_f32 v[106:107], v[106:107], v[216:217]
	v_pk_add_f32 v[108:109], v[108:109], v[248:249]
	v_lshlrev_b32_e32 v216, 16, v250
	v_and_b32_e32 v217, 0xffff0000, v250
	v_lshlrev_b32_e32 v250, 16, v251
	v_and_b32_e32 v251, 0xffff0000, v251
	v_pk_add_f32 v[218:219], v[218:219], v[216:217]
	v_pk_add_f32 v[220:221], v[220:221], v[250:251]
	s_waitcnt lgkmcnt(0)
	v_lshlrev_b32_e32 v216, 16, v252
	v_and_b32_e32 v217, 0xffff0000, v252
	v_lshlrev_b32_e32 v252, 16, v253
	v_and_b32_e32 v253, 0xffff0000, v253
	v_pk_add_f32 v[106:107], v[106:107], v[216:217]
	v_pk_add_f32 v[108:109], v[108:109], v[252:253]
	v_lshlrev_b32_e32 v216, 16, v254
	v_and_b32_e32 v217, 0xffff0000, v254
	v_lshlrev_b32_e32 v254, 16, v255
	v_and_b32_e32 v255, 0xffff0000, v255
	v_pk_add_f32 v[218:219], v[218:219], v[216:217]
	v_pk_add_f32 v[220:221], v[220:221], v[254:255]
	v_fma_f32 v106, v159, v106, -v98
	v_fma_f32 v107, v159, v107, -v99
	v_fma_f32 v108, v159, v108, -v100
	v_fma_f32 v109, v159, v109, -v101
	v_fma_f32 v218, v159, v218, -v102
	v_fma_f32 v219, v159, v219, -v103
	v_fma_f32 v220, v159, v220, -v104
	v_fma_f32 v221, v159, v221, -v105
	v_cvt_pk_bf16_f32 v106, v106, v107
	v_cvt_pk_bf16_f32 v107, v108, v109
	v_cvt_pk_bf16_f32 v108, v218, v219
	v_cvt_pk_bf16_f32 v109, v220, v221
	s_and_saveexec_b64 s[28:29], s[6:7]
	s_cbranch_execz .Lpu2_7
	global_store_dwordx4 v[190:191], v[98:101], off offset:448
	global_store_dwordx4 v[190:191], v[102:105], off offset:464

.LBB0_403:
	s_or_b64 exec, exec, s[2:3]
	s_waitcnt lgkmcnt(0)
	global_load_dwordx4 v[82:85], v[110:111], off offset:512
	global_load_dwordx4 v[86:89], v[134:135], off offset:512
	global_load_dwordx4 v[90:93], v[136:137], off offset:512
	global_load_dwordx4 v[94:97], v[138:139], off offset:512
	global_load_dwordx4 v[222:225], v[110:111], off offset:1024
	global_load_dwordx4 v[226:229], v[134:135], off offset:1024
	global_load_dwordx4 v[230:233], v[136:137], off offset:1024
	global_load_dwordx4 v[234:237], v[138:139], off offset:1024
	s_ashr_i32 s2, s30, 6
	v_or_b32_e32 v2, s28, v1
	s_mul_i32 s2, s2, 15
	v_cmp_eq_u32_e32 vcc, 0, v2
	v_cmp_lt_u32_e64 s[6:7], s41, v2
	s_ashr_i32 s3, s2, 31
	v_add_u32_e32 v2, 0xfffff80f, v2
	v_mov_b32_e32 v3, v155
	v_lshl_add_u64 v[2:3], v[2:3], 0, s[2:3]
	v_lshlrev_b64 v[2:3], 11, v[2:3]
	v_lshl_add_u64 v[184:185], v[140:141], 0, v[2:3]
	v_mov_b32_e32 v2, 0
	s_mov_b32 s28, 0
	v_cndmask_b32_e64 v159, 0.5, 1.0, vcc
	s_mov_b64 s[2:3], 0
	v_mov_b32_e32 v3, v2
	v_mov_b32_e32 v4, v2
	v_mov_b32_e32 v5, v2
	v_mov_b32_e32 v6, v2
	v_mov_b32_e32 v7, v2
	v_mov_b32_e32 v8, v2
	v_mov_b32_e32 v9, v2
	v_mov_b32_e32 v10, v2
	v_mov_b32_e32 v11, v2
	v_mov_b32_e32 v12, v2
	v_mov_b32_e32 v13, v2
	v_mov_b32_e32 v14, v2
	v_mov_b32_e32 v15, v2
	v_mov_b32_e32 v16, v2
	v_mov_b32_e32 v17, v2
	v_mov_b32_e32 v18, v2
	v_mov_b32_e32 v19, v2
	v_mov_b32_e32 v20, v2
	v_mov_b32_e32 v21, v2
	v_mov_b32_e32 v22, v2
	v_mov_b32_e32 v23, v2
	v_mov_b32_e32 v24, v2
	v_mov_b32_e32 v25, v2
	v_mov_b32_e32 v26, v2
	v_mov_b32_e32 v27, v2
	v_mov_b32_e32 v28, v2
	v_mov_b32_e32 v29, v2
	v_mov_b32_e32 v30, v2
	v_mov_b32_e32 v31, v2
	v_mov_b32_e32 v32, v2
	v_mov_b32_e32 v33, v2
	v_mov_b32_e32 v34, v2
	v_mov_b32_e32 v35, v2
	v_mov_b32_e32 v36, v2
	v_mov_b32_e32 v37, v2
	v_mov_b32_e32 v38, v2
	v_mov_b32_e32 v39, v2
	v_mov_b32_e32 v40, v2
	v_mov_b32_e32 v41, v2
	v_mov_b32_e32 v42, v2
	v_mov_b32_e32 v43, v2
	v_mov_b32_e32 v44, v2
	v_mov_b32_e32 v45, v2
	v_mov_b32_e32 v46, v2
	v_mov_b32_e32 v47, v2
	v_mov_b32_e32 v48, v2
	v_mov_b32_e32 v49, v2
	v_mov_b32_e32 v50, v2
	v_mov_b32_e32 v51, v2
	v_mov_b32_e32 v52, v2
	v_mov_b32_e32 v53, v2
	v_mov_b32_e32 v54, v2
	v_mov_b32_e32 v55, v2
	v_mov_b32_e32 v56, v2
	v_mov_b32_e32 v57, v2
	v_mov_b32_e32 v58, v2
	v_mov_b32_e32 v59, v2
	v_mov_b32_e32 v60, v2
	v_mov_b32_e32 v61, v2
	v_mov_b32_e32 v62, v2
	v_mov_b32_e32 v63, v2
	v_mov_b32_e32 v64, v2
	v_mov_b32_e32 v65, v2
	v_lshl_add_u32 v163, v197, 1, v214
	ds_read_b128 v[238:241], v163 offset:4080
	ds_read_b128 v[242:245], v163 offset:3808
	ds_read_b128 v[248:251], v163 offset:4112
	ds_read_b128 v[252:255], v163 offset:3840
	s_waitcnt lgkmcnt(3)
	v_lshlrev_b32_e32 v98, 16, v238
	v_and_b32_e32 v99, 0xffff0000, v238
	v_lshlrev_b32_e32 v100, 16, v239
	v_and_b32_e32 v101, 0xffff0000, v239
	v_lshlrev_b32_e32 v102, 16, v240
	v_and_b32_e32 v103, 0xffff0000, v240
	v_lshlrev_b32_e32 v104, 16, v241
	v_and_b32_e32 v105, 0xffff0000, v241
	ds_read_b128 v[238:241], v163 offset:4144
	s_waitcnt lgkmcnt(3)
	v_lshlrev_b32_e32 v216, 16, v242
	v_and_b32_e32 v217, 0xffff0000, v242
	v_lshlrev_b32_e32 v242, 16, v243
	v_and_b32_e32 v243, 0xffff0000, v243
	v_pk_add_f32 v[106:107], v[98:99], v[216:217]
	v_pk_add_f32 v[108:109], v[100:101], v[242:243]
	v_lshlrev_b32_e32 v216, 16, v244
	v_and_b32_e32 v217, 0xffff0000, v244
	v_lshlrev_b32_e32 v244, 16, v245
	v_and_b32_e32 v245, 0xffff0000, v245
	v_pk_add_f32 v[218:219], v[102:103], v[216:217]
	v_pk_add_f32 v[220:221], v[104:105], v[244:245]
	ds_read_b128 v[242:245], v163 offset:3872
	v_fma_f32 v106, v159, v106, -v98
	v_fma_f32 v107, v159, v107, -v99
	v_fma_f32 v108, v159, v108, -v100
	v_fma_f32 v109, v159, v109, -v101
	v_fma_f32 v218, v159, v218, -v102
	v_fma_f32 v219, v159, v219, -v103
	v_fma_f32 v220, v159, v220, -v104
	v_fma_f32 v221, v159, v221, -v105
	v_cvt_pk_bf16_f32 v106, v106, v107
	v_cvt_pk_bf16_f32 v107, v108, v109
	v_cvt_pk_bf16_f32 v108, v218, v219
	v_cvt_pk_bf16_f32 v109, v220, v221
	s_and_saveexec_b64 s[10:11], s[6:7]
	s_cbranch_execz .Lpu3_0
	global_store_dwordx4 v[184:185], v[98:101], off offset:0
	global_store_dwordx4 v[184:185], v[102:105], off offset:16
.Lpu3_0:
	s_or_b64 exec, exec, s[10:11]
	s_waitcnt vmcnt(8)
	v_mfma_f32_32x32x16_bf16 v[2:17], v[106:109], v[70:73], v[2:17]
	v_mfma_f32_32x32x16_bf16 v[18:33], v[106:109], v[74:77], v[18:33]
	v_mfma_f32_32x32x16_bf16 v[34:49], v[106:109], v[78:81], v[34:49]
	v_mfma_f32_32x32x16_bf16 v[50:65], v[106:109], v[66:69], v[50:65]
	global_load_dwordx4 v[70:73], v[110:111], off offset:1536
	global_load_dwordx4 v[74:77], v[134:135], off offset:1536
	global_load_dwordx4 v[78:81], v[136:137], off offset:1536
	global_load_dwordx4 v[66:69], v[138:139], off offset:1536
	s_waitcnt lgkmcnt(3)
	v_lshlrev_b32_e32 v98, 16, v248
	v_and_b32_e32 v99, 0xffff0000, v248
	v_lshlrev_b32_e32 v100, 16, v249
	v_and_b32_e32 v101, 0xffff0000, v249
	v_lshlrev_b32_e32 v102, 16, v250
	v_and_b32_e32 v103, 0xffff0000, v250
	v_lshlrev_b32_e32 v104, 16, v251
	v_and_b32_e32 v105, 0xffff0000, v251
	ds_read_b128 v[248:251], v163 offset:4176
	s_waitcnt lgkmcnt(3)
	v_lshlrev_b32_e32 v216, 16, v252
	v_and_b32_e32 v217, 0xffff0000, v252
	v_lshlrev_b32_e32 v252, 16, v253
	v_and_b32_e32 v253, 0xffff0000, v253
	v_pk_add_f32 v[106:107], v[98:99], v[216:217]
	v_pk_add_f32 v[108:109], v[100:101], v[252:253]
	v_lshlrev_b32_e32 v216, 16, v254
	v_and_b32_e32 v217, 0xffff0000, v254
	v_lshlrev_b32_e32 v254, 16, v255
	v_and_b32_e32 v255, 0xffff0000, v255
	v_pk_add_f32 v[218:219], v[102:103], v[216:217]
	v_pk_add_f32 v[220:221], v[104:105], v[254:255]
	ds_read_b128 v[252:255], v163 offset:3904
	v_fma_f32 v106, v159, v106, -v98
	v_fma_f32 v107, v159, v107, -v99
	v_fma_f32 v108, v159, v108, -v100
	v_fma_f32 v109, v159, v109, -v101
	v_fma_f32 v218, v159, v218, -v102
	v_fma_f32 v219, v159, v219, -v103
	v_fma_f32 v220, v159, v220, -v104
	v_fma_f32 v221, v159, v221, -v105
	v_cvt_pk_bf16_f32 v106, v106, v107
	v_cvt_pk_bf16_f32 v107, v108, v109
	v_cvt_pk_bf16_f32 v108, v218, v219
	v_cvt_pk_bf16_f32 v109, v220, v221
	s_and_saveexec_b64 s[10:11], s[6:7]
	s_cbranch_execz .Lpu3_1
	global_store_dwordx4 v[184:185], v[98:101], off offset:64
	global_store_dwordx4 v[184:185], v[102:105], off offset:80
.Lpu3_1:
	s_or_b64 exec, exec, s[10:11]
	s_waitcnt vmcnt(8)
	v_mfma_f32_32x32x16_bf16 v[2:17], v[106:109], v[82:85], v[2:17]
	v_mfma_f32_32x32x16_bf16 v[18:33], v[106:109], v[86:89], v[18:33]
	v_mfma_f32_32x32x16_bf16 v[34:49], v[106:109], v[90:93], v[34:49]
	v_mfma_f32_32x32x16_bf16 v[50:65], v[106:109], v[94:97], v[50:65]
	global_load_dwordx4 v[82:85], v[110:111], off offset:2048
	global_load_dwordx4 v[86:89], v[134:135], off offset:2048
	global_load_dwordx4 v[90:93], v[136:137], off offset:2048
	global_load_dwordx4 v[94:97], v[138:139], off offset:2048
	s_waitcnt lgkmcnt(3)
	v_lshlrev_b32_e32 v98, 16, v238
	v_and_b32_e32 v99, 0xffff0000, v238
	v_lshlrev_b32_e32 v100, 16, v239
	v_and_b32_e32 v101, 0xffff0000, v239
	v_lshlrev_b32_e32 v102, 16, v240
	v_and_b32_e32 v103, 0xffff0000, v240
	v_lshlrev_b32_e32 v104, 16, v241
	v_and_b32_e32 v105, 0xffff0000, v241
	ds_read_b128 v[238:241], v163 offset:4208
	s_waitcnt lgkmcnt(3)
	v_lshlrev_b32_e32 v216, 16, v242
	v_and_b32_e32 v217, 0xffff0000, v242
	v_lshlrev_b32_e32 v242, 16, v243
	v_and_b32_e32 v243, 0xffff0000, v243
	v_pk_add_f32 v[106:107], v[98:99], v[216:217]
	v_pk_add_f32 v[108:109], v[100:101], v[242:243]
	v_lshlrev_b32_e32 v216, 16, v244
	v_and_b32_e32 v217, 0xffff0000, v244
	v_lshlrev_b32_e32 v244, 16, v245
	v_and_b32_e32 v245, 0xffff0000, v245
	v_pk_add_f32 v[218:219], v[102:103], v[216:217]
	v_pk_add_f32 v[220:221], v[104:105], v[244:245]
	ds_read_b128 v[242:245], v163 offset:3936
	v_fma_f32 v106, v159, v106, -v98
	v_fma_f32 v107, v159, v107, -v99
	v_fma_f32 v108, v159, v108, -v100
	v_fma_f32 v109, v159, v109, -v101
	v_fma_f32 v218, v159, v218, -v102
	v_fma_f32 v219, v159, v219, -v103
	v_fma_f32 v220, v159, v220, -v104
	v_fma_f32 v221, v159, v221, -v105
	v_cvt_pk_bf16_f32 v106, v106, v107
	v_cvt_pk_bf16_f32 v107, v108, v109
	v_cvt_pk_bf16_f32 v108, v218, v219
	v_cvt_pk_bf16_f32 v109, v220, v221
	s_and_saveexec_b64 s[10:11], s[6:7]
	s_cbranch_execz .Lpu3_2
	global_store_dwordx4 v[184:185], v[98:101], off offset:128
	global_store_dwordx4 v[184:185], v[102:105], off offset:144
.Lpu3_2:
	s_or_b64 exec, exec, s[10:11]
	s_waitcnt vmcnt(8)
	v_mfma_f32_32x32x16_bf16 v[2:17], v[106:109], v[222:225], v[2:17]
	v_mfma_f32_32x32x16_bf16 v[18:33], v[106:109], v[226:229], v[18:33]
	v_mfma_f32_32x32x16_bf16 v[34:49], v[106:109], v[230:233], v[34:49]
	v_mfma_f32_32x32x16_bf16 v[50:65], v[106:109], v[234:237], v[50:65]
	global_load_dwordx4 v[222:225], v[110:111], off offset:2560
	global_load_dwordx4 v[226:229], v[134:135], off offset:2560
	global_load_dwordx4 v[230:233], v[136:137], off offset:2560
	global_load_dwordx4 v[234:237], v[138:139], off offset:2560
	s_waitcnt lgkmcnt(3)
	v_lshlrev_b32_e32 v98, 16, v248
	v_and_b32_e32 v99, 0xffff0000, v248
	v_lshlrev_b32_e32 v100, 16, v249
	v_and_b32_e32 v101, 0xffff0000, v249
	v_lshlrev_b32_e32 v102, 16, v250
	v_and_b32_e32 v103, 0xffff0000, v250
	v_lshlrev_b32_e32 v104, 16, v251
	v_and_b32_e32 v105, 0xffff0000, v251
	ds_read_b128 v[248:251], v163 offset:4240
	s_waitcnt lgkmcnt(3)
	v_lshlrev_b32_e32 v216, 16, v252
	v_and_b32_e32 v217, 0xffff0000, v252
	v_lshlrev_b32_e32 v252, 16, v253
	v_and_b32_e32 v253, 0xffff0000, v253
	v_pk_add_f32 v[106:107], v[98:99], v[216:217]
	v_pk_add_f32 v[108:109], v[100:101], v[252:253]
	v_lshlrev_b32_e32 v216, 16, v254
	v_and_b32_e32 v217, 0xffff0000, v254
	v_lshlrev_b32_e32 v254, 16, v255
	v_and_b32_e32 v255, 0xffff0000, v255
	v_pk_add_f32 v[218:219], v[102:103], v[216:217]
	v_pk_add_f32 v[220:221], v[104:105], v[254:255]
	ds_read_b128 v[252:255], v163 offset:3968
	v_fma_f32 v106, v159, v106, -v98
	v_fma_f32 v107, v159, v107, -v99
	v_fma_f32 v108, v159, v108, -v100
	v_fma_f32 v109, v159, v109, -v101
	v_fma_f32 v218, v159, v218, -v102
	v_fma_f32 v219, v159, v219, -v103
	v_fma_f32 v220, v159, v220, -v104
	v_fma_f32 v221, v159, v221, -v105
	v_cvt_pk_bf16_f32 v106, v106, v107
	v_cvt_pk_bf16_f32 v107, v108, v109
	v_cvt_pk_bf16_f32 v108, v218, v219
	v_cvt_pk_bf16_f32 v109, v220, v221
	s_and_saveexec_b64 s[10:11], s[6:7]
	s_cbranch_execz .Lpu3_3
	global_store_dwordx4 v[184:185], v[98:101], off offset:192
	global_store_dwordx4 v[184:185], v[102:105], off offset:208
.Lpu3_3:
	s_or_b64 exec, exec, s[10:11]
	s_waitcnt vmcnt(8)
	v_mfma_f32_32x32x16_bf16 v[2:17], v[106:109], v[70:73], v[2:17]
	v_mfma_f32_32x32x16_bf16 v[18:33], v[106:109], v[74:77], v[18:33]
	v_mfma_f32_32x32x16_bf16 v[34:49], v[106:109], v[78:81], v[34:49]
	v_mfma_f32_32x32x16_bf16 v[50:65], v[106:109], v[66:69], v[50:65]
	global_load_dwordx4 v[70:73], v[110:111], off offset:3072
	global_load_dwordx4 v[74:77], v[134:135], off offset:3072
	global_load_dwordx4 v[78:81], v[136:137], off offset:3072
	global_load_dwordx4 v[66:69], v[138:139], off offset:3072
	s_waitcnt lgkmcnt(3)
	v_lshlrev_b32_e32 v98, 16, v238
	v_and_b32_e32 v99, 0xffff0000, v238
	v_lshlrev_b32_e32 v100, 16, v239
	v_and_b32_e32 v101, 0xffff0000, v239
	v_lshlrev_b32_e32 v102, 16, v240
	v_and_b32_e32 v103, 0xffff0000, v240
	v_lshlrev_b32_e32 v104, 16, v241
	v_and_b32_e32 v105, 0xffff0000, v241
	ds_read_b128 v[238:241], v163 offset:4272
	s_waitcnt lgkmcnt(3)
	v_lshlrev_b32_e32 v216, 16, v242
	v_and_b32_e32 v217, 0xffff0000, v242
	v_lshlrev_b32_e32 v242, 16, v243
	v_and_b32_e32 v243, 0xffff0000, v243
	v_pk_add_f32 v[106:107], v[98:99], v[216:217]
	v_pk_add_f32 v[108:109], v[100:101], v[242:243]
	v_lshlrev_b32_e32 v216, 16, v244
	v_and_b32_e32 v217, 0xffff0000, v244
	v_lshlrev_b32_e32 v244, 16, v245
	v_and_b32_e32 v245, 0xffff0000, v245
	v_pk_add_f32 v[218:219], v[102:103], v[216:217]
	v_pk_add_f32 v[220:221], v[104:105], v[244:245]
	ds_read_b128 v[242:245], v163 offset:4000
	v_fma_f32 v106, v159, v106, -v98
	v_fma_f32 v107, v159, v107, -v99
	v_fma_f32 v108, v159, v108, -v100
	v_fma_f32 v109, v159, v109, -v101
	v_fma_f32 v218, v159, v218, -v102
	v_fma_f32 v219, v159, v219, -v103
	v_fma_f32 v220, v159, v220, -v104
	v_fma_f32 v221, v159, v221, -v105
	v_cvt_pk_bf16_f32 v106, v106, v107
	v_cvt_pk_bf16_f32 v107, v108, v109
	v_cvt_pk_bf16_f32 v108, v218, v219
	v_cvt_pk_bf16_f32 v109, v220, v221
	s_and_saveexec_b64 s[10:11], s[6:7]
	s_cbranch_execz .Lpu3_4
	global_store_dwordx4 v[184:185], v[98:101], off offset:256
	global_store_dwordx4 v[184:185], v[102:105], off offset:272
.Lpu3_4:
	s_or_b64 exec, exec, s[10:11]
	s_waitcnt vmcnt(8)
	v_mfma_f32_32x32x16_bf16 v[2:17], v[106:109], v[82:85], v[2:17]
	v_mfma_f32_32x32x16_bf16 v[18:33], v[106:109], v[86:89], v[18:33]
	v_mfma_f32_32x32x16_bf16 v[34:49], v[106:109], v[90:93], v[34:49]
	v_mfma_f32_32x32x16_bf16 v[50:65], v[106:109], v[94:97], v[50:65]
	global_load_dwordx4 v[82:85], v[110:111], off offset:3584
	global_load_dwordx4 v[86:89], v[134:135], off offset:3584
	global_load_dwordx4 v[90:93], v[136:137], off offset:3584
	global_load_dwordx4 v[94:97], v[138:139], off offset:3584
	s_waitcnt lgkmcnt(3)
	v_lshlrev_b32_e32 v98, 16, v248
	v_and_b32_e32 v99, 0xffff0000, v248
	v_lshlrev_b32_e32 v100, 16, v249
	v_and_b32_e32 v101, 0xffff0000, v249
	v_lshlrev_b32_e32 v102, 16, v250
	v_and_b32_e32 v103, 0xffff0000, v250
	v_lshlrev_b32_e32 v104, 16, v251
	v_and_b32_e32 v105, 0xffff0000, v251
	ds_read_b128 v[248:251], v163 offset:4304
	s_waitcnt lgkmcnt(3)
	v_lshlrev_b32_e32 v216, 16, v252
	v_and_b32_e32 v217, 0xffff0000, v252
	v_lshlrev_b32_e32 v252, 16, v253
	v_and_b32_e32 v253, 0xffff0000, v253
	v_pk_add_f32 v[106:107], v[98:99], v[216:217]
	v_pk_add_f32 v[108:109], v[100:101], v[252:253]
	v_lshlrev_b32_e32 v216, 16, v254
	v_and_b32_e32 v217, 0xffff0000, v254
	v_lshlrev_b32_e32 v254, 16, v255
	v_and_b32_e32 v255, 0xffff0000, v255
	v_pk_add_f32 v[218:219], v[102:103], v[216:217]
	v_pk_add_f32 v[220:221], v[104:105], v[254:255]
	ds_read_b128 v[252:255], v163 offset:4032
	v_fma_f32 v106, v159, v106, -v98
	v_fma_f32 v107, v159, v107, -v99
	v_fma_f32 v108, v159, v108, -v100
	v_fma_f32 v109, v159, v109, -v101
	v_fma_f32 v218, v159, v218, -v102
	v_fma_f32 v219, v159, v219, -v103
	v_fma_f32 v220, v159, v220, -v104
	v_fma_f32 v221, v159, v221, -v105
	v_cvt_pk_bf16_f32 v106, v106, v107
	v_cvt_pk_bf16_f32 v107, v108, v109
	v_cvt_pk_bf16_f32 v108, v218, v219
	v_cvt_pk_bf16_f32 v109, v220, v221
	s_and_saveexec_b64 s[10:11], s[6:7]
	s_cbranch_execz .Lpu3_5
	global_store_dwordx4 v[184:185], v[98:101], off offset:320
	global_store_dwordx4 v[184:185], v[102:105], off offset:336
.Lpu3_5:
	s_or_b64 exec, exec, s[10:11]
	s_waitcnt vmcnt(8)
	v_mfma_f32_32x32x16_bf16 v[2:17], v[106:109], v[222:225], v[2:17]
	v_mfma_f32_32x32x16_bf16 v[18:33], v[106:109], v[226:229], v[18:33]
	v_mfma_f32_32x32x16_bf16 v[34:49], v[106:109], v[230:233], v[34:49]
	v_mfma_f32_32x32x16_bf16 v[50:65], v[106:109], v[234:237], v[50:65]
	s_waitcnt lgkmcnt(3)
	v_lshlrev_b32_e32 v98, 16, v238
	v_and_b32_e32 v99, 0xffff0000, v238
	v_lshlrev_b32_e32 v100, 16, v239
	v_and_b32_e32 v101, 0xffff0000, v239
	v_lshlrev_b32_e32 v102, 16, v240
	v_and_b32_e32 v103, 0xffff0000, v240
	v_lshlrev_b32_e32 v104, 16, v241
	v_and_b32_e32 v105, 0xffff0000, v241
	s_waitcnt lgkmcnt(2)
	v_lshlrev_b32_e32 v216, 16, v242
	v_and_b32_e32 v217, 0xffff0000, v242
	v_lshlrev_b32_e32 v242, 16, v243
	v_and_b32_e32 v243, 0xffff0000, v243
	v_pk_add_f32 v[106:107], v[98:99], v[216:217]
	v_pk_add_f32 v[108:109], v[100:101], v[242:243]
	v_lshlrev_b32_e32 v216, 16, v244
	v_and_b32_e32 v217, 0xffff0000, v244
	v_lshlrev_b32_e32 v244, 16, v245
	v_and_b32_e32 v245, 0xffff0000, v245
	v_pk_add_f32 v[218:219], v[102:103], v[216:217]
	v_pk_add_f32 v[220:221], v[104:105], v[244:245]
	v_fma_f32 v106, v159, v106, -v98
	v_fma_f32 v107, v159, v107, -v99
	v_fma_f32 v108, v159, v108, -v100
	v_fma_f32 v109, v159, v109, -v101
	v_fma_f32 v218, v159, v218, -v102
	v_fma_f32 v219, v159, v219, -v103
	v_fma_f32 v220, v159, v220, -v104
	v_fma_f32 v221, v159, v221, -v105
	v_cvt_pk_bf16_f32 v106, v106, v107
	v_cvt_pk_bf16_f32 v107, v108, v109
	v_cvt_pk_bf16_f32 v108, v218, v219
	v_cvt_pk_bf16_f32 v109, v220, v221
	s_and_saveexec_b64 s[10:11], s[6:7]
	s_cbranch_execz .Lpu3_6
	global_store_dwordx4 v[184:185], v[98:101], off offset:384
	global_store_dwordx4 v[184:185], v[102:105], off offset:400
.Lpu3_6:
	s_or_b64 exec, exec, s[10:11]
	s_waitcnt vmcnt(4)
	v_mfma_f32_32x32x16_bf16 v[2:17], v[106:109], v[70:73], v[2:17]
	v_mfma_f32_32x32x16_bf16 v[18:33], v[106:109], v[74:77], v[18:33]
	v_mfma_f32_32x32x16_bf16 v[34:49], v[106:109], v[78:81], v[34:49]
	v_mfma_f32_32x32x16_bf16 v[50:65], v[106:109], v[66:69], v[50:65]
	s_waitcnt lgkmcnt(1)
	v_lshlrev_b32_e32 v98, 16, v248
	v_and_b32_e32 v99, 0xffff0000, v248
	v_lshlrev_b32_e32 v100, 16, v249
	v_and_b32_e32 v101, 0xffff0000, v249
	v_lshlrev_b32_e32 v102, 16, v250
	v_and_b32_e32 v103, 0xffff0000, v250
	v_lshlrev_b32_e32 v104, 16, v251
	v_and_b32_e32 v105, 0xffff0000, v251
	s_waitcnt lgkmcnt(0)
	v_lshlrev_b32_e32 v216, 16, v252
	v_and_b32_e32 v217, 0xffff0000, v252
	v_lshlrev_b32_e32 v252, 16, v253
	v_and_b32_e32 v253, 0xffff0000, v253
	v_pk_add_f32 v[106:107], v[98:99], v[216:217]
	v_pk_add_f32 v[108:109], v[100:101], v[252:253]
	v_lshlrev_b32_e32 v216, 16, v254
	v_and_b32_e32 v217, 0xffff0000, v254
	v_lshlrev_b32_e32 v254, 16, v255
	v_and_b32_e32 v255, 0xffff0000, v255
	v_pk_add_f32 v[218:219], v[102:103], v[216:217]
	v_pk_add_f32 v[220:221], v[104:105], v[254:255]
	v_fma_f32 v106, v159, v106, -v98
	v_fma_f32 v107, v159, v107, -v99
	v_fma_f32 v108, v159, v108, -v100
	v_fma_f32 v109, v159, v109, -v101
	v_fma_f32 v218, v159, v218, -v102
	v_fma_f32 v219, v159, v219, -v103
	v_fma_f32 v220, v159, v220, -v104
	v_fma_f32 v221, v159, v221, -v105
	v_cvt_pk_bf16_f32 v106, v106, v107
	v_cvt_pk_bf16_f32 v107, v108, v109
	v_cvt_pk_bf16_f32 v108, v218, v219
	v_cvt_pk_bf16_f32 v109, v220, v221
	s_and_saveexec_b64 s[10:11], s[6:7]
	s_cbranch_execz .Lpu3_7
	global_store_dwordx4 v[184:185], v[98:101], off offset:448
	global_store_dwordx4 v[184:185], v[102:105], off offset:464
